# GEMM loops: first MFMA issues immediately after the barrier (priority raise moved behind it), mid-block priority flips removed
# baseline (speedup 1.0000x reference)
; #define PG8_STAGE(bufoff, gbase, voff) do { _Pragma("unroll") for (int _i = 0; _i < 2; ++_i) \
;         __builtin_amdgcn_global_load_lds((const unsigned*)((const char*)(gbase) + (voff)[_i]), (PG8_LAS unsigned*)(lds + (bufoff) + ldsw + _i * 8192), 16, 0, 0); } while (0)
; #define PG8_LDA(dst, b, h) do { _Pragma("unroll") for (int m = 0; m < 4; ++m) _Pragma("unroll") for (int k = 0; k < 2; ++k) dst[m][k] = *(const PG8_LAS bf16x8*)(lds + PG8_SA(b, h) + aoff + m * 2048 + k * 1024); } while (0)
; #define PG8_LDB(dst, b, h) do { _Pragma("unroll") for (int n = 0; n < 2; ++n) _Pragma("unroll") for (int k = 0; k < 2; ++k) dst[n][k] = *(const PG8_LAS bf16x8*)(lds + PG8_SB(b, h) + boff + n * 2048 + k * 1024); } while (0)
; #define PG8_MMA(ai, bj, At, Bt) do { __builtin_amdgcn_s_setprio(1); _Pragma("unroll") for (int m = 0; m < 4; ++m) _Pragma("unroll") for (int n = 0; n < 2; ++n) _Pragma("unroll") for (int k = 0; k < 2; ++k) \
;         acc[ai][bj][m][n] = __builtin_amdgcn_mfma_f32_16x16x32_bf16(Bt[n][k], At[m][k], acc[ai][bj][m][n], 0, 0, 0); __builtin_amdgcn_s_setprio(0); } while (0)
; #define PG8_WAIT_V(n) asm volatile("s_waitcnt vmcnt(" #n ")" ::: "memory")
; #define PG8_BAR __builtin_amdgcn_s_barrier()
; template <class Epi, class Sched, bool ALIGN_EPI = false, bool SP2 = false>
; __device__ __forceinline__ void gemm_phase(PG8_LAS unsigned char* lds, const Gemm g, const Sched& S, const Epi& E) {
;     ...
;         for (int t = 0; t < nt; t += 2) {
;             const bool last = (t == nt - 2);
;             const char* a1 = cA + (size_t)(t + 1) * kstep;
;             const char* a2 = last ? nA : cA + (size_t)(t + 2) * kstep; const char* b2 = last ? nB : cB + (size_t)(t + 2) * kstep;
;             const char* a3 = a2 + kstep; const char* b3 = b2 + kstep;
;             if (last && has_next) S.a_ready(nxt);
;             if constexpr (SP2) {
;             PG8_LDB(B0, 0, 0); PG8_LDB(B1, 0, 1); PG8_SCHED; PG8_LDA(At, 0, 0); PG8_STAGE(PG8_SA(1, 1), a1 + hstepA, voffA);
;             PG8_WAIT_V(8); PG8_WAIT_L(0); PG8_BAR; PG8_MMA(0, 0, At, B0); PG8_MMA(0, 1, At, B1); PG8_BAR; PG8_SCHED;
;             PG8_LDA(At, 0, 1); PG8_STAGE(PG8_SB(0, 0), b2, voffB); PG8_STAGE(PG8_SB(0, 1), b2 + hstepB, voffB); PG8_STAGE(PG8_SA(0, 0), a2, voffA);
;             PG8_WAIT_V(8); PG8_WAIT_L(0); PG8_BAR; PG8_MMA(1, 0, At, B0); PG8_MMA(1, 1, At, B1); PG8_BAR; PG8_SCHED;
.LBB0_244:
	ds_read_b128 v[152:155], v147
	ds_read_b128 v[156:159], v147 offset:1024
	ds_read_b128 v[160:163], v147 offset:2048
	ds_read_b128 v[164:167], v147 offset:3072
	ds_read_b128 v[168:171], v148
	ds_read_b128 v[172:175], v148 offset:1024
	ds_read_b128 v[176:179], v148 offset:2048
	ds_read_b128 v[180:183], v148 offset:3072
	s_add_u32 s28, s26, 0xfffc0080
	s_addc_u32 s29, s27, -1
	s_cmp_eq_u32 s68, 12
	s_cselect_b32 s31, s15, s29
	s_cselect_b32 s30, s62, s28
	s_cselect_b32 s29, s13, s67
	s_cselect_b32 s28, s63, s66
	v_lshl_add_u64 v[184:185], s[26:27], 0, v[136:137]
	s_add_i32 m0, s25, 0xc000
	ds_read_b128 v[188:191], v149
	ds_read_b128 v[192:195], v149 offset:1024
	ds_read_b128 v[196:199], v149 offset:2048
	ds_read_b128 v[200:203], v149 offset:3072
	ds_read_b128 v[204:207], v149 offset:4096
	ds_read_b128 v[208:211], v149 offset:5120
	ds_read_b128 v[212:215], v149 offset:6144
	ds_read_b128 v[216:219], v149 offset:7168
	global_load_lds_dwordx4 v[184:185], off
	v_lshl_add_u64 v[184:185], s[26:27], 0, v[138:139]
	s_add_i32 m0, s25, 0xe000
	s_nop 0
	global_load_lds_dwordx4 v[184:185], off
	s_waitcnt vmcnt(8) lgkmcnt(0)
	s_barrier
	v_mfma_f32_16x16x32_bf16 v[116:119], v[152:155], v[188:191], v[116:119]
	s_setprio 1
	v_mfma_f32_16x16x32_bf16 v[108:111], v[160:163], v[188:191], v[108:111]
	v_mfma_f32_16x16x32_bf16 v[104:107], v[152:155], v[196:199], v[104:107]
	v_mfma_f32_16x16x32_bf16 v[100:103], v[160:163], v[196:199], v[100:103]
	v_mfma_f32_16x16x32_bf16 v[92:95], v[152:155], v[204:207], v[92:95]
	v_mfma_f32_16x16x32_bf16 v[84:87], v[160:163], v[204:207], v[84:87]
	v_mfma_f32_16x16x32_bf16 v[76:79], v[152:155], v[212:215], v[76:79]
	v_mfma_f32_16x16x32_bf16 v[68:71], v[160:163], v[212:215], v[68:71]
	v_mfma_f32_16x16x32_bf16 v[116:119], v[156:159], v[192:195], v[116:119]
	v_mfma_f32_16x16x32_bf16 v[108:111], v[164:167], v[192:195], v[108:111]
	v_mfma_f32_16x16x32_bf16 v[104:107], v[156:159], v[200:203], v[104:107]
	v_mfma_f32_16x16x32_bf16 v[100:103], v[164:167], v[200:203], v[100:103]
	v_mfma_f32_16x16x32_bf16 v[92:95], v[156:159], v[208:211], v[92:95]
	v_mfma_f32_16x16x32_bf16 v[84:87], v[164:167], v[208:211], v[84:87]
	v_mfma_f32_16x16x32_bf16 v[76:79], v[156:159], v[216:219], v[76:79]
	v_mfma_f32_16x16x32_bf16 v[68:71], v[164:167], v[216:219], v[68:71]
	v_mfma_f32_16x16x32_bf16 v[124:127], v[168:171], v[188:191], v[124:127]
	v_mfma_f32_16x16x32_bf16 v[120:123], v[176:179], v[188:191], v[120:123]
	v_mfma_f32_16x16x32_bf16 v[112:115], v[168:171], v[196:199], v[112:115]
	v_mfma_f32_16x16x32_bf16 v[96:99], v[176:179], v[196:199], v[96:99]
	v_mfma_f32_16x16x32_bf16 v[88:91], v[168:171], v[204:207], v[88:91]
	v_mfma_f32_16x16x32_bf16 v[80:83], v[176:179], v[204:207], v[80:83]
	v_mfma_f32_16x16x32_bf16 v[72:75], v[168:171], v[212:215], v[72:75]
	v_mfma_f32_16x16x32_bf16 v[64:67], v[176:179], v[212:215], v[64:67]
	v_mfma_f32_16x16x32_bf16 v[124:127], v[172:175], v[192:195], v[124:127]
	v_mfma_f32_16x16x32_bf16 v[120:123], v[180:183], v[192:195], v[120:123]
	v_mfma_f32_16x16x32_bf16 v[112:115], v[172:175], v[200:203], v[112:115]
	v_mfma_f32_16x16x32_bf16 v[96:99], v[180:183], v[200:203], v[96:99]
	v_mfma_f32_16x16x32_bf16 v[88:91], v[172:175], v[208:211], v[88:91]
	v_mfma_f32_16x16x32_bf16 v[80:83], v[180:183], v[208:211], v[80:83]
	v_mfma_f32_16x16x32_bf16 v[72:75], v[172:175], v[216:219], v[72:75]
	v_mfma_f32_16x16x32_bf16 v[64:67], v[180:183], v[216:219], v[64:67]
	s_barrier
	s_setprio 0
	s_add_i32 s58, s46, s36
	v_lshl_add_u64 v[184:185], s[28:29], 0, v[132:133]
	s_mov_b32 m0, s58
	ds_read_b128 v[188:191], v149 offset:16384
	ds_read_b128 v[192:195], v149 offset:17408
	ds_read_b128 v[196:199], v149 offset:18432
	ds_read_b128 v[200:203], v149 offset:19456
	ds_read_b128 v[204:207], v149 offset:20480
	ds_read_b128 v[208:211], v149 offset:21504
	ds_read_b128 v[212:215], v149 offset:22528
	ds_read_b128 v[216:219], v149 offset:23552
	global_load_lds_dwordx4 v[184:185], off
	s_add_i32 m0, s58, 0x2000
	s_add_u32 s58, s28, 0x40000
	v_lshl_add_u64 v[220:221], s[28:29], 0, v[128:129]
	s_addc_u32 s59, s29, 0
	s_add_i32 s69, s47, s36
	global_load_lds_dwordx4 v[220:221], off
	v_lshl_add_u64 v[222:223], s[58:59], 0, v[132:133]
	s_mov_b32 m0, s69
	v_lshl_add_u64 v[224:225], s[30:31], 0, v[130:131]
	global_load_lds_dwordx4 v[222:223], off
	v_lshl_add_u64 v[222:223], s[58:59], 0, v[128:129]
	s_add_i32 m0, s69, 0x2000
	s_nop 0
	global_load_lds_dwordx4 v[222:223], off
	v_lshl_add_u64 v[222:223], s[30:31], 0, v[134:135]
	s_mov_b32 m0, s25
	s_nop 0
	global_load_lds_dwordx4 v[222:223], off
	s_mov_b32 m0, s39
	s_nop 0
	global_load_lds_dwordx4 v[224:225], off
	s_waitcnt vmcnt(8) lgkmcnt(0)
	s_barrier
; #define PG8_STAGE(bufoff, gbase, voff) do { _Pragma("unroll") for (int _i = 0; _i < 2; ++_i) \
;         __builtin_amdgcn_global_load_lds((const unsigned*)((const char*)(gbase) + (voff)[_i]), (PG8_LAS unsigned*)(lds + (bufoff) + ldsw + _i * 8192), 16, 0, 0); } while (0)
; #define PG8_LDA(dst, b, h) do { _Pragma("unroll") for (int m = 0; m < 4; ++m) _Pragma("unroll") for (int k = 0; k < 2; ++k) dst[m][k] = *(const PG8_LAS bf16x8*)(lds + PG8_SA(b, h) + aoff + m * 2048 + k * 1024); } while (0)
; #define PG8_LDB(dst, b, h) do { _Pragma("unroll") for (int n = 0; n < 2; ++n) _Pragma("unroll") for (int k = 0; k < 2; ++k) dst[n][k] = *(const PG8_LAS bf16x8*)(lds + PG8_SB(b, h) + boff + n * 2048 + k * 1024); } while (0)
; #define PG8_MMA(ai, bj, At, Bt) do { __builtin_amdgcn_s_setprio(1); _Pragma("unroll") for (int m = 0; m < 4; ++m) _Pragma("unroll") for (int n = 0; n < 2; ++n) _Pragma("unroll") for (int k = 0; k < 2; ++k) \
;         acc[ai][bj][m][n] = __builtin_amdgcn_mfma_f32_16x16x32_bf16(Bt[n][k], At[m][k], acc[ai][bj][m][n], 0, 0, 0); __builtin_amdgcn_s_setprio(0); } while (0)
; #define PG8_WAIT_V(n) asm volatile("s_waitcnt vmcnt(" #n ")" ::: "memory")
; #define PG8_WAIT_L(n) asm volatile("s_waitcnt lgkmcnt(" #n ")" ::: "memory")
; #define PG8_BAR __builtin_amdgcn_s_barrier()
; #define PG8_SCHED __builtin_amdgcn_sched_barrier(0)
; template <class Epi, class Sched, bool ALIGN_EPI = false, bool SP2 = false>
; __device__ __forceinline__ void gemm_phase(PG8_LAS unsigned char* lds, const Gemm g, const Sched& S, const Epi& E) {
;     ...
;             PG8_WAIT_V(8); PG8_WAIT_L(0); PG8_BAR; PG8_MMA(1, 0, At, B0); PG8_MMA(1, 1, At, B1); PG8_BAR; PG8_SCHED;
;             PG8_LDB(B0, 1, 0); PG8_LDB(B1, 1, 1); PG8_SCHED; PG8_LDA(At, 1, 0); PG8_STAGE(PG8_SA(0, 1), a2 + hstepA, voffA);
;             PG8_WAIT_V(8); PG8_WAIT_L(0); PG8_BAR; PG8_MMA(0, 0, At, B0); PG8_MMA(0, 1, At, B1); PG8_BAR; PG8_SCHED;
	v_mfma_f32_16x16x32_bf16 v[60:63], v[152:155], v[188:191], v[60:63]
	s_setprio 1
	v_mfma_f32_16x16x32_bf16 v[52:55], v[160:163], v[188:191], v[52:55]
	v_mfma_f32_16x16x32_bf16 v[44:47], v[152:155], v[196:199], v[44:47]
	v_mfma_f32_16x16x32_bf16 v[36:39], v[160:163], v[196:199], v[36:39]
	v_mfma_f32_16x16x32_bf16 v[28:31], v[152:155], v[204:207], v[28:31]
	v_mfma_f32_16x16x32_bf16 v[20:23], v[160:163], v[204:207], v[20:23]
	v_mfma_f32_16x16x32_bf16 v[12:15], v[152:155], v[212:215], v[12:15]
	v_mfma_f32_16x16x32_bf16 v[4:7], v[160:163], v[212:215], v[4:7]
	v_mfma_f32_16x16x32_bf16 v[60:63], v[156:159], v[192:195], v[60:63]
	v_mfma_f32_16x16x32_bf16 v[52:55], v[164:167], v[192:195], v[52:55]
	v_mfma_f32_16x16x32_bf16 v[44:47], v[156:159], v[200:203], v[44:47]
	v_mfma_f32_16x16x32_bf16 v[36:39], v[164:167], v[200:203], v[36:39]
	v_mfma_f32_16x16x32_bf16 v[28:31], v[156:159], v[208:211], v[28:31]
	v_mfma_f32_16x16x32_bf16 v[20:23], v[164:167], v[208:211], v[20:23]
	v_mfma_f32_16x16x32_bf16 v[12:15], v[156:159], v[216:219], v[12:15]
	v_mfma_f32_16x16x32_bf16 v[4:7], v[164:167], v[216:219], v[4:7]
	v_mfma_f32_16x16x32_bf16 v[56:59], v[168:171], v[188:191], v[56:59]
	v_mfma_f32_16x16x32_bf16 v[48:51], v[176:179], v[188:191], v[48:51]
	v_mfma_f32_16x16x32_bf16 v[40:43], v[168:171], v[196:199], v[40:43]
	v_mfma_f32_16x16x32_bf16 v[32:35], v[176:179], v[196:199], v[32:35]
	v_mfma_f32_16x16x32_bf16 v[24:27], v[168:171], v[204:207], v[24:27]
	v_mfma_f32_16x16x32_bf16 v[16:19], v[176:179], v[204:207], v[16:19]
	v_mfma_f32_16x16x32_bf16 v[8:11], v[168:171], v[212:215], v[8:11]
	v_mfma_f32_16x16x32_bf16 v[0:3], v[176:179], v[212:215], v[0:3]
	v_mfma_f32_16x16x32_bf16 v[56:59], v[172:175], v[192:195], v[56:59]
	v_mfma_f32_16x16x32_bf16 v[48:51], v[180:183], v[192:195], v[48:51]
	v_mfma_f32_16x16x32_bf16 v[40:43], v[172:175], v[200:203], v[40:43]
	v_mfma_f32_16x16x32_bf16 v[32:35], v[180:183], v[200:203], v[32:35]
	v_mfma_f32_16x16x32_bf16 v[24:27], v[172:175], v[208:211], v[24:27]
	v_mfma_f32_16x16x32_bf16 v[16:19], v[180:183], v[208:211], v[16:19]
	v_mfma_f32_16x16x32_bf16 v[8:11], v[172:175], v[216:219], v[8:11]
	v_mfma_f32_16x16x32_bf16 v[0:3], v[180:183], v[216:219], v[0:3]
	s_barrier
	s_setprio 0
	s_add_i32 s58, 0, 0x18000
	v_add_u32_e32 v151, s58, v145
	s_add_i32 s59, 0, 0x1c000
	ds_read_b128 v[152:155], v151
	ds_read_b128 v[156:159], v151 offset:1024
	ds_read_b128 v[160:163], v151 offset:2048
	ds_read_b128 v[164:167], v151 offset:3072
	v_add_u32_e32 v151, s59, v145
	ds_read_b128 v[168:171], v151
	ds_read_b128 v[172:175], v151 offset:1024
	ds_read_b128 v[176:179], v151 offset:2048
	ds_read_b128 v[180:183], v151 offset:3072
	s_add_u32 s30, s30, 0x40000
	s_addc_u32 s31, s31, 0
	s_mov_b32 m0, s40
	v_lshl_add_u64 v[226:227], s[30:31], 0, v[134:135]
	ds_read_b128 v[188:191], v149 offset:32768
	ds_read_b128 v[192:195], v149 offset:33792
	ds_read_b128 v[196:199], v149 offset:34816
	ds_read_b128 v[200:203], v149 offset:35840
	ds_read_b128 v[204:207], v149 offset:36864
	ds_read_b128 v[208:211], v149 offset:37888
	ds_read_b128 v[212:215], v149 offset:38912
	ds_read_b128 v[216:219], v149 offset:39936
	global_load_lds_dwordx4 v[226:227], off
	v_lshl_add_u64 v[226:227], s[30:31], 0, v[130:131]
	s_mov_b32 m0, s41
	s_nop 0
	global_load_lds_dwordx4 v[226:227], off
	s_waitcnt vmcnt(8) lgkmcnt(0)
	s_barrier
	v_mfma_f32_16x16x32_bf16 v[116:119], v[152:155], v[188:191], v[116:119]
	s_setprio 1
	v_mfma_f32_16x16x32_bf16 v[108:111], v[160:163], v[188:191], v[108:111]
	v_mfma_f32_16x16x32_bf16 v[104:107], v[152:155], v[196:199], v[104:107]
	v_mfma_f32_16x16x32_bf16 v[100:103], v[160:163], v[196:199], v[100:103]
	v_mfma_f32_16x16x32_bf16 v[92:95], v[152:155], v[204:207], v[92:95]
	v_mfma_f32_16x16x32_bf16 v[84:87], v[160:163], v[204:207], v[84:87]
	v_mfma_f32_16x16x32_bf16 v[76:79], v[152:155], v[212:215], v[76:79]
	v_mfma_f32_16x16x32_bf16 v[68:71], v[160:163], v[212:215], v[68:71]
	v_mfma_f32_16x16x32_bf16 v[116:119], v[156:159], v[192:195], v[116:119]
	v_mfma_f32_16x16x32_bf16 v[108:111], v[164:167], v[192:195], v[108:111]
	v_mfma_f32_16x16x32_bf16 v[104:107], v[156:159], v[200:203], v[104:107]
	v_mfma_f32_16x16x32_bf16 v[100:103], v[164:167], v[200:203], v[100:103]
	v_mfma_f32_16x16x32_bf16 v[92:95], v[156:159], v[208:211], v[92:95]
	v_mfma_f32_16x16x32_bf16 v[84:87], v[164:167], v[208:211], v[84:87]
	v_mfma_f32_16x16x32_bf16 v[76:79], v[156:159], v[216:219], v[76:79]
	v_mfma_f32_16x16x32_bf16 v[68:71], v[164:167], v[216:219], v[68:71]
	v_mfma_f32_16x16x32_bf16 v[124:127], v[168:171], v[188:191], v[124:127]
	v_mfma_f32_16x16x32_bf16 v[120:123], v[176:179], v[188:191], v[120:123]
	v_mfma_f32_16x16x32_bf16 v[112:115], v[168:171], v[196:199], v[112:115]
	v_mfma_f32_16x16x32_bf16 v[96:99], v[176:179], v[196:199], v[96:99]
	v_mfma_f32_16x16x32_bf16 v[88:91], v[168:171], v[204:207], v[88:91]
	v_mfma_f32_16x16x32_bf16 v[80:83], v[176:179], v[204:207], v[80:83]
	v_mfma_f32_16x16x32_bf16 v[72:75], v[168:171], v[212:215], v[72:75]
	v_mfma_f32_16x16x32_bf16 v[64:67], v[176:179], v[212:215], v[64:67]
	v_mfma_f32_16x16x32_bf16 v[124:127], v[172:175], v[192:195], v[124:127]
	v_mfma_f32_16x16x32_bf16 v[120:123], v[180:183], v[192:195], v[120:123]
	v_mfma_f32_16x16x32_bf16 v[112:115], v[172:175], v[200:203], v[112:115]
	v_mfma_f32_16x16x32_bf16 v[96:99], v[180:183], v[200:203], v[96:99]
	v_mfma_f32_16x16x32_bf16 v[88:91], v[172:175], v[208:211], v[88:91]
	v_mfma_f32_16x16x32_bf16 v[80:83], v[180:183], v[208:211], v[80:83]
	v_mfma_f32_16x16x32_bf16 v[72:75], v[172:175], v[216:219], v[72:75]
	v_mfma_f32_16x16x32_bf16 v[64:67], v[180:183], v[216:219], v[64:67]
	s_barrier
; #define PG8_STAGE(bufoff, gbase, voff) do { _Pragma("unroll") for (int _i = 0; _i < 2; ++_i) \
;         __builtin_amdgcn_global_load_lds((const unsigned*)((const char*)(gbase) + (voff)[_i]), (PG8_LAS unsigned*)(lds + (bufoff) + ldsw + _i * 8192), 16, 0, 0); } while (0)
; #define PG8_LDA(dst, b, h) do { _Pragma("unroll") for (int m = 0; m < 4; ++m) _Pragma("unroll") for (int k = 0; k < 2; ++k) dst[m][k] = *(const PG8_LAS bf16x8*)(lds + PG8_SA(b, h) + aoff + m * 2048 + k * 1024); } while (0)
; #define PG8_MMA(ai, bj, At, Bt) do { __builtin_amdgcn_s_setprio(1); _Pragma("unroll") for (int m = 0; m < 4; ++m) _Pragma("unroll") for (int n = 0; n < 2; ++n) _Pragma("unroll") for (int k = 0; k < 2; ++k) \
;         acc[ai][bj][m][n] = __builtin_amdgcn_mfma_f32_16x16x32_bf16(Bt[n][k], At[m][k], acc[ai][bj][m][n], 0, 0, 0); __builtin_amdgcn_s_setprio(0); } while (0)
; #define PG8_WAIT_V(n) asm volatile("s_waitcnt vmcnt(" #n ")" ::: "memory")
; #define PG8_WAIT_L(n) asm volatile("s_waitcnt lgkmcnt(" #n ")" ::: "memory")
; #define PG8_BAR __builtin_amdgcn_s_barrier()
; #define PG8_SCHED __builtin_amdgcn_sched_barrier(0)
; template <class Epi, class Sched, bool ALIGN_EPI = false, bool SP2 = false>
; __device__ __forceinline__ void gemm_phase(PG8_LAS unsigned char* lds, const Gemm g, const Sched& S, const Epi& E) {
;     ...
;             PG8_LDA(At, 1, 1); PG8_STAGE(PG8_SB(1, 0), b3, voffB); PG8_STAGE(PG8_SB(1, 1), b3 + hstepB, voffB); PG8_STAGE(PG8_SA(1, 0), a3, voffA);
;             PG8_WAIT_V(8); PG8_WAIT_L(0); PG8_BAR; PG8_MMA(1, 0, At, B0); PG8_MMA(1, 1, At, B1); PG8_BAR; PG8_SCHED;
	s_setprio 0
	s_add_i32 s30, s58, s36
	v_lshl_add_u64 v[184:185], v[184:185], 0, s[8:9]
	s_mov_b32 m0, s30
	ds_read_b128 v[188:191], v149 offset:49152
	ds_read_b128 v[192:195], v149 offset:50176
	ds_read_b128 v[196:199], v149 offset:51200
	ds_read_b128 v[200:203], v149 offset:52224
	ds_read_b128 v[204:207], v149 offset:53248
	ds_read_b128 v[208:211], v149 offset:54272
	ds_read_b128 v[212:215], v149 offset:55296
	ds_read_b128 v[216:219], v149 offset:56320
	global_load_lds_dwordx4 v[184:185], off
	s_add_i32 m0, s30, 0x2000
	s_add_u32 s28, s28, 0x40080
	v_lshl_add_u64 v[184:185], v[220:221], 0, s[8:9]
	s_addc_u32 s29, s29, 0
	s_add_i32 s30, s59, s36
	global_load_lds_dwordx4 v[184:185], off
	v_lshl_add_u64 v[184:185], s[28:29], 0, v[132:133]
	s_mov_b32 m0, s30
	s_nop 0
	global_load_lds_dwordx4 v[184:185], off
	v_lshl_add_u64 v[184:185], s[28:29], 0, v[128:129]
	s_add_i32 m0, s30, 0x2000
	s_nop 0
	global_load_lds_dwordx4 v[184:185], off
	v_lshl_add_u64 v[184:185], v[222:223], 0, s[8:9]
	s_mov_b32 m0, s43
	s_nop 0
	global_load_lds_dwordx4 v[184:185], off
	v_lshl_add_u64 v[184:185], v[224:225], 0, s[8:9]
	s_mov_b32 m0, s44
	s_nop 0
	global_load_lds_dwordx4 v[184:185], off
	s_waitcnt vmcnt(8) lgkmcnt(0)
	s_barrier
	v_mfma_f32_16x16x32_bf16 v[60:63], v[152:155], v[188:191], v[60:63]
	s_setprio 1
	v_mfma_f32_16x16x32_bf16 v[52:55], v[160:163], v[188:191], v[52:55]
	v_mfma_f32_16x16x32_bf16 v[44:47], v[152:155], v[196:199], v[44:47]
	v_mfma_f32_16x16x32_bf16 v[36:39], v[160:163], v[196:199], v[36:39]
	v_mfma_f32_16x16x32_bf16 v[28:31], v[152:155], v[204:207], v[28:31]
	v_mfma_f32_16x16x32_bf16 v[20:23], v[160:163], v[204:207], v[20:23]
	v_mfma_f32_16x16x32_bf16 v[12:15], v[152:155], v[212:215], v[12:15]
	v_mfma_f32_16x16x32_bf16 v[4:7], v[160:163], v[212:215], v[4:7]
	v_mfma_f32_16x16x32_bf16 v[60:63], v[156:159], v[192:195], v[60:63]
	v_mfma_f32_16x16x32_bf16 v[52:55], v[164:167], v[192:195], v[52:55]
	v_mfma_f32_16x16x32_bf16 v[44:47], v[156:159], v[200:203], v[44:47]
	v_mfma_f32_16x16x32_bf16 v[36:39], v[164:167], v[200:203], v[36:39]
	v_mfma_f32_16x16x32_bf16 v[28:31], v[156:159], v[208:211], v[28:31]
	v_mfma_f32_16x16x32_bf16 v[20:23], v[164:167], v[208:211], v[20:23]
	v_mfma_f32_16x16x32_bf16 v[12:15], v[156:159], v[216:219], v[12:15]
	v_mfma_f32_16x16x32_bf16 v[4:7], v[164:167], v[216:219], v[4:7]
	v_mfma_f32_16x16x32_bf16 v[56:59], v[168:171], v[188:191], v[56:59]
	v_mfma_f32_16x16x32_bf16 v[48:51], v[176:179], v[188:191], v[48:51]
	v_mfma_f32_16x16x32_bf16 v[40:43], v[168:171], v[196:199], v[40:43]
	v_mfma_f32_16x16x32_bf16 v[32:35], v[176:179], v[196:199], v[32:35]
	v_mfma_f32_16x16x32_bf16 v[24:27], v[168:171], v[204:207], v[24:27]
	v_mfma_f32_16x16x32_bf16 v[16:19], v[176:179], v[204:207], v[16:19]
	v_mfma_f32_16x16x32_bf16 v[8:11], v[168:171], v[212:215], v[8:11]
	v_mfma_f32_16x16x32_bf16 v[0:3], v[176:179], v[212:215], v[0:3]
	v_mfma_f32_16x16x32_bf16 v[56:59], v[172:175], v[192:195], v[56:59]
	v_mfma_f32_16x16x32_bf16 v[48:51], v[180:183], v[192:195], v[48:51]
	v_mfma_f32_16x16x32_bf16 v[40:43], v[172:175], v[200:203], v[40:43]
	v_mfma_f32_16x16x32_bf16 v[32:35], v[180:183], v[200:203], v[32:35]
	v_mfma_f32_16x16x32_bf16 v[24:27], v[172:175], v[208:211], v[24:27]
	v_mfma_f32_16x16x32_bf16 v[16:19], v[180:183], v[208:211], v[16:19]
	v_mfma_f32_16x16x32_bf16 v[8:11], v[172:175], v[216:219], v[8:11]
	v_mfma_f32_16x16x32_bf16 v[0:3], v[180:183], v[216:219], v[0:3]
	s_barrier
	s_setprio 0
	s_add_i32 s68, s68, 2
	s_add_u32 s26, s26, 0x100
	s_addc_u32 s27, s27, 0
	s_add_u32 s66, s66, 0x100
	s_addc_u32 s67, s67, 0
	s_cmp_gt_u32 s68, 13
	s_cbranch_scc0 .LBB0_244
	s_and_b64 vcc, exec, s[10:11]
	s_cbranch_vccz .LBB0_247
	s_barrier

; #define PG8_STAGE(bufoff, gbase, voff) do { _Pragma("unroll") for (int _i = 0; _i < 2; ++_i) \
;         __builtin_amdgcn_global_load_lds((const unsigned*)((const char*)(gbase) + (voff)[_i]), (PG8_LAS unsigned*)(lds + (bufoff) + ldsw + _i * 8192), 16, 0, 0); } while (0)
; #define PG8_LDA(dst, b, h) do { _Pragma("unroll") for (int m = 0; m < 4; ++m) _Pragma("unroll") for (int k = 0; k < 2; ++k) dst[m][k] = *(const PG8_LAS bf16x8*)(lds + PG8_SA(b, h) + aoff + m * 2048 + k * 1024); } while (0)
; #define PG8_LDB(dst, b, h) do { _Pragma("unroll") for (int n = 0; n < 2; ++n) _Pragma("unroll") for (int k = 0; k < 2; ++k) dst[n][k] = *(const PG8_LAS bf16x8*)(lds + PG8_SB(b, h) + boff + n * 2048 + k * 1024); } while (0)
; #define PG8_MMA(ai, bj, At, Bt) do { __builtin_amdgcn_s_setprio(1); _Pragma("unroll") for (int m = 0; m < 4; ++m) _Pragma("unroll") for (int n = 0; n < 2; ++n) _Pragma("unroll") for (int k = 0; k < 2; ++k) \
;         acc[ai][bj][m][n] = __builtin_amdgcn_mfma_f32_16x16x32_bf16(Bt[n][k], At[m][k], acc[ai][bj][m][n], 0, 0, 0); __builtin_amdgcn_s_setprio(0); } while (0)
; #define PG8_WAIT_V(n) asm volatile("s_waitcnt vmcnt(" #n ")" ::: "memory")
; #define PG8_BAR __builtin_amdgcn_s_barrier()
; template <class Epi, class Sched, bool ALIGN_EPI = false, bool SP2 = false>
; __device__ __forceinline__ void gemm_phase(PG8_LAS unsigned char* lds, const Gemm g, const Sched& S, const Epi& E) {
;     ...
;         for (int t = 0; t < nt; t += 2) {
;             const bool last = (t == nt - 2);
;             const char* a1 = cA + (size_t)(t + 1) * kstep;
;             const char* a2 = last ? nA : cA + (size_t)(t + 2) * kstep; const char* b2 = last ? nB : cB + (size_t)(t + 2) * kstep;
;             const char* a3 = a2 + kstep; const char* b3 = b2 + kstep;
;             if (last && has_next) S.a_ready(nxt);
;             if constexpr (SP2) {
;             PG8_LDB(B0, 0, 0); PG8_LDB(B1, 0, 1); PG8_SCHED; PG8_LDA(At, 0, 0); PG8_STAGE(PG8_SA(1, 1), a1 + hstepA, voffA);
;             PG8_WAIT_V(8); PG8_WAIT_L(0); PG8_BAR; PG8_MMA(0, 0, At, B0); PG8_MMA(0, 1, At, B1); PG8_BAR; PG8_SCHED;
;             PG8_LDA(At, 0, 1); PG8_STAGE(PG8_SB(0, 0), b2, voffB); PG8_STAGE(PG8_SB(0, 1), b2 + hstepB, voffB); PG8_STAGE(PG8_SA(0, 0), a2, voffA);
;             PG8_WAIT_V(8); PG8_WAIT_L(0); PG8_BAR; PG8_MMA(1, 0, At, B0); PG8_MMA(1, 1, At, B1); PG8_BAR; PG8_SCHED;
.LBB0_318:
	ds_read_b128 v[128:131], v191
	ds_read_b128 v[132:135], v191 offset:1024
	ds_read_b128 v[136:139], v191 offset:2048
	ds_read_b128 v[140:143], v191 offset:3072
	ds_read_b128 v[144:147], v192
	ds_read_b128 v[148:151], v192 offset:1024
	ds_read_b128 v[168:171], v192 offset:2048
	ds_read_b128 v[172:175], v192 offset:3072
	s_add_u32 s28, s26, 0x100
	s_addc_u32 s29, s27, 0
	s_cmp_eq_u32 s72, 40
	s_cselect_b32 s35, s11, s29
	s_cselect_b32 s34, s10, s28
	s_cselect_b32 s31, s23, s71
	s_cselect_b32 s30, s22, s70
	v_lshl_add_u64 v[184:185], s[26:27], 0, v[160:161]
	s_add_i32 m0, s39, 0xc000
	ds_read_b128 v[176:179], v193
	ds_read_b128 v[180:183], v193 offset:1024
	ds_read_b128 v[196:199], v193 offset:2048
	ds_read_b128 v[200:203], v193 offset:3072
	ds_read_b128 v[204:207], v193 offset:4096
	ds_read_b128 v[208:211], v193 offset:5120
	ds_read_b128 v[212:215], v193 offset:6144
	ds_read_b128 v[216:219], v193 offset:7168
	global_load_lds_dwordx4 v[184:185], off
	v_lshl_add_u64 v[184:185], s[26:27], 0, v[162:163]
	s_add_i32 m0, s39, 0xe000
	s_nop 0
	global_load_lds_dwordx4 v[184:185], off
	s_waitcnt vmcnt(8) lgkmcnt(0)
	s_barrier
	v_mfma_f32_16x16x32_bf16 v[124:127], v[128:131], v[176:179], v[124:127]
	s_setprio 1
	v_mfma_f32_16x16x32_bf16 v[120:123], v[136:139], v[176:179], v[120:123]
	v_mfma_f32_16x16x32_bf16 v[108:111], v[128:131], v[196:199], v[108:111]
	v_mfma_f32_16x16x32_bf16 v[104:107], v[136:139], v[196:199], v[104:107]
	v_mfma_f32_16x16x32_bf16 v[92:95], v[128:131], v[204:207], v[92:95]
	v_mfma_f32_16x16x32_bf16 v[88:91], v[136:139], v[204:207], v[88:91]
	v_mfma_f32_16x16x32_bf16 v[76:79], v[128:131], v[212:215], v[76:79]
	v_mfma_f32_16x16x32_bf16 v[72:75], v[136:139], v[212:215], v[72:75]
	v_mfma_f32_16x16x32_bf16 v[124:127], v[132:135], v[180:183], v[124:127]
	v_mfma_f32_16x16x32_bf16 v[120:123], v[140:143], v[180:183], v[120:123]
	v_mfma_f32_16x16x32_bf16 v[108:111], v[132:135], v[200:203], v[108:111]
	v_mfma_f32_16x16x32_bf16 v[104:107], v[140:143], v[200:203], v[104:107]
	v_mfma_f32_16x16x32_bf16 v[92:95], v[132:135], v[208:211], v[92:95]
	v_mfma_f32_16x16x32_bf16 v[88:91], v[140:143], v[208:211], v[88:91]
	v_mfma_f32_16x16x32_bf16 v[76:79], v[132:135], v[216:219], v[76:79]
	v_mfma_f32_16x16x32_bf16 v[72:75], v[140:143], v[216:219], v[72:75]
	v_mfma_f32_16x16x32_bf16 v[116:119], v[144:147], v[176:179], v[116:119]
	v_mfma_f32_16x16x32_bf16 v[112:115], v[168:171], v[176:179], v[112:115]
	v_mfma_f32_16x16x32_bf16 v[100:103], v[144:147], v[196:199], v[100:103]
	v_mfma_f32_16x16x32_bf16 v[96:99], v[168:171], v[196:199], v[96:99]
	v_mfma_f32_16x16x32_bf16 v[84:87], v[144:147], v[204:207], v[84:87]
	v_mfma_f32_16x16x32_bf16 v[80:83], v[168:171], v[204:207], v[80:83]
	v_mfma_f32_16x16x32_bf16 v[68:71], v[144:147], v[212:215], v[68:71]
	v_mfma_f32_16x16x32_bf16 v[64:67], v[168:171], v[212:215], v[64:67]
	v_mfma_f32_16x16x32_bf16 v[116:119], v[148:151], v[180:183], v[116:119]
	v_mfma_f32_16x16x32_bf16 v[112:115], v[172:175], v[180:183], v[112:115]
	v_mfma_f32_16x16x32_bf16 v[100:103], v[148:151], v[200:203], v[100:103]
	v_mfma_f32_16x16x32_bf16 v[96:99], v[172:175], v[200:203], v[96:99]
	v_mfma_f32_16x16x32_bf16 v[84:87], v[148:151], v[208:211], v[84:87]
	v_mfma_f32_16x16x32_bf16 v[80:83], v[172:175], v[208:211], v[80:83]
	v_mfma_f32_16x16x32_bf16 v[68:71], v[148:151], v[216:219], v[68:71]
	v_mfma_f32_16x16x32_bf16 v[64:67], v[172:175], v[216:219], v[64:67]
	s_barrier
	s_setprio 0
	s_add_i32 s26, s49, s38
	v_lshl_add_u64 v[184:185], s[30:31], 0, v[154:155]
	s_mov_b32 m0, s26
	ds_read_b128 v[176:179], v193 offset:16384
	ds_read_b128 v[180:183], v193 offset:17408
	ds_read_b128 v[196:199], v193 offset:18432
	ds_read_b128 v[200:203], v193 offset:19456
	ds_read_b128 v[204:207], v193 offset:20480
	ds_read_b128 v[208:211], v193 offset:21504
	ds_read_b128 v[212:215], v193 offset:22528
	ds_read_b128 v[216:219], v193 offset:23552
	global_load_lds_dwordx4 v[184:185], off
	s_add_i32 m0, s26, 0x2000
	s_add_u32 s26, s30, 0xb0000
	v_lshl_add_u64 v[220:221], s[30:31], 0, v[158:159]
	s_addc_u32 s27, s31, 0
	s_add_i32 s58, s62, s38
	global_load_lds_dwordx4 v[220:221], off
	v_lshl_add_u64 v[222:223], s[26:27], 0, v[154:155]
	s_mov_b32 m0, s58
	v_lshl_add_u64 v[224:225], s[34:35], 0, v[156:157]
	global_load_lds_dwordx4 v[222:223], off
	v_lshl_add_u64 v[222:223], s[26:27], 0, v[158:159]
	s_add_i32 m0, s58, 0x2000
	s_nop 0
	global_load_lds_dwordx4 v[222:223], off
	v_lshl_add_u64 v[222:223], s[34:35], 0, v[152:153]
	s_mov_b32 m0, s39
	s_nop 0
	global_load_lds_dwordx4 v[222:223], off
	s_mov_b32 m0, s40
	s_nop 0
	global_load_lds_dwordx4 v[224:225], off
	s_waitcnt vmcnt(8) lgkmcnt(0)
	s_barrier
; #define PG8_STAGE(bufoff, gbase, voff) do { _Pragma("unroll") for (int _i = 0; _i < 2; ++_i) \
;         __builtin_amdgcn_global_load_lds((const unsigned*)((const char*)(gbase) + (voff)[_i]), (PG8_LAS unsigned*)(lds + (bufoff) + ldsw + _i * 8192), 16, 0, 0); } while (0)
; #define PG8_LDA(dst, b, h) do { _Pragma("unroll") for (int m = 0; m < 4; ++m) _Pragma("unroll") for (int k = 0; k < 2; ++k) dst[m][k] = *(const PG8_LAS bf16x8*)(lds + PG8_SA(b, h) + aoff + m * 2048 + k * 1024); } while (0)
; #define PG8_LDB(dst, b, h) do { _Pragma("unroll") for (int n = 0; n < 2; ++n) _Pragma("unroll") for (int k = 0; k < 2; ++k) dst[n][k] = *(const PG8_LAS bf16x8*)(lds + PG8_SB(b, h) + boff + n * 2048 + k * 1024); } while (0)
; #define PG8_MMA(ai, bj, At, Bt) do { __builtin_amdgcn_s_setprio(1); _Pragma("unroll") for (int m = 0; m < 4; ++m) _Pragma("unroll") for (int n = 0; n < 2; ++n) _Pragma("unroll") for (int k = 0; k < 2; ++k) \
;         acc[ai][bj][m][n] = __builtin_amdgcn_mfma_f32_16x16x32_bf16(Bt[n][k], At[m][k], acc[ai][bj][m][n], 0, 0, 0); __builtin_amdgcn_s_setprio(0); } while (0)
; #define PG8_WAIT_V(n) asm volatile("s_waitcnt vmcnt(" #n ")" ::: "memory")
; #define PG8_WAIT_L(n) asm volatile("s_waitcnt lgkmcnt(" #n ")" ::: "memory")
; #define PG8_BAR __builtin_amdgcn_s_barrier()
; #define PG8_SCHED __builtin_amdgcn_sched_barrier(0)
; template <class Epi, class Sched, bool ALIGN_EPI = false, bool SP2 = false>
; __device__ __forceinline__ void gemm_phase(PG8_LAS unsigned char* lds, const Gemm g, const Sched& S, const Epi& E) {
;     ...
;             PG8_WAIT_V(8); PG8_WAIT_L(0); PG8_BAR; PG8_MMA(1, 0, At, B0); PG8_MMA(1, 1, At, B1); PG8_BAR; PG8_SCHED;
;             PG8_LDB(B0, 1, 0); PG8_LDB(B1, 1, 1); PG8_SCHED; PG8_LDA(At, 1, 0); PG8_STAGE(PG8_SA(0, 1), a2 + hstepA, voffA);
;             PG8_WAIT_V(8); PG8_WAIT_L(0); PG8_BAR; PG8_MMA(0, 0, At, B0); PG8_MMA(0, 1, At, B1); PG8_BAR; PG8_SCHED;
	v_mfma_f32_16x16x32_bf16 v[60:63], v[128:131], v[176:179], v[60:63]
	s_setprio 1
	v_mfma_f32_16x16x32_bf16 v[56:59], v[136:139], v[176:179], v[56:59]
	v_mfma_f32_16x16x32_bf16 v[44:47], v[128:131], v[196:199], v[44:47]
	v_mfma_f32_16x16x32_bf16 v[40:43], v[136:139], v[196:199], v[40:43]
	v_mfma_f32_16x16x32_bf16 v[28:31], v[128:131], v[204:207], v[28:31]
	v_mfma_f32_16x16x32_bf16 v[24:27], v[136:139], v[204:207], v[24:27]
	v_mfma_f32_16x16x32_bf16 v[12:15], v[128:131], v[212:215], v[12:15]
	v_mfma_f32_16x16x32_bf16 v[8:11], v[136:139], v[212:215], v[8:11]
	v_mfma_f32_16x16x32_bf16 v[60:63], v[132:135], v[180:183], v[60:63]
	v_mfma_f32_16x16x32_bf16 v[56:59], v[140:143], v[180:183], v[56:59]
	v_mfma_f32_16x16x32_bf16 v[44:47], v[132:135], v[200:203], v[44:47]
	v_mfma_f32_16x16x32_bf16 v[40:43], v[140:143], v[200:203], v[40:43]
	v_mfma_f32_16x16x32_bf16 v[28:31], v[132:135], v[208:211], v[28:31]
	v_mfma_f32_16x16x32_bf16 v[24:27], v[140:143], v[208:211], v[24:27]
	v_mfma_f32_16x16x32_bf16 v[12:15], v[132:135], v[216:219], v[12:15]
	v_mfma_f32_16x16x32_bf16 v[8:11], v[140:143], v[216:219], v[8:11]
	v_mfma_f32_16x16x32_bf16 v[52:55], v[144:147], v[176:179], v[52:55]
	v_mfma_f32_16x16x32_bf16 v[48:51], v[168:171], v[176:179], v[48:51]
	v_mfma_f32_16x16x32_bf16 v[36:39], v[144:147], v[196:199], v[36:39]
	v_mfma_f32_16x16x32_bf16 v[32:35], v[168:171], v[196:199], v[32:35]
	v_mfma_f32_16x16x32_bf16 v[20:23], v[144:147], v[204:207], v[20:23]
	v_mfma_f32_16x16x32_bf16 v[16:19], v[168:171], v[204:207], v[16:19]
	v_mfma_f32_16x16x32_bf16 v[4:7], v[144:147], v[212:215], v[4:7]
	v_mfma_f32_16x16x32_bf16 v[0:3], v[168:171], v[212:215], v[0:3]
	v_mfma_f32_16x16x32_bf16 v[52:55], v[148:151], v[180:183], v[52:55]
	v_mfma_f32_16x16x32_bf16 v[48:51], v[172:175], v[180:183], v[48:51]
	v_mfma_f32_16x16x32_bf16 v[36:39], v[148:151], v[200:203], v[36:39]
	v_mfma_f32_16x16x32_bf16 v[32:35], v[172:175], v[200:203], v[32:35]
	v_mfma_f32_16x16x32_bf16 v[20:23], v[148:151], v[208:211], v[20:23]
	v_mfma_f32_16x16x32_bf16 v[16:19], v[172:175], v[208:211], v[16:19]
	v_mfma_f32_16x16x32_bf16 v[4:7], v[148:151], v[216:219], v[4:7]
	v_mfma_f32_16x16x32_bf16 v[0:3], v[172:175], v[216:219], v[0:3]
	s_barrier
	s_setprio 0
	s_add_i32 s58, 0, 0x18000
	s_add_i32 s59, 0, 0x1c000
	v_add_u32_e32 v140, s58, v189
	v_add_u32_e32 v172, s59, v189
	ds_read_b128 v[128:131], v140
	ds_read_b128 v[132:135], v140 offset:1024
	ds_read_b128 v[136:139], v140 offset:2048
	ds_read_b128 v[140:143], v140 offset:3072
	ds_read_b128 v[144:147], v172
	ds_read_b128 v[148:151], v172 offset:1024
	ds_read_b128 v[168:171], v172 offset:2048
	ds_read_b128 v[172:175], v172 offset:3072
	s_add_u32 s26, s34, 0xb0000
	s_addc_u32 s27, s35, 0
	s_mov_b32 m0, s41
	v_lshl_add_u64 v[226:227], s[26:27], 0, v[152:153]
	ds_read_b128 v[176:179], v193 offset:32768
	ds_read_b128 v[180:183], v193 offset:33792
	ds_read_b128 v[196:199], v193 offset:34816
	ds_read_b128 v[200:203], v193 offset:35840
	ds_read_b128 v[204:207], v193 offset:36864
	ds_read_b128 v[208:211], v193 offset:37888
	ds_read_b128 v[212:215], v193 offset:38912
	ds_read_b128 v[216:219], v193 offset:39936
	global_load_lds_dwordx4 v[226:227], off
	v_lshl_add_u64 v[226:227], s[26:27], 0, v[156:157]
	s_mov_b32 m0, s42
	s_nop 0
	global_load_lds_dwordx4 v[226:227], off
	s_waitcnt vmcnt(8) lgkmcnt(0)
	s_barrier
	v_mfma_f32_16x16x32_bf16 v[124:127], v[128:131], v[176:179], v[124:127]
	s_setprio 1
	v_mfma_f32_16x16x32_bf16 v[120:123], v[136:139], v[176:179], v[120:123]
	v_mfma_f32_16x16x32_bf16 v[108:111], v[128:131], v[196:199], v[108:111]
	v_mfma_f32_16x16x32_bf16 v[104:107], v[136:139], v[196:199], v[104:107]
	v_mfma_f32_16x16x32_bf16 v[92:95], v[128:131], v[204:207], v[92:95]
	v_mfma_f32_16x16x32_bf16 v[88:91], v[136:139], v[204:207], v[88:91]
	v_mfma_f32_16x16x32_bf16 v[76:79], v[128:131], v[212:215], v[76:79]
	v_mfma_f32_16x16x32_bf16 v[72:75], v[136:139], v[212:215], v[72:75]
	v_mfma_f32_16x16x32_bf16 v[124:127], v[132:135], v[180:183], v[124:127]
	v_mfma_f32_16x16x32_bf16 v[120:123], v[140:143], v[180:183], v[120:123]
	v_mfma_f32_16x16x32_bf16 v[108:111], v[132:135], v[200:203], v[108:111]
	v_mfma_f32_16x16x32_bf16 v[104:107], v[140:143], v[200:203], v[104:107]
	v_mfma_f32_16x16x32_bf16 v[92:95], v[132:135], v[208:211], v[92:95]
	v_mfma_f32_16x16x32_bf16 v[88:91], v[140:143], v[208:211], v[88:91]
	v_mfma_f32_16x16x32_bf16 v[76:79], v[132:135], v[216:219], v[76:79]
	v_mfma_f32_16x16x32_bf16 v[72:75], v[140:143], v[216:219], v[72:75]
	v_mfma_f32_16x16x32_bf16 v[116:119], v[144:147], v[176:179], v[116:119]
	v_mfma_f32_16x16x32_bf16 v[112:115], v[168:171], v[176:179], v[112:115]
	v_mfma_f32_16x16x32_bf16 v[100:103], v[144:147], v[196:199], v[100:103]
	v_mfma_f32_16x16x32_bf16 v[96:99], v[168:171], v[196:199], v[96:99]
	v_mfma_f32_16x16x32_bf16 v[84:87], v[144:147], v[204:207], v[84:87]
	v_mfma_f32_16x16x32_bf16 v[80:83], v[168:171], v[204:207], v[80:83]
	v_mfma_f32_16x16x32_bf16 v[68:71], v[144:147], v[212:215], v[68:71]
	v_mfma_f32_16x16x32_bf16 v[64:67], v[168:171], v[212:215], v[64:67]
	v_mfma_f32_16x16x32_bf16 v[116:119], v[148:151], v[180:183], v[116:119]
	v_mfma_f32_16x16x32_bf16 v[112:115], v[172:175], v[180:183], v[112:115]
	v_mfma_f32_16x16x32_bf16 v[100:103], v[148:151], v[200:203], v[100:103]
	v_mfma_f32_16x16x32_bf16 v[96:99], v[172:175], v[200:203], v[96:99]
	v_mfma_f32_16x16x32_bf16 v[84:87], v[148:151], v[208:211], v[84:87]
	v_mfma_f32_16x16x32_bf16 v[80:83], v[172:175], v[208:211], v[80:83]
	v_mfma_f32_16x16x32_bf16 v[68:71], v[148:151], v[216:219], v[68:71]
	v_mfma_f32_16x16x32_bf16 v[64:67], v[172:175], v[216:219], v[64:67]
	s_barrier
; #define PG8_STAGE(bufoff, gbase, voff) do { _Pragma("unroll") for (int _i = 0; _i < 2; ++_i) \
;         __builtin_amdgcn_global_load_lds((const unsigned*)((const char*)(gbase) + (voff)[_i]), (PG8_LAS unsigned*)(lds + (bufoff) + ldsw + _i * 8192), 16, 0, 0); } while (0)
; #define PG8_LDA(dst, b, h) do { _Pragma("unroll") for (int m = 0; m < 4; ++m) _Pragma("unroll") for (int k = 0; k < 2; ++k) dst[m][k] = *(const PG8_LAS bf16x8*)(lds + PG8_SA(b, h) + aoff + m * 2048 + k * 1024); } while (0)
; #define PG8_MMA(ai, bj, At, Bt) do { __builtin_amdgcn_s_setprio(1); _Pragma("unroll") for (int m = 0; m < 4; ++m) _Pragma("unroll") for (int n = 0; n < 2; ++n) _Pragma("unroll") for (int k = 0; k < 2; ++k) \
;         acc[ai][bj][m][n] = __builtin_amdgcn_mfma_f32_16x16x32_bf16(Bt[n][k], At[m][k], acc[ai][bj][m][n], 0, 0, 0); __builtin_amdgcn_s_setprio(0); } while (0)
; #define PG8_WAIT_V(n) asm volatile("s_waitcnt vmcnt(" #n ")" ::: "memory")
; #define PG8_WAIT_L(n) asm volatile("s_waitcnt lgkmcnt(" #n ")" ::: "memory")
; #define PG8_BAR __builtin_amdgcn_s_barrier()
; #define PG8_SCHED __builtin_amdgcn_sched_barrier(0)
; template <class Epi, class Sched, bool ALIGN_EPI = false, bool SP2 = false>
; __device__ __forceinline__ void gemm_phase(PG8_LAS unsigned char* lds, const Gemm g, const Sched& S, const Epi& E) {
;     ...
;             PG8_LDA(At, 1, 1); PG8_STAGE(PG8_SB(1, 0), b3, voffB); PG8_STAGE(PG8_SB(1, 1), b3 + hstepB, voffB); PG8_STAGE(PG8_SA(1, 0), a3, voffA);
;             PG8_WAIT_V(8); PG8_WAIT_L(0); PG8_BAR; PG8_MMA(1, 0, At, B0); PG8_MMA(1, 1, At, B1); PG8_BAR; PG8_SCHED;
	s_setprio 0
	s_add_i32 s26, s58, s38
	v_lshl_add_u64 v[184:185], v[184:185], 0, s[14:15]
	s_mov_b32 m0, s26
	ds_read_b128 v[176:179], v193 offset:49152
	ds_read_b128 v[180:183], v193 offset:50176
	ds_read_b128 v[196:199], v193 offset:51200
	ds_read_b128 v[200:203], v193 offset:52224
	ds_read_b128 v[204:207], v193 offset:53248
	ds_read_b128 v[208:211], v193 offset:54272
	ds_read_b128 v[212:215], v193 offset:55296
	ds_read_b128 v[216:219], v193 offset:56320
	global_load_lds_dwordx4 v[184:185], off
	s_add_i32 m0, s26, 0x2000
	s_add_u32 s26, s30, 0xb0080
	v_lshl_add_u64 v[184:185], v[220:221], 0, s[14:15]
	s_addc_u32 s27, s31, 0
	s_add_i32 s30, s59, s38
	global_load_lds_dwordx4 v[184:185], off
	v_lshl_add_u64 v[184:185], s[26:27], 0, v[154:155]
	s_mov_b32 m0, s30
	s_nop 0
	global_load_lds_dwordx4 v[184:185], off
	v_lshl_add_u64 v[184:185], s[26:27], 0, v[158:159]
	s_add_i32 m0, s30, 0x2000
	s_nop 0
	global_load_lds_dwordx4 v[184:185], off
	v_lshl_add_u64 v[184:185], v[222:223], 0, s[14:15]
	s_mov_b32 m0, s44
	s_nop 0
	global_load_lds_dwordx4 v[184:185], off
	v_lshl_add_u64 v[184:185], v[224:225], 0, s[14:15]
	s_mov_b32 m0, s45
	s_nop 0
	global_load_lds_dwordx4 v[184:185], off
	s_waitcnt vmcnt(8) lgkmcnt(0)
	s_barrier
	v_mfma_f32_16x16x32_bf16 v[60:63], v[128:131], v[176:179], v[60:63]
	s_setprio 1
	v_mfma_f32_16x16x32_bf16 v[56:59], v[136:139], v[176:179], v[56:59]
	v_mfma_f32_16x16x32_bf16 v[44:47], v[128:131], v[196:199], v[44:47]
	v_mfma_f32_16x16x32_bf16 v[40:43], v[136:139], v[196:199], v[40:43]
	v_mfma_f32_16x16x32_bf16 v[28:31], v[128:131], v[204:207], v[28:31]
	v_mfma_f32_16x16x32_bf16 v[24:27], v[136:139], v[204:207], v[24:27]
	v_mfma_f32_16x16x32_bf16 v[12:15], v[128:131], v[212:215], v[12:15]
	v_mfma_f32_16x16x32_bf16 v[8:11], v[136:139], v[212:215], v[8:11]
	v_mfma_f32_16x16x32_bf16 v[60:63], v[132:135], v[180:183], v[60:63]
	v_mfma_f32_16x16x32_bf16 v[56:59], v[140:143], v[180:183], v[56:59]
	v_mfma_f32_16x16x32_bf16 v[44:47], v[132:135], v[200:203], v[44:47]
	v_mfma_f32_16x16x32_bf16 v[40:43], v[140:143], v[200:203], v[40:43]
	v_mfma_f32_16x16x32_bf16 v[28:31], v[132:135], v[208:211], v[28:31]
	v_mfma_f32_16x16x32_bf16 v[24:27], v[140:143], v[208:211], v[24:27]
	v_mfma_f32_16x16x32_bf16 v[12:15], v[132:135], v[216:219], v[12:15]
	v_mfma_f32_16x16x32_bf16 v[8:11], v[140:143], v[216:219], v[8:11]
	v_mfma_f32_16x16x32_bf16 v[52:55], v[144:147], v[176:179], v[52:55]
	v_mfma_f32_16x16x32_bf16 v[48:51], v[168:171], v[176:179], v[48:51]
	v_mfma_f32_16x16x32_bf16 v[36:39], v[144:147], v[196:199], v[36:39]
	v_mfma_f32_16x16x32_bf16 v[32:35], v[168:171], v[196:199], v[32:35]
	v_mfma_f32_16x16x32_bf16 v[20:23], v[144:147], v[204:207], v[20:23]
	v_mfma_f32_16x16x32_bf16 v[16:19], v[168:171], v[204:207], v[16:19]
	v_mfma_f32_16x16x32_bf16 v[4:7], v[144:147], v[212:215], v[4:7]
	v_mfma_f32_16x16x32_bf16 v[0:3], v[168:171], v[212:215], v[0:3]
	v_mfma_f32_16x16x32_bf16 v[52:55], v[148:151], v[180:183], v[52:55]
	v_mfma_f32_16x16x32_bf16 v[48:51], v[172:175], v[180:183], v[48:51]
	v_mfma_f32_16x16x32_bf16 v[36:39], v[148:151], v[200:203], v[36:39]
	v_mfma_f32_16x16x32_bf16 v[32:35], v[172:175], v[200:203], v[32:35]
	v_mfma_f32_16x16x32_bf16 v[20:23], v[148:151], v[208:211], v[20:23]
	v_mfma_f32_16x16x32_bf16 v[16:19], v[172:175], v[208:211], v[16:19]
	v_mfma_f32_16x16x32_bf16 v[4:7], v[148:151], v[216:219], v[4:7]
	v_mfma_f32_16x16x32_bf16 v[0:3], v[172:175], v[216:219], v[0:3]
	s_barrier
	s_setprio 0
	s_add_i32 s72, s72, 2
	s_add_u32 s70, s70, 0x100
	s_addc_u32 s71, s71, 0
	s_cmp_gt_u32 s72, 41
	s_mov_b64 s[26:27], s[28:29]
	s_cbranch_scc0 .LBB0_318
	s_and_b64 vcc, exec, s[20:21]
	s_cbranch_vccz .LBB0_321
	s_barrier

; #define PG8_STAGE(bufoff, gbase, voff) do { _Pragma("unroll") for (int _i = 0; _i < 2; ++_i) \
;         __builtin_amdgcn_global_load_lds((const unsigned*)((const char*)(gbase) + (voff)[_i]), (PG8_LAS unsigned*)(lds + (bufoff) + ldsw + _i * 8192), 16, 0, 0); } while (0)
; #define PG8_LDA(dst, b, h) do { _Pragma("unroll") for (int m = 0; m < 4; ++m) _Pragma("unroll") for (int k = 0; k < 2; ++k) dst[m][k] = *(const PG8_LAS bf16x8*)(lds + PG8_SA(b, h) + aoff + m * 2048 + k * 1024); } while (0)
; #define PG8_LDB(dst, b, h) do { _Pragma("unroll") for (int n = 0; n < 2; ++n) _Pragma("unroll") for (int k = 0; k < 2; ++k) dst[n][k] = *(const PG8_LAS bf16x8*)(lds + PG8_SB(b, h) + boff + n * 2048 + k * 1024); } while (0)
; #define PG8_MMA(ai, bj, At, Bt) do { __builtin_amdgcn_s_setprio(1); _Pragma("unroll") for (int m = 0; m < 4; ++m) _Pragma("unroll") for (int n = 0; n < 2; ++n) _Pragma("unroll") for (int k = 0; k < 2; ++k) \
;         acc[ai][bj][m][n] = __builtin_amdgcn_mfma_f32_16x16x32_bf16(Bt[n][k], At[m][k], acc[ai][bj][m][n], 0, 0, 0); __builtin_amdgcn_s_setprio(0); } while (0)
; #define PG8_WAIT_V(n) asm volatile("s_waitcnt vmcnt(" #n ")" ::: "memory")
; #define PG8_BAR __builtin_amdgcn_s_barrier()
; template <class Epi, class Sched, bool ALIGN_EPI = false, bool SP2 = false>
; __device__ __forceinline__ void gemm_phase(PG8_LAS unsigned char* lds, const Gemm g, const Sched& S, const Epi& E) {
;     ...
;         for (int t = 0; t < nt; t += 2) {
;             const bool last = (t == nt - 2);
;             const char* a1 = cA + (size_t)(t + 1) * kstep;
;             const char* a2 = last ? nA : cA + (size_t)(t + 2) * kstep; const char* b2 = last ? nB : cB + (size_t)(t + 2) * kstep;
;             const char* a3 = a2 + kstep; const char* b3 = b2 + kstep;
;             if (last && has_next) S.a_ready(nxt);
;             if constexpr (SP2) {
;             PG8_LDB(B0, 0, 0); PG8_LDB(B1, 0, 1); PG8_SCHED; PG8_LDA(At, 0, 0); PG8_STAGE(PG8_SA(1, 1), a1 + hstepA, voffA);
;             PG8_WAIT_V(8); PG8_WAIT_L(0); PG8_BAR; PG8_MMA(0, 0, At, B0); PG8_MMA(0, 1, At, B1); PG8_BAR; PG8_SCHED;
;             PG8_LDA(At, 0, 1); PG8_STAGE(PG8_SB(0, 0), b2, voffB); PG8_STAGE(PG8_SB(0, 1), b2 + hstepB, voffB); PG8_STAGE(PG8_SA(0, 0), a2, voffA);
;             PG8_WAIT_V(8); PG8_WAIT_L(0); PG8_BAR; PG8_MMA(1, 0, At, B0); PG8_MMA(1, 1, At, B1); PG8_BAR; PG8_SCHED;
.LBB0_404:
	ds_read_b128 v[152:155], v165
	ds_read_b128 v[156:159], v165 offset:1024
	ds_read_b128 v[178:181], v165 offset:2048
	ds_read_b128 v[182:185], v165 offset:3072
	ds_read_b128 v[188:191], v166
	ds_read_b128 v[192:195], v166 offset:1024
	ds_read_b128 v[196:199], v166 offset:2048
	ds_read_b128 v[200:203], v166 offset:3072
	s_add_u32 s46, s14, 0xfffc0080
	s_addc_u32 s47, s15, -1
	s_cmp_eq_u32 s91, 12
	s_cselect_b32 s49, s11, s47
	s_cselect_b32 s48, s13, s46
	s_cselect_b32 s47, s39, s67
	s_cselect_b32 s46, s41, s66
	v_lshl_add_u64 v[160:161], s[14:15], 0, v[144:145]
	s_add_i32 m0, s71, 0xc000
	ds_read_b128 v[204:207], v167
	ds_read_b128 v[208:211], v167 offset:1024
	ds_read_b128 v[212:215], v167 offset:2048
	ds_read_b128 v[216:219], v167 offset:3072
	ds_read_b128 v[220:223], v167 offset:4096
	ds_read_b128 v[224:227], v167 offset:5120
	ds_read_b128 v[228:231], v167 offset:6144
	ds_read_b128 v[232:235], v167 offset:7168
	global_load_lds_dwordx4 v[160:161], off
	v_lshl_add_u64 v[160:161], s[14:15], 0, v[146:147]
	s_add_i32 m0, s71, 0xe000
	s_nop 0
	global_load_lds_dwordx4 v[160:161], off
	s_waitcnt vmcnt(8) lgkmcnt(0)
	s_barrier
	v_mfma_f32_16x16x32_bf16 v[124:127], v[152:155], v[204:207], v[124:127]
	s_setprio 1
	v_mfma_f32_16x16x32_bf16 v[120:123], v[178:181], v[204:207], v[120:123]
	v_mfma_f32_16x16x32_bf16 v[108:111], v[152:155], v[212:215], v[108:111]
	v_mfma_f32_16x16x32_bf16 v[104:107], v[178:181], v[212:215], v[104:107]
	v_mfma_f32_16x16x32_bf16 v[92:95], v[152:155], v[220:223], v[92:95]
	v_mfma_f32_16x16x32_bf16 v[88:91], v[178:181], v[220:223], v[88:91]
	v_mfma_f32_16x16x32_bf16 v[76:79], v[152:155], v[228:231], v[76:79]
	v_mfma_f32_16x16x32_bf16 v[72:75], v[178:181], v[228:231], v[72:75]
	v_mfma_f32_16x16x32_bf16 v[124:127], v[156:159], v[208:211], v[124:127]
	v_mfma_f32_16x16x32_bf16 v[120:123], v[182:185], v[208:211], v[120:123]
	v_mfma_f32_16x16x32_bf16 v[108:111], v[156:159], v[216:219], v[108:111]
	v_mfma_f32_16x16x32_bf16 v[104:107], v[182:185], v[216:219], v[104:107]
	v_mfma_f32_16x16x32_bf16 v[92:95], v[156:159], v[224:227], v[92:95]
	v_mfma_f32_16x16x32_bf16 v[88:91], v[182:185], v[224:227], v[88:91]
	v_mfma_f32_16x16x32_bf16 v[76:79], v[156:159], v[232:235], v[76:79]
	v_mfma_f32_16x16x32_bf16 v[72:75], v[182:185], v[232:235], v[72:75]
	v_mfma_f32_16x16x32_bf16 v[116:119], v[188:191], v[204:207], v[116:119]
	v_mfma_f32_16x16x32_bf16 v[112:115], v[196:199], v[204:207], v[112:115]
	v_mfma_f32_16x16x32_bf16 v[100:103], v[188:191], v[212:215], v[100:103]
	v_mfma_f32_16x16x32_bf16 v[96:99], v[196:199], v[212:215], v[96:99]
	v_mfma_f32_16x16x32_bf16 v[84:87], v[188:191], v[220:223], v[84:87]
	v_mfma_f32_16x16x32_bf16 v[80:83], v[196:199], v[220:223], v[80:83]
	v_mfma_f32_16x16x32_bf16 v[68:71], v[188:191], v[228:231], v[68:71]
	v_mfma_f32_16x16x32_bf16 v[64:67], v[196:199], v[228:231], v[64:67]
	v_mfma_f32_16x16x32_bf16 v[116:119], v[192:195], v[208:211], v[116:119]
	v_mfma_f32_16x16x32_bf16 v[112:115], v[200:203], v[208:211], v[112:115]
	v_mfma_f32_16x16x32_bf16 v[100:103], v[192:195], v[216:219], v[100:103]
	v_mfma_f32_16x16x32_bf16 v[96:99], v[200:203], v[216:219], v[96:99]
	v_mfma_f32_16x16x32_bf16 v[84:87], v[192:195], v[224:227], v[84:87]
	v_mfma_f32_16x16x32_bf16 v[80:83], v[200:203], v[224:227], v[80:83]
	v_mfma_f32_16x16x32_bf16 v[68:71], v[192:195], v[232:235], v[68:71]
	v_mfma_f32_16x16x32_bf16 v[64:67], v[200:203], v[232:235], v[64:67]
	s_barrier
	s_setprio 0
	s_add_i32 s58, s83, s70
	v_lshl_add_u64 v[160:161], s[46:47], 0, v[130:131]
	s_mov_b32 m0, s58
	ds_read_b128 v[204:207], v167 offset:16384
	ds_read_b128 v[208:211], v167 offset:17408
	ds_read_b128 v[212:215], v167 offset:18432
	ds_read_b128 v[216:219], v167 offset:19456
	ds_read_b128 v[220:223], v167 offset:20480
	ds_read_b128 v[224:227], v167 offset:21504
	ds_read_b128 v[228:231], v167 offset:22528
	ds_read_b128 v[232:235], v167 offset:23552
	global_load_lds_dwordx4 v[160:161], off
	s_add_i32 m0, s58, 0x2000
	s_add_u32 s58, s46, 0x40000
	v_lshl_add_u64 v[236:237], s[46:47], 0, v[134:135]
	s_addc_u32 s59, s47, 0
	s_add_i32 s92, s84, s70
	global_load_lds_dwordx4 v[236:237], off
	v_lshl_add_u64 v[238:239], s[58:59], 0, v[130:131]
	s_mov_b32 m0, s92
	v_lshl_add_u64 v[240:241], s[48:49], 0, v[132:133]
	global_load_lds_dwordx4 v[238:239], off
	v_lshl_add_u64 v[238:239], s[58:59], 0, v[134:135]
	s_add_i32 m0, s92, 0x2000
	s_nop 0
	global_load_lds_dwordx4 v[238:239], off
	v_lshl_add_u64 v[238:239], s[48:49], 0, v[128:129]
	s_mov_b32 m0, s71
	s_nop 0
	global_load_lds_dwordx4 v[238:239], off
	s_mov_b32 m0, s72
	s_nop 0
	global_load_lds_dwordx4 v[240:241], off
	s_waitcnt vmcnt(8) lgkmcnt(0)
	s_barrier
; #define PG8_STAGE(bufoff, gbase, voff) do { _Pragma("unroll") for (int _i = 0; _i < 2; ++_i) \
;         __builtin_amdgcn_global_load_lds((const unsigned*)((const char*)(gbase) + (voff)[_i]), (PG8_LAS unsigned*)(lds + (bufoff) + ldsw + _i * 8192), 16, 0, 0); } while (0)
; #define PG8_LDA(dst, b, h) do { _Pragma("unroll") for (int m = 0; m < 4; ++m) _Pragma("unroll") for (int k = 0; k < 2; ++k) dst[m][k] = *(const PG8_LAS bf16x8*)(lds + PG8_SA(b, h) + aoff + m * 2048 + k * 1024); } while (0)
; #define PG8_LDB(dst, b, h) do { _Pragma("unroll") for (int n = 0; n < 2; ++n) _Pragma("unroll") for (int k = 0; k < 2; ++k) dst[n][k] = *(const PG8_LAS bf16x8*)(lds + PG8_SB(b, h) + boff + n * 2048 + k * 1024); } while (0)
; #define PG8_MMA(ai, bj, At, Bt) do { __builtin_amdgcn_s_setprio(1); _Pragma("unroll") for (int m = 0; m < 4; ++m) _Pragma("unroll") for (int n = 0; n < 2; ++n) _Pragma("unroll") for (int k = 0; k < 2; ++k) \
;         acc[ai][bj][m][n] = __builtin_amdgcn_mfma_f32_16x16x32_bf16(Bt[n][k], At[m][k], acc[ai][bj][m][n], 0, 0, 0); __builtin_amdgcn_s_setprio(0); } while (0)
; #define PG8_WAIT_V(n) asm volatile("s_waitcnt vmcnt(" #n ")" ::: "memory")
; #define PG8_WAIT_L(n) asm volatile("s_waitcnt lgkmcnt(" #n ")" ::: "memory")
; #define PG8_BAR __builtin_amdgcn_s_barrier()
; #define PG8_SCHED __builtin_amdgcn_sched_barrier(0)
; template <class Epi, class Sched, bool ALIGN_EPI = false, bool SP2 = false>
; __device__ __forceinline__ void gemm_phase(PG8_LAS unsigned char* lds, const Gemm g, const Sched& S, const Epi& E) {
;     ...
;             PG8_WAIT_V(8); PG8_WAIT_L(0); PG8_BAR; PG8_MMA(1, 0, At, B0); PG8_MMA(1, 1, At, B1); PG8_BAR; PG8_SCHED;
;             PG8_LDB(B0, 1, 0); PG8_LDB(B1, 1, 1); PG8_SCHED; PG8_LDA(At, 1, 0); PG8_STAGE(PG8_SA(0, 1), a2 + hstepA, voffA);
;             PG8_WAIT_V(8); PG8_WAIT_L(0); PG8_BAR; PG8_MMA(0, 0, At, B0); PG8_MMA(0, 1, At, B1); PG8_BAR; PG8_SCHED;
	v_mfma_f32_16x16x32_bf16 v[60:63], v[152:155], v[204:207], v[60:63]
	s_setprio 1
	v_mfma_f32_16x16x32_bf16 v[56:59], v[178:181], v[204:207], v[56:59]
	v_mfma_f32_16x16x32_bf16 v[44:47], v[152:155], v[212:215], v[44:47]
	v_mfma_f32_16x16x32_bf16 v[40:43], v[178:181], v[212:215], v[40:43]
	v_mfma_f32_16x16x32_bf16 v[28:31], v[152:155], v[220:223], v[28:31]
	v_mfma_f32_16x16x32_bf16 v[24:27], v[178:181], v[220:223], v[24:27]
	v_mfma_f32_16x16x32_bf16 v[12:15], v[152:155], v[228:231], v[12:15]
	v_mfma_f32_16x16x32_bf16 v[8:11], v[178:181], v[228:231], v[8:11]
	v_mfma_f32_16x16x32_bf16 v[60:63], v[156:159], v[208:211], v[60:63]
	v_mfma_f32_16x16x32_bf16 v[56:59], v[182:185], v[208:211], v[56:59]
	v_mfma_f32_16x16x32_bf16 v[44:47], v[156:159], v[216:219], v[44:47]
	v_mfma_f32_16x16x32_bf16 v[40:43], v[182:185], v[216:219], v[40:43]
	v_mfma_f32_16x16x32_bf16 v[28:31], v[156:159], v[224:227], v[28:31]
	v_mfma_f32_16x16x32_bf16 v[24:27], v[182:185], v[224:227], v[24:27]
	v_mfma_f32_16x16x32_bf16 v[12:15], v[156:159], v[232:235], v[12:15]
	v_mfma_f32_16x16x32_bf16 v[8:11], v[182:185], v[232:235], v[8:11]
	v_mfma_f32_16x16x32_bf16 v[52:55], v[188:191], v[204:207], v[52:55]
	v_mfma_f32_16x16x32_bf16 v[48:51], v[196:199], v[204:207], v[48:51]
	v_mfma_f32_16x16x32_bf16 v[36:39], v[188:191], v[212:215], v[36:39]
	v_mfma_f32_16x16x32_bf16 v[32:35], v[196:199], v[212:215], v[32:35]
	v_mfma_f32_16x16x32_bf16 v[20:23], v[188:191], v[220:223], v[20:23]
	v_mfma_f32_16x16x32_bf16 v[16:19], v[196:199], v[220:223], v[16:19]
	v_mfma_f32_16x16x32_bf16 v[4:7], v[188:191], v[228:231], v[4:7]
	v_mfma_f32_16x16x32_bf16 v[0:3], v[196:199], v[228:231], v[0:3]
	v_mfma_f32_16x16x32_bf16 v[52:55], v[192:195], v[208:211], v[52:55]
	v_mfma_f32_16x16x32_bf16 v[48:51], v[200:203], v[208:211], v[48:51]
	v_mfma_f32_16x16x32_bf16 v[36:39], v[192:195], v[216:219], v[36:39]
	v_mfma_f32_16x16x32_bf16 v[32:35], v[200:203], v[216:219], v[32:35]
	v_mfma_f32_16x16x32_bf16 v[20:23], v[192:195], v[224:227], v[20:23]
	v_mfma_f32_16x16x32_bf16 v[16:19], v[200:203], v[224:227], v[16:19]
	v_mfma_f32_16x16x32_bf16 v[4:7], v[192:195], v[232:235], v[4:7]
	v_mfma_f32_16x16x32_bf16 v[0:3], v[200:203], v[232:235], v[0:3]
	s_barrier
	s_setprio 0
	s_add_i32 s58, 0, 0x18000
	v_add_u32_e32 v136, s58, v163
	s_add_i32 s59, 0, 0x1c000
	ds_read_b128 v[152:155], v136
	ds_read_b128 v[156:159], v136 offset:1024
	ds_read_b128 v[178:181], v136 offset:2048
	ds_read_b128 v[182:185], v136 offset:3072
	v_add_u32_e32 v136, s59, v163
	ds_read_b128 v[188:191], v136
	ds_read_b128 v[192:195], v136 offset:1024
	ds_read_b128 v[196:199], v136 offset:2048
	ds_read_b128 v[200:203], v136 offset:3072
	s_add_u32 s48, s48, 0x40000
	s_addc_u32 s49, s49, 0
	s_mov_b32 m0, s73
	v_lshl_add_u64 v[242:243], s[48:49], 0, v[128:129]
	ds_read_b128 v[204:207], v167 offset:32768
	ds_read_b128 v[208:211], v167 offset:33792
	ds_read_b128 v[212:215], v167 offset:34816
	ds_read_b128 v[216:219], v167 offset:35840
	ds_read_b128 v[220:223], v167 offset:36864
	ds_read_b128 v[224:227], v167 offset:37888
	ds_read_b128 v[228:231], v167 offset:38912
	ds_read_b128 v[232:235], v167 offset:39936
	global_load_lds_dwordx4 v[242:243], off
	v_lshl_add_u64 v[242:243], s[48:49], 0, v[132:133]
	s_mov_b32 m0, s74
	s_nop 0
	global_load_lds_dwordx4 v[242:243], off
	s_waitcnt vmcnt(8) lgkmcnt(0)
	s_barrier
	v_mfma_f32_16x16x32_bf16 v[124:127], v[152:155], v[204:207], v[124:127]
	s_setprio 1
	v_mfma_f32_16x16x32_bf16 v[120:123], v[178:181], v[204:207], v[120:123]
	v_mfma_f32_16x16x32_bf16 v[108:111], v[152:155], v[212:215], v[108:111]
	v_mfma_f32_16x16x32_bf16 v[104:107], v[178:181], v[212:215], v[104:107]
	v_mfma_f32_16x16x32_bf16 v[92:95], v[152:155], v[220:223], v[92:95]
	v_mfma_f32_16x16x32_bf16 v[88:91], v[178:181], v[220:223], v[88:91]
	v_mfma_f32_16x16x32_bf16 v[76:79], v[152:155], v[228:231], v[76:79]
	v_mfma_f32_16x16x32_bf16 v[72:75], v[178:181], v[228:231], v[72:75]
	v_mfma_f32_16x16x32_bf16 v[124:127], v[156:159], v[208:211], v[124:127]
	v_mfma_f32_16x16x32_bf16 v[120:123], v[182:185], v[208:211], v[120:123]
	v_mfma_f32_16x16x32_bf16 v[108:111], v[156:159], v[216:219], v[108:111]
	v_mfma_f32_16x16x32_bf16 v[104:107], v[182:185], v[216:219], v[104:107]
	v_mfma_f32_16x16x32_bf16 v[92:95], v[156:159], v[224:227], v[92:95]
	v_mfma_f32_16x16x32_bf16 v[88:91], v[182:185], v[224:227], v[88:91]
	v_mfma_f32_16x16x32_bf16 v[76:79], v[156:159], v[232:235], v[76:79]
	v_mfma_f32_16x16x32_bf16 v[72:75], v[182:185], v[232:235], v[72:75]
	v_mfma_f32_16x16x32_bf16 v[116:119], v[188:191], v[204:207], v[116:119]
	v_mfma_f32_16x16x32_bf16 v[112:115], v[196:199], v[204:207], v[112:115]
	v_mfma_f32_16x16x32_bf16 v[100:103], v[188:191], v[212:215], v[100:103]
	v_mfma_f32_16x16x32_bf16 v[96:99], v[196:199], v[212:215], v[96:99]
	v_mfma_f32_16x16x32_bf16 v[84:87], v[188:191], v[220:223], v[84:87]
	v_mfma_f32_16x16x32_bf16 v[80:83], v[196:199], v[220:223], v[80:83]
	v_mfma_f32_16x16x32_bf16 v[68:71], v[188:191], v[228:231], v[68:71]
	v_mfma_f32_16x16x32_bf16 v[64:67], v[196:199], v[228:231], v[64:67]
	v_mfma_f32_16x16x32_bf16 v[116:119], v[192:195], v[208:211], v[116:119]
	v_mfma_f32_16x16x32_bf16 v[112:115], v[200:203], v[208:211], v[112:115]
	v_mfma_f32_16x16x32_bf16 v[100:103], v[192:195], v[216:219], v[100:103]
	v_mfma_f32_16x16x32_bf16 v[96:99], v[200:203], v[216:219], v[96:99]
	v_mfma_f32_16x16x32_bf16 v[84:87], v[192:195], v[224:227], v[84:87]
	v_mfma_f32_16x16x32_bf16 v[80:83], v[200:203], v[224:227], v[80:83]
	v_mfma_f32_16x16x32_bf16 v[68:71], v[192:195], v[232:235], v[68:71]
	v_mfma_f32_16x16x32_bf16 v[64:67], v[200:203], v[232:235], v[64:67]
	s_barrier
; #define PG8_STAGE(bufoff, gbase, voff) do { _Pragma("unroll") for (int _i = 0; _i < 2; ++_i) \
;         __builtin_amdgcn_global_load_lds((const unsigned*)((const char*)(gbase) + (voff)[_i]), (PG8_LAS unsigned*)(lds + (bufoff) + ldsw + _i * 8192), 16, 0, 0); } while (0)
; #define PG8_LDA(dst, b, h) do { _Pragma("unroll") for (int m = 0; m < 4; ++m) _Pragma("unroll") for (int k = 0; k < 2; ++k) dst[m][k] = *(const PG8_LAS bf16x8*)(lds + PG8_SA(b, h) + aoff + m * 2048 + k * 1024); } while (0)
; #define PG8_MMA(ai, bj, At, Bt) do { __builtin_amdgcn_s_setprio(1); _Pragma("unroll") for (int m = 0; m < 4; ++m) _Pragma("unroll") for (int n = 0; n < 2; ++n) _Pragma("unroll") for (int k = 0; k < 2; ++k) \
;         acc[ai][bj][m][n] = __builtin_amdgcn_mfma_f32_16x16x32_bf16(Bt[n][k], At[m][k], acc[ai][bj][m][n], 0, 0, 0); __builtin_amdgcn_s_setprio(0); } while (0)
; #define PG8_WAIT_V(n) asm volatile("s_waitcnt vmcnt(" #n ")" ::: "memory")
; #define PG8_WAIT_L(n) asm volatile("s_waitcnt lgkmcnt(" #n ")" ::: "memory")
; #define PG8_BAR __builtin_amdgcn_s_barrier()
; #define PG8_SCHED __builtin_amdgcn_sched_barrier(0)
; template <class Epi, class Sched, bool ALIGN_EPI = false, bool SP2 = false>
; __device__ __forceinline__ void gemm_phase(PG8_LAS unsigned char* lds, const Gemm g, const Sched& S, const Epi& E) {
;     ...
;             PG8_LDA(At, 1, 1); PG8_STAGE(PG8_SB(1, 0), b3, voffB); PG8_STAGE(PG8_SB(1, 1), b3 + hstepB, voffB); PG8_STAGE(PG8_SA(1, 0), a3, voffA);
;             PG8_WAIT_V(8); PG8_WAIT_L(0); PG8_BAR; PG8_MMA(1, 0, At, B0); PG8_MMA(1, 1, At, B1); PG8_BAR; PG8_SCHED;
	s_setprio 0
	s_add_i32 s48, s58, s70
	v_lshl_add_u64 v[160:161], v[160:161], 0, s[30:31]
	s_mov_b32 m0, s48
	ds_read_b128 v[204:207], v167 offset:49152
	ds_read_b128 v[208:211], v167 offset:50176
	ds_read_b128 v[212:215], v167 offset:51200
	ds_read_b128 v[216:219], v167 offset:52224
	ds_read_b128 v[220:223], v167 offset:53248
	ds_read_b128 v[224:227], v167 offset:54272
	ds_read_b128 v[228:231], v167 offset:55296
	ds_read_b128 v[232:235], v167 offset:56320
	global_load_lds_dwordx4 v[160:161], off
	s_add_i32 m0, s48, 0x2000
	s_add_u32 s46, s46, 0x40080
	v_lshl_add_u64 v[160:161], v[236:237], 0, s[30:31]
	s_addc_u32 s47, s47, 0
	s_add_i32 s48, s59, s70
	global_load_lds_dwordx4 v[160:161], off
	v_lshl_add_u64 v[160:161], s[46:47], 0, v[130:131]
	s_mov_b32 m0, s48
	s_nop 0
	global_load_lds_dwordx4 v[160:161], off
	v_lshl_add_u64 v[160:161], s[46:47], 0, v[134:135]
	s_add_i32 m0, s48, 0x2000
	s_nop 0
	global_load_lds_dwordx4 v[160:161], off
	v_lshl_add_u64 v[160:161], v[238:239], 0, s[30:31]
	s_mov_b32 m0, s76
	s_nop 0
	global_load_lds_dwordx4 v[160:161], off
	v_lshl_add_u64 v[160:161], v[240:241], 0, s[30:31]
	s_mov_b32 m0, s77
	s_nop 0
	global_load_lds_dwordx4 v[160:161], off
	s_waitcnt vmcnt(8) lgkmcnt(0)
	s_barrier
	v_mfma_f32_16x16x32_bf16 v[60:63], v[152:155], v[204:207], v[60:63]
	s_setprio 1
	v_mfma_f32_16x16x32_bf16 v[56:59], v[178:181], v[204:207], v[56:59]
	v_mfma_f32_16x16x32_bf16 v[44:47], v[152:155], v[212:215], v[44:47]
	v_mfma_f32_16x16x32_bf16 v[40:43], v[178:181], v[212:215], v[40:43]
	v_mfma_f32_16x16x32_bf16 v[28:31], v[152:155], v[220:223], v[28:31]
	v_mfma_f32_16x16x32_bf16 v[24:27], v[178:181], v[220:223], v[24:27]
	v_mfma_f32_16x16x32_bf16 v[12:15], v[152:155], v[228:231], v[12:15]
	v_mfma_f32_16x16x32_bf16 v[8:11], v[178:181], v[228:231], v[8:11]
	v_mfma_f32_16x16x32_bf16 v[60:63], v[156:159], v[208:211], v[60:63]
	v_mfma_f32_16x16x32_bf16 v[56:59], v[182:185], v[208:211], v[56:59]
	v_mfma_f32_16x16x32_bf16 v[44:47], v[156:159], v[216:219], v[44:47]
	v_mfma_f32_16x16x32_bf16 v[40:43], v[182:185], v[216:219], v[40:43]
	v_mfma_f32_16x16x32_bf16 v[28:31], v[156:159], v[224:227], v[28:31]
	v_mfma_f32_16x16x32_bf16 v[24:27], v[182:185], v[224:227], v[24:27]
	v_mfma_f32_16x16x32_bf16 v[12:15], v[156:159], v[232:235], v[12:15]
	v_mfma_f32_16x16x32_bf16 v[8:11], v[182:185], v[232:235], v[8:11]
	v_mfma_f32_16x16x32_bf16 v[52:55], v[188:191], v[204:207], v[52:55]
	v_mfma_f32_16x16x32_bf16 v[48:51], v[196:199], v[204:207], v[48:51]
	v_mfma_f32_16x16x32_bf16 v[36:39], v[188:191], v[212:215], v[36:39]
	v_mfma_f32_16x16x32_bf16 v[32:35], v[196:199], v[212:215], v[32:35]
	v_mfma_f32_16x16x32_bf16 v[20:23], v[188:191], v[220:223], v[20:23]
	v_mfma_f32_16x16x32_bf16 v[16:19], v[196:199], v[220:223], v[16:19]
	v_mfma_f32_16x16x32_bf16 v[4:7], v[188:191], v[228:231], v[4:7]
	v_mfma_f32_16x16x32_bf16 v[0:3], v[196:199], v[228:231], v[0:3]
	v_mfma_f32_16x16x32_bf16 v[52:55], v[192:195], v[208:211], v[52:55]
	v_mfma_f32_16x16x32_bf16 v[48:51], v[200:203], v[208:211], v[48:51]
	v_mfma_f32_16x16x32_bf16 v[36:39], v[192:195], v[216:219], v[36:39]
	v_mfma_f32_16x16x32_bf16 v[32:35], v[200:203], v[216:219], v[32:35]
	v_mfma_f32_16x16x32_bf16 v[20:23], v[192:195], v[224:227], v[20:23]
	v_mfma_f32_16x16x32_bf16 v[16:19], v[200:203], v[224:227], v[16:19]
	v_mfma_f32_16x16x32_bf16 v[4:7], v[192:195], v[232:235], v[4:7]
	v_mfma_f32_16x16x32_bf16 v[0:3], v[200:203], v[232:235], v[0:3]
	s_barrier
	s_setprio 0
	s_add_i32 s91, s91, 2
	s_add_u32 s14, s14, 0x100
	s_addc_u32 s15, s15, 0
	s_add_u32 s66, s66, 0x100
	s_addc_u32 s67, s67, 0
	s_cmp_gt_u32 s91, 13
	s_cbranch_scc0 .LBB0_404
	s_and_b64 vcc, exec, s[34:35]
	s_cbranch_vccz .LBB0_407
	s_barrier

; #define PG8_STAGE(bufoff, gbase, voff) do { _Pragma("unroll") for (int _i = 0; _i < 2; ++_i) \
;         __builtin_amdgcn_global_load_lds((const unsigned*)((const char*)(gbase) + (voff)[_i]), (PG8_LAS unsigned*)(lds + (bufoff) + ldsw + _i * 8192), 16, 0, 0); } while (0)
; #define PG8_LDA(dst, b, h) do { _Pragma("unroll") for (int m = 0; m < 4; ++m) _Pragma("unroll") for (int k = 0; k < 2; ++k) dst[m][k] = *(const PG8_LAS bf16x8*)(lds + PG8_SA(b, h) + aoff + m * 2048 + k * 1024); } while (0)
; #define PG8_LDB(dst, b, h) do { _Pragma("unroll") for (int n = 0; n < 2; ++n) _Pragma("unroll") for (int k = 0; k < 2; ++k) dst[n][k] = *(const PG8_LAS bf16x8*)(lds + PG8_SB(b, h) + boff + n * 2048 + k * 1024); } while (0)
; #define PG8_MMA(ai, bj, At, Bt) do { __builtin_amdgcn_s_setprio(1); _Pragma("unroll") for (int m = 0; m < 4; ++m) _Pragma("unroll") for (int n = 0; n < 2; ++n) _Pragma("unroll") for (int k = 0; k < 2; ++k) \
;         acc[ai][bj][m][n] = __builtin_amdgcn_mfma_f32_16x16x32_bf16(Bt[n][k], At[m][k], acc[ai][bj][m][n], 0, 0, 0); __builtin_amdgcn_s_setprio(0); } while (0)
; #define PG8_WAIT_V(n) asm volatile("s_waitcnt vmcnt(" #n ")" ::: "memory")
; #define PG8_BAR __builtin_amdgcn_s_barrier()
; template <class Epi, class Sched, bool ALIGN_EPI = false, bool SP2 = false>
; __device__ __forceinline__ void gemm_phase(PG8_LAS unsigned char* lds, const Gemm g, const Sched& S, const Epi& E) {
;     ...
;         for (int t = 0; t < nt; t += 2) {
;             const bool last = (t == nt - 2);
;             const char* a1 = cA + (size_t)(t + 1) * kstep;
;             const char* a2 = last ? nA : cA + (size_t)(t + 2) * kstep; const char* b2 = last ? nB : cB + (size_t)(t + 2) * kstep;
;             const char* a3 = a2 + kstep; const char* b3 = b2 + kstep;
;             if (last && has_next) S.a_ready(nxt);
;             if constexpr (SP2) {
;             PG8_LDB(B0, 0, 0); PG8_LDB(B1, 0, 1); PG8_SCHED; PG8_LDA(At, 0, 0); PG8_STAGE(PG8_SA(1, 1), a1 + hstepA, voffA);
;             PG8_WAIT_V(8); PG8_WAIT_L(0); PG8_BAR; PG8_MMA(0, 0, At, B0); PG8_MMA(0, 1, At, B1); PG8_BAR; PG8_SCHED;
;             PG8_LDA(At, 0, 1); PG8_STAGE(PG8_SB(0, 0), b2, voffB); PG8_STAGE(PG8_SB(0, 1), b2 + hstepB, voffB); PG8_STAGE(PG8_SA(0, 0), a2, voffA);
;             PG8_WAIT_V(8); PG8_WAIT_L(0); PG8_BAR; PG8_MMA(1, 0, At, B0); PG8_MMA(1, 1, At, B1); PG8_BAR; PG8_SCHED;
.LBB0_524:
	ds_read_b128 v[144:147], v153
	ds_read_b128 v[158:161], v153 offset:1024
	ds_read_b128 v[162:165], v153 offset:2048
	ds_read_b128 v[166:169], v153 offset:3072
	ds_read_b128 v[170:173], v154
	ds_read_b128 v[174:177], v154 offset:1024
	ds_read_b128 v[178:181], v154 offset:2048
	ds_read_b128 v[182:185], v154 offset:3072
	s_add_u32 s30, s28, 0x100
	s_addc_u32 s31, s29, 0
	s_cmp_eq_u32 s76, 2
	s_cselect_b32 s37, s9, s31
	s_cselect_b32 s36, s8, s30
	s_cselect_b32 s35, s25, s75
	s_cselect_b32 s34, s24, s74
	v_lshl_add_u64 v[148:149], s[28:29], 0, v[136:137]
	s_add_i32 m0, s42, 0xc000
	ds_read_b128 v[188:191], v155
	ds_read_b128 v[192:195], v155 offset:1024
	ds_read_b128 v[196:199], v155 offset:2048
	ds_read_b128 v[200:203], v155 offset:3072
	ds_read_b128 v[204:207], v155 offset:4096
	ds_read_b128 v[208:211], v155 offset:5120
	ds_read_b128 v[212:215], v155 offset:6144
	ds_read_b128 v[216:219], v155 offset:7168
	global_load_lds_dwordx4 v[148:149], off
	v_lshl_add_u64 v[148:149], s[28:29], 0, v[138:139]
	s_add_i32 m0, s42, 0xe000
	s_nop 0
	global_load_lds_dwordx4 v[148:149], off
	s_waitcnt vmcnt(8) lgkmcnt(0)
	s_barrier
	v_mfma_f32_16x16x32_bf16 v[124:127], v[144:147], v[188:191], v[124:127]
	s_setprio 1
	v_mfma_f32_16x16x32_bf16 v[120:123], v[162:165], v[188:191], v[120:123]
	v_mfma_f32_16x16x32_bf16 v[108:111], v[144:147], v[196:199], v[108:111]
	v_mfma_f32_16x16x32_bf16 v[104:107], v[162:165], v[196:199], v[104:107]
	v_mfma_f32_16x16x32_bf16 v[92:95], v[144:147], v[204:207], v[92:95]
	v_mfma_f32_16x16x32_bf16 v[88:91], v[162:165], v[204:207], v[88:91]
	v_mfma_f32_16x16x32_bf16 v[76:79], v[144:147], v[212:215], v[76:79]
	v_mfma_f32_16x16x32_bf16 v[72:75], v[162:165], v[212:215], v[72:75]
	v_mfma_f32_16x16x32_bf16 v[124:127], v[158:161], v[192:195], v[124:127]
	v_mfma_f32_16x16x32_bf16 v[120:123], v[166:169], v[192:195], v[120:123]
	v_mfma_f32_16x16x32_bf16 v[108:111], v[158:161], v[200:203], v[108:111]
	v_mfma_f32_16x16x32_bf16 v[104:107], v[166:169], v[200:203], v[104:107]
	v_mfma_f32_16x16x32_bf16 v[92:95], v[158:161], v[208:211], v[92:95]
	v_mfma_f32_16x16x32_bf16 v[88:91], v[166:169], v[208:211], v[88:91]
	v_mfma_f32_16x16x32_bf16 v[76:79], v[158:161], v[216:219], v[76:79]
	v_mfma_f32_16x16x32_bf16 v[72:75], v[166:169], v[216:219], v[72:75]
	v_mfma_f32_16x16x32_bf16 v[116:119], v[170:173], v[188:191], v[116:119]
	v_mfma_f32_16x16x32_bf16 v[112:115], v[178:181], v[188:191], v[112:115]
	v_mfma_f32_16x16x32_bf16 v[100:103], v[170:173], v[196:199], v[100:103]
	v_mfma_f32_16x16x32_bf16 v[96:99], v[178:181], v[196:199], v[96:99]
	v_mfma_f32_16x16x32_bf16 v[84:87], v[170:173], v[204:207], v[84:87]
	v_mfma_f32_16x16x32_bf16 v[80:83], v[178:181], v[204:207], v[80:83]
	v_mfma_f32_16x16x32_bf16 v[68:71], v[170:173], v[212:215], v[68:71]
	v_mfma_f32_16x16x32_bf16 v[64:67], v[178:181], v[212:215], v[64:67]
	v_mfma_f32_16x16x32_bf16 v[116:119], v[174:177], v[192:195], v[116:119]
	v_mfma_f32_16x16x32_bf16 v[112:115], v[182:185], v[192:195], v[112:115]
	v_mfma_f32_16x16x32_bf16 v[100:103], v[174:177], v[200:203], v[100:103]
	v_mfma_f32_16x16x32_bf16 v[96:99], v[182:185], v[200:203], v[96:99]
	v_mfma_f32_16x16x32_bf16 v[84:87], v[174:177], v[208:211], v[84:87]
	v_mfma_f32_16x16x32_bf16 v[80:83], v[182:185], v[208:211], v[80:83]
	v_mfma_f32_16x16x32_bf16 v[68:71], v[174:177], v[216:219], v[68:71]
	v_mfma_f32_16x16x32_bf16 v[64:67], v[182:185], v[216:219], v[64:67]
	s_barrier
	s_setprio 0
	s_add_i32 s28, s66, s40
	v_lshl_add_u64 v[148:149], s[34:35], 0, v[132:133]
	s_mov_b32 m0, s28
	ds_read_b128 v[188:191], v155 offset:16384
	ds_read_b128 v[192:195], v155 offset:17408
	ds_read_b128 v[196:199], v155 offset:18432
	ds_read_b128 v[200:203], v155 offset:19456
	ds_read_b128 v[204:207], v155 offset:20480
	ds_read_b128 v[208:211], v155 offset:21504
	ds_read_b128 v[212:215], v155 offset:22528
	ds_read_b128 v[216:219], v155 offset:23552
	global_load_lds_dwordx4 v[148:149], off
	s_add_i32 m0, s28, 0x2000
	s_add_u32 s28, s34, 0x18000
	v_lshl_add_u64 v[220:221], s[34:35], 0, v[128:129]
	s_addc_u32 s29, s35, 0
	s_add_i32 s58, s67, s40
	global_load_lds_dwordx4 v[220:221], off
	v_lshl_add_u64 v[222:223], s[28:29], 0, v[132:133]
	s_mov_b32 m0, s58
	v_lshl_add_u64 v[224:225], s[36:37], 0, v[130:131]
	global_load_lds_dwordx4 v[222:223], off
	v_lshl_add_u64 v[222:223], s[28:29], 0, v[128:129]
	s_add_i32 m0, s58, 0x2000
	s_nop 0
	global_load_lds_dwordx4 v[222:223], off
	v_lshl_add_u64 v[222:223], s[36:37], 0, v[134:135]
	s_mov_b32 m0, s42
	s_nop 0
	global_load_lds_dwordx4 v[222:223], off
	s_mov_b32 m0, s43
	s_nop 0
	global_load_lds_dwordx4 v[224:225], off
	s_waitcnt vmcnt(8) lgkmcnt(0)
	s_barrier
; #define PG8_STAGE(bufoff, gbase, voff) do { _Pragma("unroll") for (int _i = 0; _i < 2; ++_i) \
;         __builtin_amdgcn_global_load_lds((const unsigned*)((const char*)(gbase) + (voff)[_i]), (PG8_LAS unsigned*)(lds + (bufoff) + ldsw + _i * 8192), 16, 0, 0); } while (0)
; #define PG8_LDA(dst, b, h) do { _Pragma("unroll") for (int m = 0; m < 4; ++m) _Pragma("unroll") for (int k = 0; k < 2; ++k) dst[m][k] = *(const PG8_LAS bf16x8*)(lds + PG8_SA(b, h) + aoff + m * 2048 + k * 1024); } while (0)
; #define PG8_LDB(dst, b, h) do { _Pragma("unroll") for (int n = 0; n < 2; ++n) _Pragma("unroll") for (int k = 0; k < 2; ++k) dst[n][k] = *(const PG8_LAS bf16x8*)(lds + PG8_SB(b, h) + boff + n * 2048 + k * 1024); } while (0)
; #define PG8_MMA(ai, bj, At, Bt) do { __builtin_amdgcn_s_setprio(1); _Pragma("unroll") for (int m = 0; m < 4; ++m) _Pragma("unroll") for (int n = 0; n < 2; ++n) _Pragma("unroll") for (int k = 0; k < 2; ++k) \
;         acc[ai][bj][m][n] = __builtin_amdgcn_mfma_f32_16x16x32_bf16(Bt[n][k], At[m][k], acc[ai][bj][m][n], 0, 0, 0); __builtin_amdgcn_s_setprio(0); } while (0)
; #define PG8_WAIT_V(n) asm volatile("s_waitcnt vmcnt(" #n ")" ::: "memory")
; #define PG8_WAIT_L(n) asm volatile("s_waitcnt lgkmcnt(" #n ")" ::: "memory")
; #define PG8_BAR __builtin_amdgcn_s_barrier()
; #define PG8_SCHED __builtin_amdgcn_sched_barrier(0)
; template <class Epi, class Sched, bool ALIGN_EPI = false, bool SP2 = false>
; __device__ __forceinline__ void gemm_phase(PG8_LAS unsigned char* lds, const Gemm g, const Sched& S, const Epi& E) {
;     ...
;             PG8_WAIT_V(8); PG8_WAIT_L(0); PG8_BAR; PG8_MMA(1, 0, At, B0); PG8_MMA(1, 1, At, B1); PG8_BAR; PG8_SCHED;
;             PG8_LDB(B0, 1, 0); PG8_LDB(B1, 1, 1); PG8_SCHED; PG8_LDA(At, 1, 0); PG8_STAGE(PG8_SA(0, 1), a2 + hstepA, voffA);
;             PG8_WAIT_V(8); PG8_WAIT_L(0); PG8_BAR; PG8_MMA(0, 0, At, B0); PG8_MMA(0, 1, At, B1); PG8_BAR; PG8_SCHED;
	v_mfma_f32_16x16x32_bf16 v[60:63], v[144:147], v[188:191], v[60:63]
	s_setprio 1
	v_mfma_f32_16x16x32_bf16 v[56:59], v[162:165], v[188:191], v[56:59]
	v_mfma_f32_16x16x32_bf16 v[44:47], v[144:147], v[196:199], v[44:47]
	v_mfma_f32_16x16x32_bf16 v[40:43], v[162:165], v[196:199], v[40:43]
	v_mfma_f32_16x16x32_bf16 v[28:31], v[144:147], v[204:207], v[28:31]
	v_mfma_f32_16x16x32_bf16 v[24:27], v[162:165], v[204:207], v[24:27]
	v_mfma_f32_16x16x32_bf16 v[12:15], v[144:147], v[212:215], v[12:15]
	v_mfma_f32_16x16x32_bf16 v[8:11], v[162:165], v[212:215], v[8:11]
	v_mfma_f32_16x16x32_bf16 v[60:63], v[158:161], v[192:195], v[60:63]
	v_mfma_f32_16x16x32_bf16 v[56:59], v[166:169], v[192:195], v[56:59]
	v_mfma_f32_16x16x32_bf16 v[44:47], v[158:161], v[200:203], v[44:47]
	v_mfma_f32_16x16x32_bf16 v[40:43], v[166:169], v[200:203], v[40:43]
	v_mfma_f32_16x16x32_bf16 v[28:31], v[158:161], v[208:211], v[28:31]
	v_mfma_f32_16x16x32_bf16 v[24:27], v[166:169], v[208:211], v[24:27]
	v_mfma_f32_16x16x32_bf16 v[12:15], v[158:161], v[216:219], v[12:15]
	v_mfma_f32_16x16x32_bf16 v[8:11], v[166:169], v[216:219], v[8:11]
	v_mfma_f32_16x16x32_bf16 v[52:55], v[170:173], v[188:191], v[52:55]
	v_mfma_f32_16x16x32_bf16 v[48:51], v[178:181], v[188:191], v[48:51]
	v_mfma_f32_16x16x32_bf16 v[36:39], v[170:173], v[196:199], v[36:39]
	v_mfma_f32_16x16x32_bf16 v[32:35], v[178:181], v[196:199], v[32:35]
	v_mfma_f32_16x16x32_bf16 v[20:23], v[170:173], v[204:207], v[20:23]
	v_mfma_f32_16x16x32_bf16 v[16:19], v[178:181], v[204:207], v[16:19]
	v_mfma_f32_16x16x32_bf16 v[4:7], v[170:173], v[212:215], v[4:7]
	v_mfma_f32_16x16x32_bf16 v[0:3], v[178:181], v[212:215], v[0:3]
	v_mfma_f32_16x16x32_bf16 v[52:55], v[174:177], v[192:195], v[52:55]
	v_mfma_f32_16x16x32_bf16 v[48:51], v[182:185], v[192:195], v[48:51]
	v_mfma_f32_16x16x32_bf16 v[36:39], v[174:177], v[200:203], v[36:39]
	v_mfma_f32_16x16x32_bf16 v[32:35], v[182:185], v[200:203], v[32:35]
	v_mfma_f32_16x16x32_bf16 v[20:23], v[174:177], v[208:211], v[20:23]
	v_mfma_f32_16x16x32_bf16 v[16:19], v[182:185], v[208:211], v[16:19]
	v_mfma_f32_16x16x32_bf16 v[4:7], v[174:177], v[216:219], v[4:7]
	v_mfma_f32_16x16x32_bf16 v[0:3], v[182:185], v[216:219], v[0:3]
	s_barrier
	s_setprio 0
	s_add_i32 s58, 0, 0x18000
	v_add_u32_e32 v157, s58, v151
	s_add_i32 s59, 0, 0x1c000
	ds_read_b128 v[144:147], v157
	ds_read_b128 v[158:161], v157 offset:1024
	ds_read_b128 v[162:165], v157 offset:2048
	ds_read_b128 v[166:169], v157 offset:3072
	v_add_u32_e32 v157, s59, v151
	ds_read_b128 v[170:173], v157
	ds_read_b128 v[174:177], v157 offset:1024
	ds_read_b128 v[178:181], v157 offset:2048
	ds_read_b128 v[182:185], v157 offset:3072
	s_add_u32 s28, s36, 0x30000
	s_addc_u32 s29, s37, 0
	s_mov_b32 m0, s44
	v_lshl_add_u64 v[226:227], s[28:29], 0, v[134:135]
	ds_read_b128 v[188:191], v155 offset:32768
	ds_read_b128 v[192:195], v155 offset:33792
	ds_read_b128 v[196:199], v155 offset:34816
	ds_read_b128 v[200:203], v155 offset:35840
	ds_read_b128 v[204:207], v155 offset:36864
	ds_read_b128 v[208:211], v155 offset:37888
	ds_read_b128 v[212:215], v155 offset:38912
	ds_read_b128 v[216:219], v155 offset:39936
	global_load_lds_dwordx4 v[226:227], off
	v_lshl_add_u64 v[226:227], s[28:29], 0, v[130:131]
	s_mov_b32 m0, s45
	s_nop 0
	global_load_lds_dwordx4 v[226:227], off
	s_waitcnt vmcnt(8) lgkmcnt(0)
	s_barrier
	v_mfma_f32_16x16x32_bf16 v[124:127], v[144:147], v[188:191], v[124:127]
	s_setprio 1
	v_mfma_f32_16x16x32_bf16 v[120:123], v[162:165], v[188:191], v[120:123]
	v_mfma_f32_16x16x32_bf16 v[108:111], v[144:147], v[196:199], v[108:111]
	v_mfma_f32_16x16x32_bf16 v[104:107], v[162:165], v[196:199], v[104:107]
	v_mfma_f32_16x16x32_bf16 v[92:95], v[144:147], v[204:207], v[92:95]
	v_mfma_f32_16x16x32_bf16 v[88:91], v[162:165], v[204:207], v[88:91]
	v_mfma_f32_16x16x32_bf16 v[76:79], v[144:147], v[212:215], v[76:79]
	v_mfma_f32_16x16x32_bf16 v[72:75], v[162:165], v[212:215], v[72:75]
	v_mfma_f32_16x16x32_bf16 v[124:127], v[158:161], v[192:195], v[124:127]
	v_mfma_f32_16x16x32_bf16 v[120:123], v[166:169], v[192:195], v[120:123]
	v_mfma_f32_16x16x32_bf16 v[108:111], v[158:161], v[200:203], v[108:111]
	v_mfma_f32_16x16x32_bf16 v[104:107], v[166:169], v[200:203], v[104:107]
	v_mfma_f32_16x16x32_bf16 v[92:95], v[158:161], v[208:211], v[92:95]
	v_mfma_f32_16x16x32_bf16 v[88:91], v[166:169], v[208:211], v[88:91]
	v_mfma_f32_16x16x32_bf16 v[76:79], v[158:161], v[216:219], v[76:79]
	v_mfma_f32_16x16x32_bf16 v[72:75], v[166:169], v[216:219], v[72:75]
	v_mfma_f32_16x16x32_bf16 v[116:119], v[170:173], v[188:191], v[116:119]
	v_mfma_f32_16x16x32_bf16 v[112:115], v[178:181], v[188:191], v[112:115]
	v_mfma_f32_16x16x32_bf16 v[100:103], v[170:173], v[196:199], v[100:103]
	v_mfma_f32_16x16x32_bf16 v[96:99], v[178:181], v[196:199], v[96:99]
	v_mfma_f32_16x16x32_bf16 v[84:87], v[170:173], v[204:207], v[84:87]
	v_mfma_f32_16x16x32_bf16 v[80:83], v[178:181], v[204:207], v[80:83]
	v_mfma_f32_16x16x32_bf16 v[68:71], v[170:173], v[212:215], v[68:71]
	v_mfma_f32_16x16x32_bf16 v[64:67], v[178:181], v[212:215], v[64:67]
	v_mfma_f32_16x16x32_bf16 v[116:119], v[174:177], v[192:195], v[116:119]
	v_mfma_f32_16x16x32_bf16 v[112:115], v[182:185], v[192:195], v[112:115]
	v_mfma_f32_16x16x32_bf16 v[100:103], v[174:177], v[200:203], v[100:103]
	v_mfma_f32_16x16x32_bf16 v[96:99], v[182:185], v[200:203], v[96:99]
	v_mfma_f32_16x16x32_bf16 v[84:87], v[174:177], v[208:211], v[84:87]
	v_mfma_f32_16x16x32_bf16 v[80:83], v[182:185], v[208:211], v[80:83]
	v_mfma_f32_16x16x32_bf16 v[68:71], v[174:177], v[216:219], v[68:71]
	v_mfma_f32_16x16x32_bf16 v[64:67], v[182:185], v[216:219], v[64:67]
	s_barrier
; #define PG8_STAGE(bufoff, gbase, voff) do { _Pragma("unroll") for (int _i = 0; _i < 2; ++_i) \
;         __builtin_amdgcn_global_load_lds((const unsigned*)((const char*)(gbase) + (voff)[_i]), (PG8_LAS unsigned*)(lds + (bufoff) + ldsw + _i * 8192), 16, 0, 0); } while (0)
; #define PG8_LDA(dst, b, h) do { _Pragma("unroll") for (int m = 0; m < 4; ++m) _Pragma("unroll") for (int k = 0; k < 2; ++k) dst[m][k] = *(const PG8_LAS bf16x8*)(lds + PG8_SA(b, h) + aoff + m * 2048 + k * 1024); } while (0)
; #define PG8_MMA(ai, bj, At, Bt) do { __builtin_amdgcn_s_setprio(1); _Pragma("unroll") for (int m = 0; m < 4; ++m) _Pragma("unroll") for (int n = 0; n < 2; ++n) _Pragma("unroll") for (int k = 0; k < 2; ++k) \
;         acc[ai][bj][m][n] = __builtin_amdgcn_mfma_f32_16x16x32_bf16(Bt[n][k], At[m][k], acc[ai][bj][m][n], 0, 0, 0); __builtin_amdgcn_s_setprio(0); } while (0)
; #define PG8_WAIT_V(n) asm volatile("s_waitcnt vmcnt(" #n ")" ::: "memory")
; #define PG8_WAIT_L(n) asm volatile("s_waitcnt lgkmcnt(" #n ")" ::: "memory")
; #define PG8_BAR __builtin_amdgcn_s_barrier()
; #define PG8_SCHED __builtin_amdgcn_sched_barrier(0)
; template <class Epi, class Sched, bool ALIGN_EPI = false, bool SP2 = false>
; __device__ __forceinline__ void gemm_phase(PG8_LAS unsigned char* lds, const Gemm g, const Sched& S, const Epi& E) {
;     ...
;             PG8_LDA(At, 1, 1); PG8_STAGE(PG8_SB(1, 0), b3, voffB); PG8_STAGE(PG8_SB(1, 1), b3 + hstepB, voffB); PG8_STAGE(PG8_SA(1, 0), a3, voffA);
;             PG8_WAIT_V(8); PG8_WAIT_L(0); PG8_BAR; PG8_MMA(1, 0, At, B0); PG8_MMA(1, 1, At, B1); PG8_BAR; PG8_SCHED;
	s_setprio 0
	s_add_i32 s28, s58, s40
	v_lshl_add_u64 v[148:149], v[148:149], 0, s[12:13]
	s_mov_b32 m0, s28
	ds_read_b128 v[188:191], v155 offset:49152
	ds_read_b128 v[192:195], v155 offset:50176
	ds_read_b128 v[196:199], v155 offset:51200
	ds_read_b128 v[200:203], v155 offset:52224
	ds_read_b128 v[204:207], v155 offset:53248
	ds_read_b128 v[208:211], v155 offset:54272
	ds_read_b128 v[212:215], v155 offset:55296
	ds_read_b128 v[216:219], v155 offset:56320
	global_load_lds_dwordx4 v[148:149], off
	s_add_i32 m0, s28, 0x2000
	s_add_u32 s28, s34, 0x18080
	v_lshl_add_u64 v[148:149], v[220:221], 0, s[12:13]
	s_addc_u32 s29, s35, 0
	s_add_i32 s34, s59, s40
	global_load_lds_dwordx4 v[148:149], off
	v_lshl_add_u64 v[148:149], s[28:29], 0, v[132:133]
	s_mov_b32 m0, s34
	s_nop 0
	global_load_lds_dwordx4 v[148:149], off
	v_lshl_add_u64 v[148:149], s[28:29], 0, v[128:129]
	s_add_i32 m0, s34, 0x2000
	s_nop 0
	global_load_lds_dwordx4 v[148:149], off
	v_lshl_add_u64 v[148:149], v[222:223], 0, s[12:13]
	s_mov_b32 m0, s47
	s_nop 0
	global_load_lds_dwordx4 v[148:149], off
	v_lshl_add_u64 v[148:149], v[224:225], 0, s[12:13]
	s_mov_b32 m0, s48
	s_nop 0
	global_load_lds_dwordx4 v[148:149], off
	s_waitcnt vmcnt(8) lgkmcnt(0)
	s_barrier
	v_mfma_f32_16x16x32_bf16 v[60:63], v[144:147], v[188:191], v[60:63]
	s_setprio 1
	v_mfma_f32_16x16x32_bf16 v[56:59], v[162:165], v[188:191], v[56:59]
	v_mfma_f32_16x16x32_bf16 v[44:47], v[144:147], v[196:199], v[44:47]
	v_mfma_f32_16x16x32_bf16 v[40:43], v[162:165], v[196:199], v[40:43]
	v_mfma_f32_16x16x32_bf16 v[28:31], v[144:147], v[204:207], v[28:31]
	v_mfma_f32_16x16x32_bf16 v[24:27], v[162:165], v[204:207], v[24:27]
	v_mfma_f32_16x16x32_bf16 v[12:15], v[144:147], v[212:215], v[12:15]
	v_mfma_f32_16x16x32_bf16 v[8:11], v[162:165], v[212:215], v[8:11]
	v_mfma_f32_16x16x32_bf16 v[60:63], v[158:161], v[192:195], v[60:63]
	v_mfma_f32_16x16x32_bf16 v[56:59], v[166:169], v[192:195], v[56:59]
	v_mfma_f32_16x16x32_bf16 v[44:47], v[158:161], v[200:203], v[44:47]
	v_mfma_f32_16x16x32_bf16 v[40:43], v[166:169], v[200:203], v[40:43]
	v_mfma_f32_16x16x32_bf16 v[28:31], v[158:161], v[208:211], v[28:31]
	v_mfma_f32_16x16x32_bf16 v[24:27], v[166:169], v[208:211], v[24:27]
	v_mfma_f32_16x16x32_bf16 v[12:15], v[158:161], v[216:219], v[12:15]
	v_mfma_f32_16x16x32_bf16 v[8:11], v[166:169], v[216:219], v[8:11]
	v_mfma_f32_16x16x32_bf16 v[52:55], v[170:173], v[188:191], v[52:55]
	v_mfma_f32_16x16x32_bf16 v[48:51], v[178:181], v[188:191], v[48:51]
	v_mfma_f32_16x16x32_bf16 v[36:39], v[170:173], v[196:199], v[36:39]
	v_mfma_f32_16x16x32_bf16 v[32:35], v[178:181], v[196:199], v[32:35]
	v_mfma_f32_16x16x32_bf16 v[20:23], v[170:173], v[204:207], v[20:23]
	v_mfma_f32_16x16x32_bf16 v[16:19], v[178:181], v[204:207], v[16:19]
	v_mfma_f32_16x16x32_bf16 v[4:7], v[170:173], v[212:215], v[4:7]
	v_mfma_f32_16x16x32_bf16 v[0:3], v[178:181], v[212:215], v[0:3]
	v_mfma_f32_16x16x32_bf16 v[52:55], v[174:177], v[192:195], v[52:55]
	v_mfma_f32_16x16x32_bf16 v[48:51], v[182:185], v[192:195], v[48:51]
	v_mfma_f32_16x16x32_bf16 v[36:39], v[174:177], v[200:203], v[36:39]
	v_mfma_f32_16x16x32_bf16 v[32:35], v[182:185], v[200:203], v[32:35]
	v_mfma_f32_16x16x32_bf16 v[20:23], v[174:177], v[208:211], v[20:23]
	v_mfma_f32_16x16x32_bf16 v[16:19], v[182:185], v[208:211], v[16:19]
	v_mfma_f32_16x16x32_bf16 v[4:7], v[174:177], v[216:219], v[4:7]
	v_mfma_f32_16x16x32_bf16 v[0:3], v[182:185], v[216:219], v[0:3]
	s_barrier
	s_setprio 0
	s_add_i32 s76, s76, 2
	s_add_u32 s74, s74, 0x100
	s_addc_u32 s75, s75, 0
	s_cmp_gt_u32 s76, 3
	s_mov_b64 s[28:29], s[30:31]
	s_cbranch_scc0 .LBB0_524
	s_and_b64 vcc, exec, s[14:15]
	s_cbranch_vccz .LBB0_527
	s_barrier

; #define PG8_STAGE(bufoff, gbase, voff) do { _Pragma("unroll") for (int _i = 0; _i < 2; ++_i) \
;         __builtin_amdgcn_global_load_lds((const unsigned*)((const char*)(gbase) + (voff)[_i]), (PG8_LAS unsigned*)(lds + (bufoff) + ldsw + _i * 8192), 16, 0, 0); } while (0)
; #define PG8_LDA(dst, b, h) do { _Pragma("unroll") for (int m = 0; m < 4; ++m) _Pragma("unroll") for (int k = 0; k < 2; ++k) dst[m][k] = *(const PG8_LAS bf16x8*)(lds + PG8_SA(b, h) + aoff + m * 2048 + k * 1024); } while (0)
; #define PG8_LDB(dst, b, h) do { _Pragma("unroll") for (int n = 0; n < 2; ++n) _Pragma("unroll") for (int k = 0; k < 2; ++k) dst[n][k] = *(const PG8_LAS bf16x8*)(lds + PG8_SB(b, h) + boff + n * 2048 + k * 1024); } while (0)
; #define PG8_WAIT_V(n) asm volatile("s_waitcnt vmcnt(" #n ")" ::: "memory")
; #define PG8_WAIT_L(n) asm volatile("s_waitcnt lgkmcnt(" #n ")" ::: "memory")
; #define PG8_BAR __builtin_amdgcn_s_barrier()
; #define PG8_SCHED __builtin_amdgcn_sched_barrier(0)
; template <class Epi, class Sched, bool ALIGN_EPI = false, bool SP2 = false>
; __device__ __forceinline__ void gemm_phase(PG8_LAS unsigned char* lds, const Gemm g, const Sched& S, const Epi& E) {
;     ...
;         const bool has_next = S.next(ui + 1, nxt);
;         const char* nA = has_next ? (const char*)g.A + (size_t)nxt.pm * tstepA : cA; const char* nB = has_next ? (const char*)g.Bt + (size_t)nxt.pn * tstepB : cB;
;         for (int t = 0; t < nt; t += 2) {
;             const bool last = (t == nt - 2);
;             const char* a1 = cA + (size_t)(t + 1) * kstep;
;             const char* a2 = last ? nA : cA + (size_t)(t + 2) * kstep; const char* b2 = last ? nB : cB + (size_t)(t + 2) * kstep;
;             const char* a3 = a2 + kstep; const char* b3 = b2 + kstep;
;             if (last && has_next) S.a_ready(nxt);
;             if constexpr (SP2) {
;             PG8_LDB(B0, 0, 0); PG8_LDB(B1, 0, 1); PG8_SCHED; PG8_LDA(At, 0, 0); PG8_STAGE(PG8_SA(1, 1), a1 + hstepA, voffA);
;             PG8_WAIT_V(8); PG8_WAIT_L(0); PG8_BAR; PG8_MMA(0, 0, At, B0); PG8_MMA(0, 1, At, B1); PG8_BAR; PG8_SCHED;
;             PG8_LDA(At, 0, 1); PG8_STAGE(PG8_SB(0, 0), b2, voffB); PG8_STAGE(PG8_SB(0, 1), b2 + hstepB, voffB); PG8_STAGE(PG8_SA(0, 0), a2, voffA);
;             PG8_WAIT_V(8); PG8_WAIT_L(0); PG8_BAR; PG8_MMA(1, 0, At, B0); PG8_MMA(1, 1, At, B1); PG8_BAR; PG8_SCHED;
.LBB0_542:
	s_add_u32 s39, s34, s38
	s_addc_u32 s44, s35, 0
	s_add_u32 s42, s39, 0x100
	s_addc_u32 s43, s44, 0
	s_and_b64 s[40:41], s[36:37], exec
	s_cselect_b32 s41, s27, s43
	s_cselect_b32 s40, s26, s42
	s_add_u32 s38, s30, s38
	s_addc_u32 s42, s31, 0
	s_add_u32 s38, s38, 0x100
	s_addc_u32 s42, s42, 0
	s_and_b64 s[36:37], s[36:37], exec
	s_cselect_b32 s43, s25, s42
	s_cselect_b32 s42, s89, s38
	s_add_u32 s46, s39, 0x30080
	ds_read_b128 v[140:143], v149
	ds_read_b128 v[154:157], v149 offset:1024
	ds_read_b128 v[158:161], v149 offset:2048
	ds_read_b128 v[162:165], v149 offset:3072
	ds_read_b128 v[166:169], v150
	ds_read_b128 v[170:173], v150 offset:1024
	ds_read_b128 v[174:177], v150 offset:2048
	ds_read_b128 v[178:181], v150 offset:3072
	s_addc_u32 s47, s44, 0
	s_add_i32 vcc_hi, s78, s68
	s_add_i32 m0, s70, 0xc000
	s_add_i32 s58, s70, 0xe000
	s_add_i32 s96, vcc_hi, 0x2000
	s_add_u32 s44, s42, 0x10000
	s_addc_u32 s45, s43, 0
	s_add_i32 vcc_lo, s79, s68
	s_add_i32 s97, vcc_lo, 0x2000
	s_add_i32 s95, 0, 0x18000
	s_add_i32 s94, 0, 0x1c000
	s_add_u32 s38, s40, 0x30000
	s_addc_u32 s39, s41, 0
	s_add_i32 s93, s95, s68
	s_add_i32 s91, s93, 0x2000
	s_add_u32 s36, s42, 0x10080
	s_addc_u32 s37, s43, 0
	s_add_i32 s92, s94, s68
	s_add_i32 s90, s92, 0x2000
	v_lshl_add_u64 v[144:145], s[46:47], 0, v[134:135]
	ds_read_b128 v[182:185], v151
	ds_read_b128 v[188:191], v151 offset:1024
	ds_read_b128 v[192:195], v151 offset:2048
	ds_read_b128 v[196:199], v151 offset:3072
	ds_read_b128 v[200:203], v151 offset:4096
	ds_read_b128 v[204:207], v151 offset:5120
	ds_read_b128 v[208:211], v151 offset:6144
	ds_read_b128 v[212:215], v151 offset:7168
	global_load_lds_dwordx4 v[144:145], off
	v_lshl_add_u64 v[144:145], s[46:47], 0, v[130:131]
	s_mov_b32 m0, s58
	s_nop 0
	global_load_lds_dwordx4 v[144:145], off
	s_waitcnt vmcnt(8) lgkmcnt(0)
	s_barrier
	v_mfma_f32_16x16x32_bf16 v[124:127], v[140:143], v[182:185], v[124:127]
	s_setprio 1
	v_mfma_f32_16x16x32_bf16 v[120:123], v[158:161], v[182:185], v[120:123]
	v_mfma_f32_16x16x32_bf16 v[108:111], v[140:143], v[192:195], v[108:111]
	v_mfma_f32_16x16x32_bf16 v[104:107], v[158:161], v[192:195], v[104:107]
	v_mfma_f32_16x16x32_bf16 v[92:95], v[140:143], v[200:203], v[92:95]
	v_mfma_f32_16x16x32_bf16 v[88:91], v[158:161], v[200:203], v[88:91]
	v_mfma_f32_16x16x32_bf16 v[76:79], v[140:143], v[208:211], v[76:79]
	v_mfma_f32_16x16x32_bf16 v[72:75], v[158:161], v[208:211], v[72:75]
	v_mfma_f32_16x16x32_bf16 v[124:127], v[154:157], v[188:191], v[124:127]
	v_mfma_f32_16x16x32_bf16 v[120:123], v[162:165], v[188:191], v[120:123]
	v_mfma_f32_16x16x32_bf16 v[108:111], v[154:157], v[196:199], v[108:111]
	v_mfma_f32_16x16x32_bf16 v[104:107], v[162:165], v[196:199], v[104:107]
	v_mfma_f32_16x16x32_bf16 v[92:95], v[154:157], v[204:207], v[92:95]
	v_mfma_f32_16x16x32_bf16 v[88:91], v[162:165], v[204:207], v[88:91]
	v_mfma_f32_16x16x32_bf16 v[76:79], v[154:157], v[212:215], v[76:79]
	v_mfma_f32_16x16x32_bf16 v[72:75], v[162:165], v[212:215], v[72:75]
	v_mfma_f32_16x16x32_bf16 v[116:119], v[166:169], v[182:185], v[116:119]
	v_mfma_f32_16x16x32_bf16 v[112:115], v[174:177], v[182:185], v[112:115]
	v_mfma_f32_16x16x32_bf16 v[100:103], v[166:169], v[192:195], v[100:103]
	v_mfma_f32_16x16x32_bf16 v[96:99], v[174:177], v[192:195], v[96:99]
	v_mfma_f32_16x16x32_bf16 v[84:87], v[166:169], v[200:203], v[84:87]
	v_mfma_f32_16x16x32_bf16 v[80:83], v[174:177], v[200:203], v[80:83]
	v_mfma_f32_16x16x32_bf16 v[68:71], v[166:169], v[208:211], v[68:71]
	v_mfma_f32_16x16x32_bf16 v[64:67], v[174:177], v[208:211], v[64:67]
	v_mfma_f32_16x16x32_bf16 v[116:119], v[170:173], v[188:191], v[116:119]
	v_mfma_f32_16x16x32_bf16 v[112:115], v[178:181], v[188:191], v[112:115]
	v_mfma_f32_16x16x32_bf16 v[100:103], v[170:173], v[196:199], v[100:103]
	v_mfma_f32_16x16x32_bf16 v[96:99], v[178:181], v[196:199], v[96:99]
	v_mfma_f32_16x16x32_bf16 v[84:87], v[170:173], v[204:207], v[84:87]
	v_mfma_f32_16x16x32_bf16 v[80:83], v[178:181], v[204:207], v[80:83]
	v_mfma_f32_16x16x32_bf16 v[68:71], v[170:173], v[212:215], v[68:71]
	v_mfma_f32_16x16x32_bf16 v[64:67], v[178:181], v[212:215], v[64:67]
	s_barrier
	s_setprio 0
	s_mov_b32 m0, vcc_hi
	v_lshl_add_u64 v[144:145], s[42:43], 0, v[132:133]
	ds_read_b128 v[182:185], v151 offset:16384
	ds_read_b128 v[188:191], v151 offset:17408
	ds_read_b128 v[192:195], v151 offset:18432
	ds_read_b128 v[196:199], v151 offset:19456
	ds_read_b128 v[200:203], v151 offset:20480
	ds_read_b128 v[204:207], v151 offset:21504
	ds_read_b128 v[208:211], v151 offset:22528
	ds_read_b128 v[212:215], v151 offset:23552
	global_load_lds_dwordx4 v[144:145], off
	v_lshl_add_u64 v[216:217], s[42:43], 0, v[128:129]
	s_mov_b32 m0, s96
	v_lshl_add_u64 v[218:219], s[44:45], 0, v[132:133]
	global_load_lds_dwordx4 v[216:217], off
	s_mov_b32 m0, vcc_lo
	v_lshl_add_u64 v[220:221], s[40:41], 0, v[130:131]
	global_load_lds_dwordx4 v[218:219], off
	v_lshl_add_u64 v[218:219], s[44:45], 0, v[128:129]
	s_mov_b32 m0, s97
	s_nop 0
	global_load_lds_dwordx4 v[218:219], off
	v_lshl_add_u64 v[218:219], s[40:41], 0, v[134:135]
	s_mov_b32 m0, s70
	s_nop 0
	global_load_lds_dwordx4 v[218:219], off
	s_mov_b32 m0, s71
	s_nop 0
	global_load_lds_dwordx4 v[220:221], off
	s_waitcnt vmcnt(8) lgkmcnt(0)
	s_barrier
; #define PG8_STAGE(bufoff, gbase, voff) do { _Pragma("unroll") for (int _i = 0; _i < 2; ++_i) \
;         __builtin_amdgcn_global_load_lds((const unsigned*)((const char*)(gbase) + (voff)[_i]), (PG8_LAS unsigned*)(lds + (bufoff) + ldsw + _i * 8192), 16, 0, 0); } while (0)
; #define PG8_LDA(dst, b, h) do { _Pragma("unroll") for (int m = 0; m < 4; ++m) _Pragma("unroll") for (int k = 0; k < 2; ++k) dst[m][k] = *(const PG8_LAS bf16x8*)(lds + PG8_SA(b, h) + aoff + m * 2048 + k * 1024); } while (0)
; #define PG8_LDB(dst, b, h) do { _Pragma("unroll") for (int n = 0; n < 2; ++n) _Pragma("unroll") for (int k = 0; k < 2; ++k) dst[n][k] = *(const PG8_LAS bf16x8*)(lds + PG8_SB(b, h) + boff + n * 2048 + k * 1024); } while (0)
; #define PG8_MMA(ai, bj, At, Bt) do { __builtin_amdgcn_s_setprio(1); _Pragma("unroll") for (int m = 0; m < 4; ++m) _Pragma("unroll") for (int n = 0; n < 2; ++n) _Pragma("unroll") for (int k = 0; k < 2; ++k) \
;         acc[ai][bj][m][n] = __builtin_amdgcn_mfma_f32_16x16x32_bf16(Bt[n][k], At[m][k], acc[ai][bj][m][n], 0, 0, 0); __builtin_amdgcn_s_setprio(0); } while (0)
; #define PG8_WAIT_V(n) asm volatile("s_waitcnt vmcnt(" #n ")" ::: "memory")
; #define PG8_WAIT_L(n) asm volatile("s_waitcnt lgkmcnt(" #n ")" ::: "memory")
; #define PG8_BAR __builtin_amdgcn_s_barrier()
; #define PG8_SCHED __builtin_amdgcn_sched_barrier(0)
; template <class Epi, class Sched, bool ALIGN_EPI = false, bool SP2 = false>
; __device__ __forceinline__ void gemm_phase(PG8_LAS unsigned char* lds, const Gemm g, const Sched& S, const Epi& E) {
;     ...
;             PG8_WAIT_V(8); PG8_WAIT_L(0); PG8_BAR; PG8_MMA(1, 0, At, B0); PG8_MMA(1, 1, At, B1); PG8_BAR; PG8_SCHED;
;             PG8_LDB(B0, 1, 0); PG8_LDB(B1, 1, 1); PG8_SCHED; PG8_LDA(At, 1, 0); PG8_STAGE(PG8_SA(0, 1), a2 + hstepA, voffA);
;             PG8_WAIT_V(8); PG8_WAIT_L(0); PG8_BAR; PG8_MMA(0, 0, At, B0); PG8_MMA(0, 1, At, B1); PG8_BAR; PG8_SCHED;
	v_mfma_f32_16x16x32_bf16 v[60:63], v[140:143], v[182:185], v[60:63]
	s_setprio 1
	v_mfma_f32_16x16x32_bf16 v[56:59], v[158:161], v[182:185], v[56:59]
	v_mfma_f32_16x16x32_bf16 v[44:47], v[140:143], v[192:195], v[44:47]
	v_mfma_f32_16x16x32_bf16 v[40:43], v[158:161], v[192:195], v[40:43]
	v_mfma_f32_16x16x32_bf16 v[28:31], v[140:143], v[200:203], v[28:31]
	v_mfma_f32_16x16x32_bf16 v[24:27], v[158:161], v[200:203], v[24:27]
	v_mfma_f32_16x16x32_bf16 v[12:15], v[140:143], v[208:211], v[12:15]
	v_mfma_f32_16x16x32_bf16 v[8:11], v[158:161], v[208:211], v[8:11]
	v_mfma_f32_16x16x32_bf16 v[60:63], v[154:157], v[188:191], v[60:63]
	v_mfma_f32_16x16x32_bf16 v[56:59], v[162:165], v[188:191], v[56:59]
	v_mfma_f32_16x16x32_bf16 v[44:47], v[154:157], v[196:199], v[44:47]
	v_mfma_f32_16x16x32_bf16 v[40:43], v[162:165], v[196:199], v[40:43]
	v_mfma_f32_16x16x32_bf16 v[28:31], v[154:157], v[204:207], v[28:31]
	v_mfma_f32_16x16x32_bf16 v[24:27], v[162:165], v[204:207], v[24:27]
	v_mfma_f32_16x16x32_bf16 v[12:15], v[154:157], v[212:215], v[12:15]
	v_mfma_f32_16x16x32_bf16 v[8:11], v[162:165], v[212:215], v[8:11]
	v_mfma_f32_16x16x32_bf16 v[52:55], v[166:169], v[182:185], v[52:55]
	v_mfma_f32_16x16x32_bf16 v[48:51], v[174:177], v[182:185], v[48:51]
	v_mfma_f32_16x16x32_bf16 v[36:39], v[166:169], v[192:195], v[36:39]
	v_mfma_f32_16x16x32_bf16 v[32:35], v[174:177], v[192:195], v[32:35]
	v_mfma_f32_16x16x32_bf16 v[20:23], v[166:169], v[200:203], v[20:23]
	v_mfma_f32_16x16x32_bf16 v[16:19], v[174:177], v[200:203], v[16:19]
	v_mfma_f32_16x16x32_bf16 v[4:7], v[166:169], v[208:211], v[4:7]
	v_mfma_f32_16x16x32_bf16 v[0:3], v[174:177], v[208:211], v[0:3]
	v_mfma_f32_16x16x32_bf16 v[52:55], v[170:173], v[188:191], v[52:55]
	v_mfma_f32_16x16x32_bf16 v[48:51], v[178:181], v[188:191], v[48:51]
	v_mfma_f32_16x16x32_bf16 v[36:39], v[170:173], v[196:199], v[36:39]
	v_mfma_f32_16x16x32_bf16 v[32:35], v[178:181], v[196:199], v[32:35]
	v_mfma_f32_16x16x32_bf16 v[20:23], v[170:173], v[204:207], v[20:23]
	v_mfma_f32_16x16x32_bf16 v[16:19], v[178:181], v[204:207], v[16:19]
	v_mfma_f32_16x16x32_bf16 v[4:7], v[170:173], v[212:215], v[4:7]
	v_mfma_f32_16x16x32_bf16 v[0:3], v[178:181], v[212:215], v[0:3]
	s_barrier
	s_setprio 0
	v_add_u32_e32 v153, s95, v147
	ds_read_b128 v[140:143], v153
	ds_read_b128 v[154:157], v153 offset:1024
	ds_read_b128 v[158:161], v153 offset:2048
	ds_read_b128 v[162:165], v153 offset:3072
	v_add_u32_e32 v153, s94, v147
	ds_read_b128 v[166:169], v153
	ds_read_b128 v[170:173], v153 offset:1024
	ds_read_b128 v[174:177], v153 offset:2048
	ds_read_b128 v[178:181], v153 offset:3072
	s_mov_b32 m0, s72
	v_lshl_add_u64 v[222:223], s[38:39], 0, v[134:135]
	ds_read_b128 v[182:185], v151 offset:32768
	ds_read_b128 v[188:191], v151 offset:33792
	ds_read_b128 v[192:195], v151 offset:34816
	ds_read_b128 v[196:199], v151 offset:35840
	ds_read_b128 v[200:203], v151 offset:36864
	ds_read_b128 v[204:207], v151 offset:37888
	ds_read_b128 v[208:211], v151 offset:38912
	ds_read_b128 v[212:215], v151 offset:39936
	global_load_lds_dwordx4 v[222:223], off
	v_lshl_add_u64 v[222:223], s[38:39], 0, v[130:131]
	s_mov_b32 m0, s73
	s_nop 0
	global_load_lds_dwordx4 v[222:223], off
	s_waitcnt vmcnt(8) lgkmcnt(0)
	s_barrier
	v_mfma_f32_16x16x32_bf16 v[124:127], v[140:143], v[182:185], v[124:127]
	s_setprio 1
	v_mfma_f32_16x16x32_bf16 v[120:123], v[158:161], v[182:185], v[120:123]
	v_mfma_f32_16x16x32_bf16 v[108:111], v[140:143], v[192:195], v[108:111]
	v_mfma_f32_16x16x32_bf16 v[104:107], v[158:161], v[192:195], v[104:107]
	v_mfma_f32_16x16x32_bf16 v[92:95], v[140:143], v[200:203], v[92:95]
	v_mfma_f32_16x16x32_bf16 v[88:91], v[158:161], v[200:203], v[88:91]
	v_mfma_f32_16x16x32_bf16 v[76:79], v[140:143], v[208:211], v[76:79]
	v_mfma_f32_16x16x32_bf16 v[72:75], v[158:161], v[208:211], v[72:75]
	v_mfma_f32_16x16x32_bf16 v[124:127], v[154:157], v[188:191], v[124:127]
	v_mfma_f32_16x16x32_bf16 v[120:123], v[162:165], v[188:191], v[120:123]
	v_mfma_f32_16x16x32_bf16 v[108:111], v[154:157], v[196:199], v[108:111]
	v_mfma_f32_16x16x32_bf16 v[104:107], v[162:165], v[196:199], v[104:107]
	v_mfma_f32_16x16x32_bf16 v[92:95], v[154:157], v[204:207], v[92:95]
	v_mfma_f32_16x16x32_bf16 v[88:91], v[162:165], v[204:207], v[88:91]
	v_mfma_f32_16x16x32_bf16 v[76:79], v[154:157], v[212:215], v[76:79]
	v_mfma_f32_16x16x32_bf16 v[72:75], v[162:165], v[212:215], v[72:75]
	v_mfma_f32_16x16x32_bf16 v[116:119], v[166:169], v[182:185], v[116:119]
	v_mfma_f32_16x16x32_bf16 v[112:115], v[174:177], v[182:185], v[112:115]
	v_mfma_f32_16x16x32_bf16 v[100:103], v[166:169], v[192:195], v[100:103]
	v_mfma_f32_16x16x32_bf16 v[96:99], v[174:177], v[192:195], v[96:99]
	v_mfma_f32_16x16x32_bf16 v[84:87], v[166:169], v[200:203], v[84:87]
	v_mfma_f32_16x16x32_bf16 v[80:83], v[174:177], v[200:203], v[80:83]
	v_mfma_f32_16x16x32_bf16 v[68:71], v[166:169], v[208:211], v[68:71]
	v_mfma_f32_16x16x32_bf16 v[64:67], v[174:177], v[208:211], v[64:67]
	v_mfma_f32_16x16x32_bf16 v[116:119], v[170:173], v[188:191], v[116:119]
	v_mfma_f32_16x16x32_bf16 v[112:115], v[178:181], v[188:191], v[112:115]
	v_mfma_f32_16x16x32_bf16 v[100:103], v[170:173], v[196:199], v[100:103]
	v_mfma_f32_16x16x32_bf16 v[96:99], v[178:181], v[196:199], v[96:99]
	v_mfma_f32_16x16x32_bf16 v[84:87], v[170:173], v[204:207], v[84:87]
	v_mfma_f32_16x16x32_bf16 v[80:83], v[178:181], v[204:207], v[80:83]
	v_mfma_f32_16x16x32_bf16 v[68:71], v[170:173], v[212:215], v[68:71]
	v_mfma_f32_16x16x32_bf16 v[64:67], v[178:181], v[212:215], v[64:67]
	s_barrier
; #define PG8_STAGE(bufoff, gbase, voff) do { _Pragma("unroll") for (int _i = 0; _i < 2; ++_i) \
;         __builtin_amdgcn_global_load_lds((const unsigned*)((const char*)(gbase) + (voff)[_i]), (PG8_LAS unsigned*)(lds + (bufoff) + ldsw + _i * 8192), 16, 0, 0); } while (0)
; #define PG8_LDA(dst, b, h) do { _Pragma("unroll") for (int m = 0; m < 4; ++m) _Pragma("unroll") for (int k = 0; k < 2; ++k) dst[m][k] = *(const PG8_LAS bf16x8*)(lds + PG8_SA(b, h) + aoff + m * 2048 + k * 1024); } while (0)
; #define PG8_MMA(ai, bj, At, Bt) do { __builtin_amdgcn_s_setprio(1); _Pragma("unroll") for (int m = 0; m < 4; ++m) _Pragma("unroll") for (int n = 0; n < 2; ++n) _Pragma("unroll") for (int k = 0; k < 2; ++k) \
;         acc[ai][bj][m][n] = __builtin_amdgcn_mfma_f32_16x16x32_bf16(Bt[n][k], At[m][k], acc[ai][bj][m][n], 0, 0, 0); __builtin_amdgcn_s_setprio(0); } while (0)
; #define PG8_WAIT_V(n) asm volatile("s_waitcnt vmcnt(" #n ")" ::: "memory")
; #define PG8_WAIT_L(n) asm volatile("s_waitcnt lgkmcnt(" #n ")" ::: "memory")
; #define PG8_BAR __builtin_amdgcn_s_barrier()
; #define PG8_SCHED __builtin_amdgcn_sched_barrier(0)
; template <class Epi, class Sched, bool ALIGN_EPI = false, bool SP2 = false>
; __device__ __forceinline__ void gemm_phase(PG8_LAS unsigned char* lds, const Gemm g, const Sched& S, const Epi& E) {
;     ...
;             PG8_LDA(At, 1, 1); PG8_STAGE(PG8_SB(1, 0), b3, voffB); PG8_STAGE(PG8_SB(1, 1), b3 + hstepB, voffB); PG8_STAGE(PG8_SA(1, 0), a3, voffA);
;             PG8_WAIT_V(8); PG8_WAIT_L(0); PG8_BAR; PG8_MMA(1, 0, At, B0); PG8_MMA(1, 1, At, B1); PG8_BAR; PG8_SCHED;
	s_setprio 0
	s_mov_b32 m0, s93
	v_lshl_add_u64 v[144:145], v[144:145], 0, s[12:13]
	ds_read_b128 v[182:185], v151 offset:49152
	ds_read_b128 v[188:191], v151 offset:50176
	ds_read_b128 v[192:195], v151 offset:51200
	ds_read_b128 v[196:199], v151 offset:52224
	ds_read_b128 v[200:203], v151 offset:53248
	ds_read_b128 v[204:207], v151 offset:54272
	ds_read_b128 v[208:211], v151 offset:55296
	ds_read_b128 v[212:215], v151 offset:56320
	global_load_lds_dwordx4 v[144:145], off
	v_lshl_add_u64 v[144:145], v[216:217], 0, s[12:13]
	s_mov_b32 m0, s91
	s_nop 0
	global_load_lds_dwordx4 v[144:145], off
	v_lshl_add_u64 v[144:145], s[36:37], 0, v[132:133]
	s_mov_b32 m0, s92
	s_nop 0
	global_load_lds_dwordx4 v[144:145], off
	v_lshl_add_u64 v[144:145], s[36:37], 0, v[128:129]
	s_mov_b32 m0, s90
	s_nop 0
	global_load_lds_dwordx4 v[144:145], off
	v_lshl_add_u64 v[144:145], v[218:219], 0, s[12:13]
	s_mov_b32 m0, s75
	s_nop 0
	global_load_lds_dwordx4 v[144:145], off
	v_lshl_add_u64 v[144:145], v[220:221], 0, s[12:13]
	s_mov_b32 m0, s76
	s_nop 0
	global_load_lds_dwordx4 v[144:145], off
	s_waitcnt vmcnt(8) lgkmcnt(0)
	s_barrier
	v_mfma_f32_16x16x32_bf16 v[60:63], v[140:143], v[182:185], v[60:63]
	s_setprio 1
	v_mfma_f32_16x16x32_bf16 v[56:59], v[158:161], v[182:185], v[56:59]
	v_mfma_f32_16x16x32_bf16 v[44:47], v[140:143], v[192:195], v[44:47]
	v_mfma_f32_16x16x32_bf16 v[40:43], v[158:161], v[192:195], v[40:43]
	v_mfma_f32_16x16x32_bf16 v[28:31], v[140:143], v[200:203], v[28:31]
	v_mfma_f32_16x16x32_bf16 v[24:27], v[158:161], v[200:203], v[24:27]
	v_mfma_f32_16x16x32_bf16 v[12:15], v[140:143], v[208:211], v[12:15]
	v_mfma_f32_16x16x32_bf16 v[8:11], v[158:161], v[208:211], v[8:11]
	v_mfma_f32_16x16x32_bf16 v[60:63], v[154:157], v[188:191], v[60:63]
	v_mfma_f32_16x16x32_bf16 v[56:59], v[162:165], v[188:191], v[56:59]
	v_mfma_f32_16x16x32_bf16 v[44:47], v[154:157], v[196:199], v[44:47]
	v_mfma_f32_16x16x32_bf16 v[40:43], v[162:165], v[196:199], v[40:43]
	v_mfma_f32_16x16x32_bf16 v[28:31], v[154:157], v[204:207], v[28:31]
	v_mfma_f32_16x16x32_bf16 v[24:27], v[162:165], v[204:207], v[24:27]
	v_mfma_f32_16x16x32_bf16 v[12:15], v[154:157], v[212:215], v[12:15]
	v_mfma_f32_16x16x32_bf16 v[8:11], v[162:165], v[212:215], v[8:11]
	v_mfma_f32_16x16x32_bf16 v[52:55], v[166:169], v[182:185], v[52:55]
	v_mfma_f32_16x16x32_bf16 v[48:51], v[174:177], v[182:185], v[48:51]
	v_mfma_f32_16x16x32_bf16 v[36:39], v[166:169], v[192:195], v[36:39]
	v_mfma_f32_16x16x32_bf16 v[32:35], v[174:177], v[192:195], v[32:35]
	v_mfma_f32_16x16x32_bf16 v[20:23], v[166:169], v[200:203], v[20:23]
	v_mfma_f32_16x16x32_bf16 v[16:19], v[174:177], v[200:203], v[16:19]
	v_mfma_f32_16x16x32_bf16 v[4:7], v[166:169], v[208:211], v[4:7]
	v_mfma_f32_16x16x32_bf16 v[0:3], v[174:177], v[208:211], v[0:3]
	v_mfma_f32_16x16x32_bf16 v[52:55], v[170:173], v[188:191], v[52:55]
	v_mfma_f32_16x16x32_bf16 v[48:51], v[178:181], v[188:191], v[48:51]
	v_mfma_f32_16x16x32_bf16 v[36:39], v[170:173], v[196:199], v[36:39]
	v_mfma_f32_16x16x32_bf16 v[32:35], v[178:181], v[196:199], v[32:35]
	v_mfma_f32_16x16x32_bf16 v[20:23], v[170:173], v[204:207], v[20:23]
	v_mfma_f32_16x16x32_bf16 v[16:19], v[178:181], v[204:207], v[16:19]
	v_mfma_f32_16x16x32_bf16 v[4:7], v[170:173], v[212:215], v[4:7]
	v_mfma_f32_16x16x32_bf16 v[0:3], v[178:181], v[212:215], v[0:3]
	s_barrier
	s_setprio 0
	s_movk_i32 s38, 0x100
	s_andn2_b64 vcc, exec, s[8:9]
	s_mov_b64 s[36:37], -1
	s_mov_b64 s[8:9], 0
	s_cbranch_vccz .LBB0_542
	s_and_b64 vcc, exec, s[14:15]
	s_cbranch_vccz .LBB0_545
	s_barrier

; #define PG8_STAGE(bufoff, gbase, voff) do { _Pragma("unroll") for (int _i = 0; _i < 2; ++_i) \
;         __builtin_amdgcn_global_load_lds((const unsigned*)((const char*)(gbase) + (voff)[_i]), (PG8_LAS unsigned*)(lds + (bufoff) + ldsw + _i * 8192), 16, 0, 0); } while (0)
; #define PG8_LDA(dst, b, h) do { _Pragma("unroll") for (int m = 0; m < 4; ++m) _Pragma("unroll") for (int k = 0; k < 2; ++k) dst[m][k] = *(const PG8_LAS bf16x8*)(lds + PG8_SA(b, h) + aoff + m * 2048 + k * 1024); } while (0)
; #define PG8_LDB(dst, b, h) do { _Pragma("unroll") for (int n = 0; n < 2; ++n) _Pragma("unroll") for (int k = 0; k < 2; ++k) dst[n][k] = *(const PG8_LAS bf16x8*)(lds + PG8_SB(b, h) + boff + n * 2048 + k * 1024); } while (0)
; #define PG8_MMA(ai, bj, At, Bt) do { __builtin_amdgcn_s_setprio(1); _Pragma("unroll") for (int m = 0; m < 4; ++m) _Pragma("unroll") for (int n = 0; n < 2; ++n) _Pragma("unroll") for (int k = 0; k < 2; ++k) \
;         acc[ai][bj][m][n] = __builtin_amdgcn_mfma_f32_16x16x32_bf16(Bt[n][k], At[m][k], acc[ai][bj][m][n], 0, 0, 0); __builtin_amdgcn_s_setprio(0); } while (0)
; #define PG8_WAIT_V(n) asm volatile("s_waitcnt vmcnt(" #n ")" ::: "memory")
; #define PG8_BAR __builtin_amdgcn_s_barrier()
; template <class Epi, class Sched, bool ALIGN_EPI = false, bool SP2 = false>
; __device__ __forceinline__ void gemm_phase(PG8_LAS unsigned char* lds, const Gemm g, const Sched& S, const Epi& E) {
;     ...
;         for (int t = 0; t < nt; t += 2) {
;             const bool last = (t == nt - 2);
;             const char* a1 = cA + (size_t)(t + 1) * kstep;
;             const char* a2 = last ? nA : cA + (size_t)(t + 2) * kstep; const char* b2 = last ? nB : cB + (size_t)(t + 2) * kstep;
;             const char* a3 = a2 + kstep; const char* b3 = b2 + kstep;
;             if (last && has_next) S.a_ready(nxt);
;             if constexpr (SP2) {
;             PG8_LDB(B0, 0, 0); PG8_LDB(B1, 0, 1); PG8_SCHED; PG8_LDA(At, 0, 0); PG8_STAGE(PG8_SA(1, 1), a1 + hstepA, voffA);
;             PG8_WAIT_V(8); PG8_WAIT_L(0); PG8_BAR; PG8_MMA(0, 0, At, B0); PG8_MMA(0, 1, At, B1); PG8_BAR; PG8_SCHED;
;             PG8_LDA(At, 0, 1); PG8_STAGE(PG8_SB(0, 0), b2, voffB); PG8_STAGE(PG8_SB(0, 1), b2 + hstepB, voffB); PG8_STAGE(PG8_SA(0, 0), a2, voffA);
;             PG8_WAIT_V(8); PG8_WAIT_L(0); PG8_BAR; PG8_MMA(1, 0, At, B0); PG8_MMA(1, 1, At, B1); PG8_BAR; PG8_SCHED;
.LBB0_971:
	ds_read_b128 v[128:131], v191
	ds_read_b128 v[132:135], v191 offset:1024
	ds_read_b128 v[136:139], v191 offset:2048
	ds_read_b128 v[140:143], v191 offset:3072
	ds_read_b128 v[144:147], v192
	ds_read_b128 v[148:151], v192 offset:1024
	ds_read_b128 v[168:171], v192 offset:2048
	ds_read_b128 v[172:175], v192 offset:3072
	s_add_u32 s34, s30, 0xfffc0080
	s_addc_u32 s35, s31, -1
	s_cmp_eq_u32 s74, 12
	s_cselect_b32 s37, s21, s35
	s_cselect_b32 s36, s27, s34
	s_cselect_b32 s35, s19, s73
	s_cselect_b32 s34, s68, s69
	v_lshl_add_u64 v[184:185], s[30:31], 0, v[160:161]
	s_add_i32 m0, s29, 0xc000
	ds_read_b128 v[176:179], v193
	ds_read_b128 v[180:183], v193 offset:1024
	ds_read_b128 v[196:199], v193 offset:2048
	ds_read_b128 v[200:203], v193 offset:3072
	ds_read_b128 v[204:207], v193 offset:4096
	ds_read_b128 v[208:211], v193 offset:5120
	ds_read_b128 v[212:215], v193 offset:6144
	ds_read_b128 v[216:219], v193 offset:7168
	global_load_lds_dwordx4 v[184:185], off
	v_lshl_add_u64 v[184:185], s[30:31], 0, v[162:163]
	s_add_i32 m0, s29, 0xe000
	s_nop 0
	global_load_lds_dwordx4 v[184:185], off
	s_waitcnt vmcnt(8) lgkmcnt(0)
	s_barrier
	v_mfma_f32_16x16x32_bf16 v[124:127], v[128:131], v[176:179], v[124:127]
	s_setprio 1
	v_mfma_f32_16x16x32_bf16 v[120:123], v[136:139], v[176:179], v[120:123]
	v_mfma_f32_16x16x32_bf16 v[108:111], v[128:131], v[196:199], v[108:111]
	v_mfma_f32_16x16x32_bf16 v[104:107], v[136:139], v[196:199], v[104:107]
	v_mfma_f32_16x16x32_bf16 v[92:95], v[128:131], v[204:207], v[92:95]
	v_mfma_f32_16x16x32_bf16 v[88:91], v[136:139], v[204:207], v[88:91]
	v_mfma_f32_16x16x32_bf16 v[76:79], v[128:131], v[212:215], v[76:79]
	v_mfma_f32_16x16x32_bf16 v[72:75], v[136:139], v[212:215], v[72:75]
	v_mfma_f32_16x16x32_bf16 v[124:127], v[132:135], v[180:183], v[124:127]
	v_mfma_f32_16x16x32_bf16 v[120:123], v[140:143], v[180:183], v[120:123]
	v_mfma_f32_16x16x32_bf16 v[108:111], v[132:135], v[200:203], v[108:111]
	v_mfma_f32_16x16x32_bf16 v[104:107], v[140:143], v[200:203], v[104:107]
	v_mfma_f32_16x16x32_bf16 v[92:95], v[132:135], v[208:211], v[92:95]
	v_mfma_f32_16x16x32_bf16 v[88:91], v[140:143], v[208:211], v[88:91]
	v_mfma_f32_16x16x32_bf16 v[76:79], v[132:135], v[216:219], v[76:79]
	v_mfma_f32_16x16x32_bf16 v[72:75], v[140:143], v[216:219], v[72:75]
	v_mfma_f32_16x16x32_bf16 v[116:119], v[144:147], v[176:179], v[116:119]
	v_mfma_f32_16x16x32_bf16 v[112:115], v[168:171], v[176:179], v[112:115]
	v_mfma_f32_16x16x32_bf16 v[100:103], v[144:147], v[196:199], v[100:103]
	v_mfma_f32_16x16x32_bf16 v[96:99], v[168:171], v[196:199], v[96:99]
	v_mfma_f32_16x16x32_bf16 v[84:87], v[144:147], v[204:207], v[84:87]
	v_mfma_f32_16x16x32_bf16 v[80:83], v[168:171], v[204:207], v[80:83]
	v_mfma_f32_16x16x32_bf16 v[68:71], v[144:147], v[212:215], v[68:71]
	v_mfma_f32_16x16x32_bf16 v[64:67], v[168:171], v[212:215], v[64:67]
	v_mfma_f32_16x16x32_bf16 v[116:119], v[148:151], v[180:183], v[116:119]
	v_mfma_f32_16x16x32_bf16 v[112:115], v[172:175], v[180:183], v[112:115]
	v_mfma_f32_16x16x32_bf16 v[100:103], v[148:151], v[200:203], v[100:103]
	v_mfma_f32_16x16x32_bf16 v[96:99], v[172:175], v[200:203], v[96:99]
	v_mfma_f32_16x16x32_bf16 v[84:87], v[148:151], v[208:211], v[84:87]
	v_mfma_f32_16x16x32_bf16 v[80:83], v[172:175], v[208:211], v[80:83]
	v_mfma_f32_16x16x32_bf16 v[68:71], v[148:151], v[216:219], v[68:71]
	v_mfma_f32_16x16x32_bf16 v[64:67], v[172:175], v[216:219], v[64:67]
	s_barrier
	s_setprio 0
	s_add_i32 s58, s49, s39
	v_lshl_add_u64 v[184:185], s[34:35], 0, v[154:155]
	s_mov_b32 m0, s58
	ds_read_b128 v[176:179], v193 offset:16384
	ds_read_b128 v[180:183], v193 offset:17408
	ds_read_b128 v[196:199], v193 offset:18432
	ds_read_b128 v[200:203], v193 offset:19456
	ds_read_b128 v[204:207], v193 offset:20480
	ds_read_b128 v[208:211], v193 offset:21504
	ds_read_b128 v[212:215], v193 offset:22528
	ds_read_b128 v[216:219], v193 offset:23552
	global_load_lds_dwordx4 v[184:185], off
	s_add_i32 m0, s58, 0x2000
	s_add_u32 s58, s34, 0x40000
	v_lshl_add_u64 v[220:221], s[34:35], 0, v[158:159]
	s_addc_u32 s59, s35, 0
	s_add_i32 s75, s66, s39
	global_load_lds_dwordx4 v[220:221], off
	v_lshl_add_u64 v[222:223], s[58:59], 0, v[154:155]
	s_mov_b32 m0, s75
	v_lshl_add_u64 v[224:225], s[36:37], 0, v[156:157]
	global_load_lds_dwordx4 v[222:223], off
	v_lshl_add_u64 v[222:223], s[58:59], 0, v[158:159]
	s_add_i32 m0, s75, 0x2000
	s_nop 0
	global_load_lds_dwordx4 v[222:223], off
	v_lshl_add_u64 v[222:223], s[36:37], 0, v[152:153]
	s_mov_b32 m0, s29
	s_nop 0
	global_load_lds_dwordx4 v[222:223], off
	s_mov_b32 m0, s40
	s_nop 0
	global_load_lds_dwordx4 v[224:225], off
	s_waitcnt vmcnt(8) lgkmcnt(0)
	s_barrier
; #define PG8_STAGE(bufoff, gbase, voff) do { _Pragma("unroll") for (int _i = 0; _i < 2; ++_i) \
;         __builtin_amdgcn_global_load_lds((const unsigned*)((const char*)(gbase) + (voff)[_i]), (PG8_LAS unsigned*)(lds + (bufoff) + ldsw + _i * 8192), 16, 0, 0); } while (0)
; #define PG8_LDA(dst, b, h) do { _Pragma("unroll") for (int m = 0; m < 4; ++m) _Pragma("unroll") for (int k = 0; k < 2; ++k) dst[m][k] = *(const PG8_LAS bf16x8*)(lds + PG8_SA(b, h) + aoff + m * 2048 + k * 1024); } while (0)
; #define PG8_LDB(dst, b, h) do { _Pragma("unroll") for (int n = 0; n < 2; ++n) _Pragma("unroll") for (int k = 0; k < 2; ++k) dst[n][k] = *(const PG8_LAS bf16x8*)(lds + PG8_SB(b, h) + boff + n * 2048 + k * 1024); } while (0)
; #define PG8_MMA(ai, bj, At, Bt) do { __builtin_amdgcn_s_setprio(1); _Pragma("unroll") for (int m = 0; m < 4; ++m) _Pragma("unroll") for (int n = 0; n < 2; ++n) _Pragma("unroll") for (int k = 0; k < 2; ++k) \
;         acc[ai][bj][m][n] = __builtin_amdgcn_mfma_f32_16x16x32_bf16(Bt[n][k], At[m][k], acc[ai][bj][m][n], 0, 0, 0); __builtin_amdgcn_s_setprio(0); } while (0)
; #define PG8_WAIT_V(n) asm volatile("s_waitcnt vmcnt(" #n ")" ::: "memory")
; #define PG8_WAIT_L(n) asm volatile("s_waitcnt lgkmcnt(" #n ")" ::: "memory")
; #define PG8_BAR __builtin_amdgcn_s_barrier()
; #define PG8_SCHED __builtin_amdgcn_sched_barrier(0)
; template <class Epi, class Sched, bool ALIGN_EPI = false, bool SP2 = false>
; __device__ __forceinline__ void gemm_phase(PG8_LAS unsigned char* lds, const Gemm g, const Sched& S, const Epi& E) {
;     ...
;             PG8_WAIT_V(8); PG8_WAIT_L(0); PG8_BAR; PG8_MMA(1, 0, At, B0); PG8_MMA(1, 1, At, B1); PG8_BAR; PG8_SCHED;
;             PG8_LDB(B0, 1, 0); PG8_LDB(B1, 1, 1); PG8_SCHED; PG8_LDA(At, 1, 0); PG8_STAGE(PG8_SA(0, 1), a2 + hstepA, voffA);
;             PG8_WAIT_V(8); PG8_WAIT_L(0); PG8_BAR; PG8_MMA(0, 0, At, B0); PG8_MMA(0, 1, At, B1); PG8_BAR; PG8_SCHED;
	v_mfma_f32_16x16x32_bf16 v[60:63], v[128:131], v[176:179], v[60:63]
	s_setprio 1
	v_mfma_f32_16x16x32_bf16 v[56:59], v[136:139], v[176:179], v[56:59]
	v_mfma_f32_16x16x32_bf16 v[44:47], v[128:131], v[196:199], v[44:47]
	v_mfma_f32_16x16x32_bf16 v[40:43], v[136:139], v[196:199], v[40:43]
	v_mfma_f32_16x16x32_bf16 v[28:31], v[128:131], v[204:207], v[28:31]
	v_mfma_f32_16x16x32_bf16 v[24:27], v[136:139], v[204:207], v[24:27]
	v_mfma_f32_16x16x32_bf16 v[12:15], v[128:131], v[212:215], v[12:15]
	v_mfma_f32_16x16x32_bf16 v[8:11], v[136:139], v[212:215], v[8:11]
	v_mfma_f32_16x16x32_bf16 v[60:63], v[132:135], v[180:183], v[60:63]
	v_mfma_f32_16x16x32_bf16 v[56:59], v[140:143], v[180:183], v[56:59]
	v_mfma_f32_16x16x32_bf16 v[44:47], v[132:135], v[200:203], v[44:47]
	v_mfma_f32_16x16x32_bf16 v[40:43], v[140:143], v[200:203], v[40:43]
	v_mfma_f32_16x16x32_bf16 v[28:31], v[132:135], v[208:211], v[28:31]
	v_mfma_f32_16x16x32_bf16 v[24:27], v[140:143], v[208:211], v[24:27]
	v_mfma_f32_16x16x32_bf16 v[12:15], v[132:135], v[216:219], v[12:15]
	v_mfma_f32_16x16x32_bf16 v[8:11], v[140:143], v[216:219], v[8:11]
	v_mfma_f32_16x16x32_bf16 v[52:55], v[144:147], v[176:179], v[52:55]
	v_mfma_f32_16x16x32_bf16 v[48:51], v[168:171], v[176:179], v[48:51]
	v_mfma_f32_16x16x32_bf16 v[36:39], v[144:147], v[196:199], v[36:39]
	v_mfma_f32_16x16x32_bf16 v[32:35], v[168:171], v[196:199], v[32:35]
	v_mfma_f32_16x16x32_bf16 v[20:23], v[144:147], v[204:207], v[20:23]
	v_mfma_f32_16x16x32_bf16 v[16:19], v[168:171], v[204:207], v[16:19]
	v_mfma_f32_16x16x32_bf16 v[4:7], v[144:147], v[212:215], v[4:7]
	v_mfma_f32_16x16x32_bf16 v[0:3], v[168:171], v[212:215], v[0:3]
	v_mfma_f32_16x16x32_bf16 v[52:55], v[148:151], v[180:183], v[52:55]
	v_mfma_f32_16x16x32_bf16 v[48:51], v[172:175], v[180:183], v[48:51]
	v_mfma_f32_16x16x32_bf16 v[36:39], v[148:151], v[200:203], v[36:39]
	v_mfma_f32_16x16x32_bf16 v[32:35], v[172:175], v[200:203], v[32:35]
	v_mfma_f32_16x16x32_bf16 v[20:23], v[148:151], v[208:211], v[20:23]
	v_mfma_f32_16x16x32_bf16 v[16:19], v[172:175], v[208:211], v[16:19]
	v_mfma_f32_16x16x32_bf16 v[4:7], v[148:151], v[216:219], v[4:7]
	v_mfma_f32_16x16x32_bf16 v[0:3], v[172:175], v[216:219], v[0:3]
	s_barrier
	s_setprio 0
	s_add_i32 s58, 0, 0x18000
	s_add_i32 s59, 0, 0x1c000
	v_add_u32_e32 v140, s58, v189
	v_add_u32_e32 v172, s59, v189
	ds_read_b128 v[128:131], v140
	ds_read_b128 v[132:135], v140 offset:1024
	ds_read_b128 v[136:139], v140 offset:2048
	ds_read_b128 v[140:143], v140 offset:3072
	ds_read_b128 v[144:147], v172
	ds_read_b128 v[148:151], v172 offset:1024
	ds_read_b128 v[168:171], v172 offset:2048
	ds_read_b128 v[172:175], v172 offset:3072
	s_add_u32 s36, s36, 0x40000
	s_addc_u32 s37, s37, 0
	s_mov_b32 m0, s41
	v_lshl_add_u64 v[226:227], s[36:37], 0, v[152:153]
	ds_read_b128 v[176:179], v193 offset:32768
	ds_read_b128 v[180:183], v193 offset:33792
	ds_read_b128 v[196:199], v193 offset:34816
	ds_read_b128 v[200:203], v193 offset:35840
	ds_read_b128 v[204:207], v193 offset:36864
	ds_read_b128 v[208:211], v193 offset:37888
	ds_read_b128 v[212:215], v193 offset:38912
	ds_read_b128 v[216:219], v193 offset:39936
	global_load_lds_dwordx4 v[226:227], off
	v_lshl_add_u64 v[226:227], s[36:37], 0, v[156:157]
	s_mov_b32 m0, s42
	s_nop 0
	global_load_lds_dwordx4 v[226:227], off
	s_waitcnt vmcnt(8) lgkmcnt(0)
	s_barrier
	v_mfma_f32_16x16x32_bf16 v[124:127], v[128:131], v[176:179], v[124:127]
	s_setprio 1
	v_mfma_f32_16x16x32_bf16 v[120:123], v[136:139], v[176:179], v[120:123]
	v_mfma_f32_16x16x32_bf16 v[108:111], v[128:131], v[196:199], v[108:111]
	v_mfma_f32_16x16x32_bf16 v[104:107], v[136:139], v[196:199], v[104:107]
	v_mfma_f32_16x16x32_bf16 v[92:95], v[128:131], v[204:207], v[92:95]
	v_mfma_f32_16x16x32_bf16 v[88:91], v[136:139], v[204:207], v[88:91]
	v_mfma_f32_16x16x32_bf16 v[76:79], v[128:131], v[212:215], v[76:79]
	v_mfma_f32_16x16x32_bf16 v[72:75], v[136:139], v[212:215], v[72:75]
	v_mfma_f32_16x16x32_bf16 v[124:127], v[132:135], v[180:183], v[124:127]
	v_mfma_f32_16x16x32_bf16 v[120:123], v[140:143], v[180:183], v[120:123]
	v_mfma_f32_16x16x32_bf16 v[108:111], v[132:135], v[200:203], v[108:111]
	v_mfma_f32_16x16x32_bf16 v[104:107], v[140:143], v[200:203], v[104:107]
	v_mfma_f32_16x16x32_bf16 v[92:95], v[132:135], v[208:211], v[92:95]
	v_mfma_f32_16x16x32_bf16 v[88:91], v[140:143], v[208:211], v[88:91]
	v_mfma_f32_16x16x32_bf16 v[76:79], v[132:135], v[216:219], v[76:79]
	v_mfma_f32_16x16x32_bf16 v[72:75], v[140:143], v[216:219], v[72:75]
	v_mfma_f32_16x16x32_bf16 v[116:119], v[144:147], v[176:179], v[116:119]
	v_mfma_f32_16x16x32_bf16 v[112:115], v[168:171], v[176:179], v[112:115]
	v_mfma_f32_16x16x32_bf16 v[100:103], v[144:147], v[196:199], v[100:103]
	v_mfma_f32_16x16x32_bf16 v[96:99], v[168:171], v[196:199], v[96:99]
	v_mfma_f32_16x16x32_bf16 v[84:87], v[144:147], v[204:207], v[84:87]
	v_mfma_f32_16x16x32_bf16 v[80:83], v[168:171], v[204:207], v[80:83]
	v_mfma_f32_16x16x32_bf16 v[68:71], v[144:147], v[212:215], v[68:71]
	v_mfma_f32_16x16x32_bf16 v[64:67], v[168:171], v[212:215], v[64:67]
	v_mfma_f32_16x16x32_bf16 v[116:119], v[148:151], v[180:183], v[116:119]
	v_mfma_f32_16x16x32_bf16 v[112:115], v[172:175], v[180:183], v[112:115]
	v_mfma_f32_16x16x32_bf16 v[100:103], v[148:151], v[200:203], v[100:103]
	v_mfma_f32_16x16x32_bf16 v[96:99], v[172:175], v[200:203], v[96:99]
	v_mfma_f32_16x16x32_bf16 v[84:87], v[148:151], v[208:211], v[84:87]
	v_mfma_f32_16x16x32_bf16 v[80:83], v[172:175], v[208:211], v[80:83]
	v_mfma_f32_16x16x32_bf16 v[68:71], v[148:151], v[216:219], v[68:71]
	v_mfma_f32_16x16x32_bf16 v[64:67], v[172:175], v[216:219], v[64:67]
	s_barrier
; #define PG8_STAGE(bufoff, gbase, voff) do { _Pragma("unroll") for (int _i = 0; _i < 2; ++_i) \
;         __builtin_amdgcn_global_load_lds((const unsigned*)((const char*)(gbase) + (voff)[_i]), (PG8_LAS unsigned*)(lds + (bufoff) + ldsw + _i * 8192), 16, 0, 0); } while (0)
; #define PG8_LDA(dst, b, h) do { _Pragma("unroll") for (int m = 0; m < 4; ++m) _Pragma("unroll") for (int k = 0; k < 2; ++k) dst[m][k] = *(const PG8_LAS bf16x8*)(lds + PG8_SA(b, h) + aoff + m * 2048 + k * 1024); } while (0)
; #define PG8_MMA(ai, bj, At, Bt) do { __builtin_amdgcn_s_setprio(1); _Pragma("unroll") for (int m = 0; m < 4; ++m) _Pragma("unroll") for (int n = 0; n < 2; ++n) _Pragma("unroll") for (int k = 0; k < 2; ++k) \
;         acc[ai][bj][m][n] = __builtin_amdgcn_mfma_f32_16x16x32_bf16(Bt[n][k], At[m][k], acc[ai][bj][m][n], 0, 0, 0); __builtin_amdgcn_s_setprio(0); } while (0)
; #define PG8_WAIT_V(n) asm volatile("s_waitcnt vmcnt(" #n ")" ::: "memory")
; #define PG8_WAIT_L(n) asm volatile("s_waitcnt lgkmcnt(" #n ")" ::: "memory")
; #define PG8_BAR __builtin_amdgcn_s_barrier()
; #define PG8_SCHED __builtin_amdgcn_sched_barrier(0)
; template <class Epi, class Sched, bool ALIGN_EPI = false, bool SP2 = false>
; __device__ __forceinline__ void gemm_phase(PG8_LAS unsigned char* lds, const Gemm g, const Sched& S, const Epi& E) {
;     ...
;             PG8_LDA(At, 1, 1); PG8_STAGE(PG8_SB(1, 0), b3, voffB); PG8_STAGE(PG8_SB(1, 1), b3 + hstepB, voffB); PG8_STAGE(PG8_SA(1, 0), a3, voffA);
;             PG8_WAIT_V(8); PG8_WAIT_L(0); PG8_BAR; PG8_MMA(1, 0, At, B0); PG8_MMA(1, 1, At, B1); PG8_BAR; PG8_SCHED;
	s_setprio 0
	s_add_i32 s36, s58, s39
	v_lshl_add_u64 v[184:185], v[184:185], 0, s[14:15]
	s_mov_b32 m0, s36
	ds_read_b128 v[176:179], v193 offset:49152
	ds_read_b128 v[180:183], v193 offset:50176
	ds_read_b128 v[196:199], v193 offset:51200
	ds_read_b128 v[200:203], v193 offset:52224
	ds_read_b128 v[204:207], v193 offset:53248
	ds_read_b128 v[208:211], v193 offset:54272
	ds_read_b128 v[212:215], v193 offset:55296
	ds_read_b128 v[216:219], v193 offset:56320
	global_load_lds_dwordx4 v[184:185], off
	s_add_i32 m0, s36, 0x2000
	s_add_u32 s34, s34, 0x40080
	v_lshl_add_u64 v[184:185], v[220:221], 0, s[14:15]
	s_addc_u32 s35, s35, 0
	s_add_i32 s36, s59, s39
	global_load_lds_dwordx4 v[184:185], off
	v_lshl_add_u64 v[184:185], s[34:35], 0, v[154:155]
	s_mov_b32 m0, s36
	s_nop 0
	global_load_lds_dwordx4 v[184:185], off
	v_lshl_add_u64 v[184:185], s[34:35], 0, v[158:159]
	s_add_i32 m0, s36, 0x2000
	s_nop 0
	global_load_lds_dwordx4 v[184:185], off
	v_lshl_add_u64 v[184:185], v[222:223], 0, s[14:15]
	s_mov_b32 m0, s44
	s_nop 0
	global_load_lds_dwordx4 v[184:185], off
	v_lshl_add_u64 v[184:185], v[224:225], 0, s[14:15]
	s_mov_b32 m0, s45
	s_nop 0
	global_load_lds_dwordx4 v[184:185], off
	s_waitcnt vmcnt(8) lgkmcnt(0)
	s_barrier
	v_mfma_f32_16x16x32_bf16 v[60:63], v[128:131], v[176:179], v[60:63]
	s_setprio 1
	v_mfma_f32_16x16x32_bf16 v[56:59], v[136:139], v[176:179], v[56:59]
	v_mfma_f32_16x16x32_bf16 v[44:47], v[128:131], v[196:199], v[44:47]
	v_mfma_f32_16x16x32_bf16 v[40:43], v[136:139], v[196:199], v[40:43]
	v_mfma_f32_16x16x32_bf16 v[28:31], v[128:131], v[204:207], v[28:31]
	v_mfma_f32_16x16x32_bf16 v[24:27], v[136:139], v[204:207], v[24:27]
	v_mfma_f32_16x16x32_bf16 v[12:15], v[128:131], v[212:215], v[12:15]
	v_mfma_f32_16x16x32_bf16 v[8:11], v[136:139], v[212:215], v[8:11]
	v_mfma_f32_16x16x32_bf16 v[60:63], v[132:135], v[180:183], v[60:63]
	v_mfma_f32_16x16x32_bf16 v[56:59], v[140:143], v[180:183], v[56:59]
	v_mfma_f32_16x16x32_bf16 v[44:47], v[132:135], v[200:203], v[44:47]
	v_mfma_f32_16x16x32_bf16 v[40:43], v[140:143], v[200:203], v[40:43]
	v_mfma_f32_16x16x32_bf16 v[28:31], v[132:135], v[208:211], v[28:31]
	v_mfma_f32_16x16x32_bf16 v[24:27], v[140:143], v[208:211], v[24:27]
	v_mfma_f32_16x16x32_bf16 v[12:15], v[132:135], v[216:219], v[12:15]
	v_mfma_f32_16x16x32_bf16 v[8:11], v[140:143], v[216:219], v[8:11]
	v_mfma_f32_16x16x32_bf16 v[52:55], v[144:147], v[176:179], v[52:55]
	v_mfma_f32_16x16x32_bf16 v[48:51], v[168:171], v[176:179], v[48:51]
	v_mfma_f32_16x16x32_bf16 v[36:39], v[144:147], v[196:199], v[36:39]
	v_mfma_f32_16x16x32_bf16 v[32:35], v[168:171], v[196:199], v[32:35]
	v_mfma_f32_16x16x32_bf16 v[20:23], v[144:147], v[204:207], v[20:23]
	v_mfma_f32_16x16x32_bf16 v[16:19], v[168:171], v[204:207], v[16:19]
	v_mfma_f32_16x16x32_bf16 v[4:7], v[144:147], v[212:215], v[4:7]
	v_mfma_f32_16x16x32_bf16 v[0:3], v[168:171], v[212:215], v[0:3]
	v_mfma_f32_16x16x32_bf16 v[52:55], v[148:151], v[180:183], v[52:55]
	v_mfma_f32_16x16x32_bf16 v[48:51], v[172:175], v[180:183], v[48:51]
	v_mfma_f32_16x16x32_bf16 v[36:39], v[148:151], v[200:203], v[36:39]
	v_mfma_f32_16x16x32_bf16 v[32:35], v[172:175], v[200:203], v[32:35]
	v_mfma_f32_16x16x32_bf16 v[20:23], v[148:151], v[208:211], v[20:23]
	v_mfma_f32_16x16x32_bf16 v[16:19], v[172:175], v[208:211], v[16:19]
	v_mfma_f32_16x16x32_bf16 v[4:7], v[148:151], v[216:219], v[4:7]
	v_mfma_f32_16x16x32_bf16 v[0:3], v[172:175], v[216:219], v[0:3]
	s_barrier
	s_setprio 0
	s_add_i32 s74, s74, 2
	s_add_u32 s30, s30, 0x100
	s_addc_u32 s31, s31, 0
	s_add_u32 s69, s69, 0x100
	s_addc_u32 s73, s73, 0
	s_cmp_gt_u32 s74, 13
	s_cbranch_scc0 .LBB0_971
	s_and_b64 vcc, exec, s[16:17]
	s_cbranch_vccz .LBB0_974
	s_barrier

; #define PG8_STAGE(bufoff, gbase, voff) do { _Pragma("unroll") for (int _i = 0; _i < 2; ++_i) \
;         __builtin_amdgcn_global_load_lds((const unsigned*)((const char*)(gbase) + (voff)[_i]), (PG8_LAS unsigned*)(lds + (bufoff) + ldsw + _i * 8192), 16, 0, 0); } while (0)
; #define PG8_LDA(dst, b, h) do { _Pragma("unroll") for (int m = 0; m < 4; ++m) _Pragma("unroll") for (int k = 0; k < 2; ++k) dst[m][k] = *(const PG8_LAS bf16x8*)(lds + PG8_SA(b, h) + aoff + m * 2048 + k * 1024); } while (0)
; #define PG8_LDB(dst, b, h) do { _Pragma("unroll") for (int n = 0; n < 2; ++n) _Pragma("unroll") for (int k = 0; k < 2; ++k) dst[n][k] = *(const PG8_LAS bf16x8*)(lds + PG8_SB(b, h) + boff + n * 2048 + k * 1024); } while (0)
; #define PG8_MMA(ai, bj, At, Bt) do { __builtin_amdgcn_s_setprio(1); _Pragma("unroll") for (int m = 0; m < 4; ++m) _Pragma("unroll") for (int n = 0; n < 2; ++n) _Pragma("unroll") for (int k = 0; k < 2; ++k) \
;         acc[ai][bj][m][n] = __builtin_amdgcn_mfma_f32_16x16x32_bf16(Bt[n][k], At[m][k], acc[ai][bj][m][n], 0, 0, 0); __builtin_amdgcn_s_setprio(0); } while (0)
; #define PG8_WAIT_V(n) asm volatile("s_waitcnt vmcnt(" #n ")" ::: "memory")
; #define PG8_BAR __builtin_amdgcn_s_barrier()
; template <class Epi, class Sched, bool ALIGN_EPI = false, bool SP2 = false>
; __device__ __forceinline__ void gemm_phase(PG8_LAS unsigned char* lds, const Gemm g, const Sched& S, const Epi& E) {
;     ...
;         for (int t = 0; t < nt; t += 2) {
;             const bool last = (t == nt - 2);
;             const char* a1 = cA + (size_t)(t + 1) * kstep;
;             const char* a2 = last ? nA : cA + (size_t)(t + 2) * kstep; const char* b2 = last ? nB : cB + (size_t)(t + 2) * kstep;
;             const char* a3 = a2 + kstep; const char* b3 = b2 + kstep;
;             if (last && has_next) S.a_ready(nxt);
;             if constexpr (SP2) {
;             PG8_LDB(B0, 0, 0); PG8_LDB(B1, 0, 1); PG8_SCHED; PG8_LDA(At, 0, 0); PG8_STAGE(PG8_SA(1, 1), a1 + hstepA, voffA);
;             PG8_WAIT_V(8); PG8_WAIT_L(0); PG8_BAR; PG8_MMA(0, 0, At, B0); PG8_MMA(0, 1, At, B1); PG8_BAR; PG8_SCHED;
;             PG8_LDA(At, 0, 1); PG8_STAGE(PG8_SB(0, 0), b2, voffB); PG8_STAGE(PG8_SB(0, 1), b2 + hstepB, voffB); PG8_STAGE(PG8_SA(0, 0), a2, voffA);
;             PG8_WAIT_V(8); PG8_WAIT_L(0); PG8_BAR; PG8_MMA(1, 0, At, B0); PG8_MMA(1, 1, At, B1); PG8_BAR; PG8_SCHED;
.LBB0_1055:
	ds_read_b128 v[144:147], v153
	ds_read_b128 v[158:161], v153 offset:1024
	ds_read_b128 v[162:165], v153 offset:2048
	ds_read_b128 v[166:169], v153 offset:3072
	ds_read_b128 v[170:173], v154
	ds_read_b128 v[174:177], v154 offset:1024
	ds_read_b128 v[178:181], v154 offset:2048
	ds_read_b128 v[182:185], v154 offset:3072
	s_add_u32 s28, s26, 0xfffc0080
	s_addc_u32 s29, s27, -1
	s_cmp_eq_u32 s69, 12
	s_cselect_b32 s31, s19, s29
	s_cselect_b32 s30, s49, s28
	s_cselect_b32 s29, s17, s68
	s_cselect_b32 s28, s66, s67
	v_lshl_add_u64 v[148:149], s[26:27], 0, v[136:137]
	s_add_i32 m0, s25, 0xc000
	ds_read_b128 v[188:191], v155
	ds_read_b128 v[192:195], v155 offset:1024
	ds_read_b128 v[196:199], v155 offset:2048
	ds_read_b128 v[200:203], v155 offset:3072
	ds_read_b128 v[204:207], v155 offset:4096
	ds_read_b128 v[208:211], v155 offset:5120
	ds_read_b128 v[212:215], v155 offset:6144
	ds_read_b128 v[216:219], v155 offset:7168
	global_load_lds_dwordx4 v[148:149], off
	v_lshl_add_u64 v[148:149], s[26:27], 0, v[138:139]
	s_add_i32 m0, s25, 0xe000
	s_nop 0
	global_load_lds_dwordx4 v[148:149], off
	s_waitcnt vmcnt(8) lgkmcnt(0)
	s_barrier
	v_mfma_f32_16x16x32_bf16 v[116:119], v[144:147], v[188:191], v[116:119]
	s_setprio 1
	v_mfma_f32_16x16x32_bf16 v[112:115], v[162:165], v[188:191], v[112:115]
	v_mfma_f32_16x16x32_bf16 v[108:111], v[144:147], v[196:199], v[108:111]
	v_mfma_f32_16x16x32_bf16 v[100:103], v[162:165], v[196:199], v[100:103]
	v_mfma_f32_16x16x32_bf16 v[92:95], v[144:147], v[204:207], v[92:95]
	v_mfma_f32_16x16x32_bf16 v[84:87], v[162:165], v[204:207], v[84:87]
	v_mfma_f32_16x16x32_bf16 v[76:79], v[144:147], v[212:215], v[76:79]
	v_mfma_f32_16x16x32_bf16 v[68:71], v[162:165], v[212:215], v[68:71]
	v_mfma_f32_16x16x32_bf16 v[116:119], v[158:161], v[192:195], v[116:119]
	v_mfma_f32_16x16x32_bf16 v[112:115], v[166:169], v[192:195], v[112:115]
	v_mfma_f32_16x16x32_bf16 v[108:111], v[158:161], v[200:203], v[108:111]
	v_mfma_f32_16x16x32_bf16 v[100:103], v[166:169], v[200:203], v[100:103]
	v_mfma_f32_16x16x32_bf16 v[92:95], v[158:161], v[208:211], v[92:95]
	v_mfma_f32_16x16x32_bf16 v[84:87], v[166:169], v[208:211], v[84:87]
	v_mfma_f32_16x16x32_bf16 v[76:79], v[158:161], v[216:219], v[76:79]
	v_mfma_f32_16x16x32_bf16 v[68:71], v[166:169], v[216:219], v[68:71]
	v_mfma_f32_16x16x32_bf16 v[124:127], v[170:173], v[188:191], v[124:127]
	v_mfma_f32_16x16x32_bf16 v[120:123], v[178:181], v[188:191], v[120:123]
	v_mfma_f32_16x16x32_bf16 v[104:107], v[170:173], v[196:199], v[104:107]
	v_mfma_f32_16x16x32_bf16 v[96:99], v[178:181], v[196:199], v[96:99]
	v_mfma_f32_16x16x32_bf16 v[88:91], v[170:173], v[204:207], v[88:91]
	v_mfma_f32_16x16x32_bf16 v[80:83], v[178:181], v[204:207], v[80:83]
	v_mfma_f32_16x16x32_bf16 v[72:75], v[170:173], v[212:215], v[72:75]
	v_mfma_f32_16x16x32_bf16 v[64:67], v[178:181], v[212:215], v[64:67]
	v_mfma_f32_16x16x32_bf16 v[124:127], v[174:177], v[192:195], v[124:127]
	v_mfma_f32_16x16x32_bf16 v[120:123], v[182:185], v[192:195], v[120:123]
	v_mfma_f32_16x16x32_bf16 v[104:107], v[174:177], v[200:203], v[104:107]
	v_mfma_f32_16x16x32_bf16 v[96:99], v[182:185], v[200:203], v[96:99]
	v_mfma_f32_16x16x32_bf16 v[88:91], v[174:177], v[208:211], v[88:91]
	v_mfma_f32_16x16x32_bf16 v[80:83], v[182:185], v[208:211], v[80:83]
	v_mfma_f32_16x16x32_bf16 v[72:75], v[174:177], v[216:219], v[72:75]
	v_mfma_f32_16x16x32_bf16 v[64:67], v[182:185], v[216:219], v[64:67]
	s_barrier
	s_setprio 0
	s_add_i32 s58, s45, s35
	v_lshl_add_u64 v[148:149], s[28:29], 0, v[132:133]
	s_mov_b32 m0, s58
	ds_read_b128 v[188:191], v155 offset:16384
	ds_read_b128 v[192:195], v155 offset:17408
	ds_read_b128 v[196:199], v155 offset:18432
	ds_read_b128 v[200:203], v155 offset:19456
	ds_read_b128 v[204:207], v155 offset:20480
	ds_read_b128 v[208:211], v155 offset:21504
	ds_read_b128 v[212:215], v155 offset:22528
	ds_read_b128 v[216:219], v155 offset:23552
	global_load_lds_dwordx4 v[148:149], off
	s_add_i32 m0, s58, 0x2000
	s_add_u32 s58, s28, 0x40000
	v_lshl_add_u64 v[220:221], s[28:29], 0, v[128:129]
	s_addc_u32 s59, s29, 0
	s_add_i32 s73, s46, s35
	global_load_lds_dwordx4 v[220:221], off
	v_lshl_add_u64 v[222:223], s[58:59], 0, v[132:133]
	s_mov_b32 m0, s73
	v_lshl_add_u64 v[224:225], s[30:31], 0, v[130:131]
	global_load_lds_dwordx4 v[222:223], off
	v_lshl_add_u64 v[222:223], s[58:59], 0, v[128:129]
	s_add_i32 m0, s73, 0x2000
	s_nop 0
	global_load_lds_dwordx4 v[222:223], off
	v_lshl_add_u64 v[222:223], s[30:31], 0, v[134:135]
	s_mov_b32 m0, s25
	s_nop 0
	global_load_lds_dwordx4 v[222:223], off
	s_mov_b32 m0, s38
	s_nop 0
	global_load_lds_dwordx4 v[224:225], off
	s_waitcnt vmcnt(8) lgkmcnt(0)
	s_barrier
; #define PG8_STAGE(bufoff, gbase, voff) do { _Pragma("unroll") for (int _i = 0; _i < 2; ++_i) \
;         __builtin_amdgcn_global_load_lds((const unsigned*)((const char*)(gbase) + (voff)[_i]), (PG8_LAS unsigned*)(lds + (bufoff) + ldsw + _i * 8192), 16, 0, 0); } while (0)
; #define PG8_LDA(dst, b, h) do { _Pragma("unroll") for (int m = 0; m < 4; ++m) _Pragma("unroll") for (int k = 0; k < 2; ++k) dst[m][k] = *(const PG8_LAS bf16x8*)(lds + PG8_SA(b, h) + aoff + m * 2048 + k * 1024); } while (0)
; #define PG8_LDB(dst, b, h) do { _Pragma("unroll") for (int n = 0; n < 2; ++n) _Pragma("unroll") for (int k = 0; k < 2; ++k) dst[n][k] = *(const PG8_LAS bf16x8*)(lds + PG8_SB(b, h) + boff + n * 2048 + k * 1024); } while (0)
; #define PG8_MMA(ai, bj, At, Bt) do { __builtin_amdgcn_s_setprio(1); _Pragma("unroll") for (int m = 0; m < 4; ++m) _Pragma("unroll") for (int n = 0; n < 2; ++n) _Pragma("unroll") for (int k = 0; k < 2; ++k) \
;         acc[ai][bj][m][n] = __builtin_amdgcn_mfma_f32_16x16x32_bf16(Bt[n][k], At[m][k], acc[ai][bj][m][n], 0, 0, 0); __builtin_amdgcn_s_setprio(0); } while (0)
; #define PG8_WAIT_V(n) asm volatile("s_waitcnt vmcnt(" #n ")" ::: "memory")
; #define PG8_WAIT_L(n) asm volatile("s_waitcnt lgkmcnt(" #n ")" ::: "memory")
; #define PG8_BAR __builtin_amdgcn_s_barrier()
; #define PG8_SCHED __builtin_amdgcn_sched_barrier(0)
; template <class Epi, class Sched, bool ALIGN_EPI = false, bool SP2 = false>
; __device__ __forceinline__ void gemm_phase(PG8_LAS unsigned char* lds, const Gemm g, const Sched& S, const Epi& E) {
;     ...
;             PG8_WAIT_V(8); PG8_WAIT_L(0); PG8_BAR; PG8_MMA(1, 0, At, B0); PG8_MMA(1, 1, At, B1); PG8_BAR; PG8_SCHED;
;             PG8_LDB(B0, 1, 0); PG8_LDB(B1, 1, 1); PG8_SCHED; PG8_LDA(At, 1, 0); PG8_STAGE(PG8_SA(0, 1), a2 + hstepA, voffA);
;             PG8_WAIT_V(8); PG8_WAIT_L(0); PG8_BAR; PG8_MMA(0, 0, At, B0); PG8_MMA(0, 1, At, B1); PG8_BAR; PG8_SCHED;
	v_mfma_f32_16x16x32_bf16 v[60:63], v[144:147], v[188:191], v[60:63]
	s_setprio 1
	v_mfma_f32_16x16x32_bf16 v[52:55], v[162:165], v[188:191], v[52:55]
	v_mfma_f32_16x16x32_bf16 v[44:47], v[144:147], v[196:199], v[44:47]
	v_mfma_f32_16x16x32_bf16 v[36:39], v[162:165], v[196:199], v[36:39]
	v_mfma_f32_16x16x32_bf16 v[28:31], v[144:147], v[204:207], v[28:31]
	v_mfma_f32_16x16x32_bf16 v[20:23], v[162:165], v[204:207], v[20:23]
	v_mfma_f32_16x16x32_bf16 v[12:15], v[144:147], v[212:215], v[12:15]
	v_mfma_f32_16x16x32_bf16 v[4:7], v[162:165], v[212:215], v[4:7]
	v_mfma_f32_16x16x32_bf16 v[60:63], v[158:161], v[192:195], v[60:63]
	v_mfma_f32_16x16x32_bf16 v[52:55], v[166:169], v[192:195], v[52:55]
	v_mfma_f32_16x16x32_bf16 v[44:47], v[158:161], v[200:203], v[44:47]
	v_mfma_f32_16x16x32_bf16 v[36:39], v[166:169], v[200:203], v[36:39]
	v_mfma_f32_16x16x32_bf16 v[28:31], v[158:161], v[208:211], v[28:31]
	v_mfma_f32_16x16x32_bf16 v[20:23], v[166:169], v[208:211], v[20:23]
	v_mfma_f32_16x16x32_bf16 v[12:15], v[158:161], v[216:219], v[12:15]
	v_mfma_f32_16x16x32_bf16 v[4:7], v[166:169], v[216:219], v[4:7]
	v_mfma_f32_16x16x32_bf16 v[56:59], v[170:173], v[188:191], v[56:59]
	v_mfma_f32_16x16x32_bf16 v[48:51], v[178:181], v[188:191], v[48:51]
	v_mfma_f32_16x16x32_bf16 v[40:43], v[170:173], v[196:199], v[40:43]
	v_mfma_f32_16x16x32_bf16 v[32:35], v[178:181], v[196:199], v[32:35]
	v_mfma_f32_16x16x32_bf16 v[24:27], v[170:173], v[204:207], v[24:27]
	v_mfma_f32_16x16x32_bf16 v[16:19], v[178:181], v[204:207], v[16:19]
	v_mfma_f32_16x16x32_bf16 v[8:11], v[170:173], v[212:215], v[8:11]
	v_mfma_f32_16x16x32_bf16 v[0:3], v[178:181], v[212:215], v[0:3]
	v_mfma_f32_16x16x32_bf16 v[56:59], v[174:177], v[192:195], v[56:59]
	v_mfma_f32_16x16x32_bf16 v[48:51], v[182:185], v[192:195], v[48:51]
	v_mfma_f32_16x16x32_bf16 v[40:43], v[174:177], v[200:203], v[40:43]
	v_mfma_f32_16x16x32_bf16 v[32:35], v[182:185], v[200:203], v[32:35]
	v_mfma_f32_16x16x32_bf16 v[24:27], v[174:177], v[208:211], v[24:27]
	v_mfma_f32_16x16x32_bf16 v[16:19], v[182:185], v[208:211], v[16:19]
	v_mfma_f32_16x16x32_bf16 v[8:11], v[174:177], v[216:219], v[8:11]
	v_mfma_f32_16x16x32_bf16 v[0:3], v[182:185], v[216:219], v[0:3]
	s_barrier
	s_setprio 0
	s_add_i32 s58, 0, 0x18000
	v_add_u32_e32 v157, s58, v151
	s_add_i32 s59, 0, 0x1c000
	ds_read_b128 v[144:147], v157
	ds_read_b128 v[158:161], v157 offset:1024
	ds_read_b128 v[162:165], v157 offset:2048
	ds_read_b128 v[166:169], v157 offset:3072
	v_add_u32_e32 v157, s59, v151
	ds_read_b128 v[170:173], v157
	ds_read_b128 v[174:177], v157 offset:1024
	ds_read_b128 v[178:181], v157 offset:2048
	ds_read_b128 v[182:185], v157 offset:3072
	s_add_u32 s30, s30, 0x40000
	s_addc_u32 s31, s31, 0
	s_mov_b32 m0, s39
	v_lshl_add_u64 v[226:227], s[30:31], 0, v[134:135]
	ds_read_b128 v[188:191], v155 offset:32768
	ds_read_b128 v[192:195], v155 offset:33792
	ds_read_b128 v[196:199], v155 offset:34816
	ds_read_b128 v[200:203], v155 offset:35840
	ds_read_b128 v[204:207], v155 offset:36864
	ds_read_b128 v[208:211], v155 offset:37888
	ds_read_b128 v[212:215], v155 offset:38912
	ds_read_b128 v[216:219], v155 offset:39936
	global_load_lds_dwordx4 v[226:227], off
	v_lshl_add_u64 v[226:227], s[30:31], 0, v[130:131]
	s_mov_b32 m0, s40
	s_nop 0
	global_load_lds_dwordx4 v[226:227], off
	s_waitcnt vmcnt(8) lgkmcnt(0)
	s_barrier
	v_mfma_f32_16x16x32_bf16 v[116:119], v[144:147], v[188:191], v[116:119]
	s_setprio 1
	v_mfma_f32_16x16x32_bf16 v[112:115], v[162:165], v[188:191], v[112:115]
	v_mfma_f32_16x16x32_bf16 v[108:111], v[144:147], v[196:199], v[108:111]
	v_mfma_f32_16x16x32_bf16 v[100:103], v[162:165], v[196:199], v[100:103]
	v_mfma_f32_16x16x32_bf16 v[92:95], v[144:147], v[204:207], v[92:95]
	v_mfma_f32_16x16x32_bf16 v[84:87], v[162:165], v[204:207], v[84:87]
	v_mfma_f32_16x16x32_bf16 v[76:79], v[144:147], v[212:215], v[76:79]
	v_mfma_f32_16x16x32_bf16 v[68:71], v[162:165], v[212:215], v[68:71]
	v_mfma_f32_16x16x32_bf16 v[116:119], v[158:161], v[192:195], v[116:119]
	v_mfma_f32_16x16x32_bf16 v[112:115], v[166:169], v[192:195], v[112:115]
	v_mfma_f32_16x16x32_bf16 v[108:111], v[158:161], v[200:203], v[108:111]
	v_mfma_f32_16x16x32_bf16 v[100:103], v[166:169], v[200:203], v[100:103]
	v_mfma_f32_16x16x32_bf16 v[92:95], v[158:161], v[208:211], v[92:95]
	v_mfma_f32_16x16x32_bf16 v[84:87], v[166:169], v[208:211], v[84:87]
	v_mfma_f32_16x16x32_bf16 v[76:79], v[158:161], v[216:219], v[76:79]
	v_mfma_f32_16x16x32_bf16 v[68:71], v[166:169], v[216:219], v[68:71]
	v_mfma_f32_16x16x32_bf16 v[124:127], v[170:173], v[188:191], v[124:127]
	v_mfma_f32_16x16x32_bf16 v[120:123], v[178:181], v[188:191], v[120:123]
	v_mfma_f32_16x16x32_bf16 v[104:107], v[170:173], v[196:199], v[104:107]
	v_mfma_f32_16x16x32_bf16 v[96:99], v[178:181], v[196:199], v[96:99]
	v_mfma_f32_16x16x32_bf16 v[88:91], v[170:173], v[204:207], v[88:91]
	v_mfma_f32_16x16x32_bf16 v[80:83], v[178:181], v[204:207], v[80:83]
	v_mfma_f32_16x16x32_bf16 v[72:75], v[170:173], v[212:215], v[72:75]
	v_mfma_f32_16x16x32_bf16 v[64:67], v[178:181], v[212:215], v[64:67]
	v_mfma_f32_16x16x32_bf16 v[124:127], v[174:177], v[192:195], v[124:127]
	v_mfma_f32_16x16x32_bf16 v[120:123], v[182:185], v[192:195], v[120:123]
	v_mfma_f32_16x16x32_bf16 v[104:107], v[174:177], v[200:203], v[104:107]
	v_mfma_f32_16x16x32_bf16 v[96:99], v[182:185], v[200:203], v[96:99]
	v_mfma_f32_16x16x32_bf16 v[88:91], v[174:177], v[208:211], v[88:91]
	v_mfma_f32_16x16x32_bf16 v[80:83], v[182:185], v[208:211], v[80:83]
	v_mfma_f32_16x16x32_bf16 v[72:75], v[174:177], v[216:219], v[72:75]
	v_mfma_f32_16x16x32_bf16 v[64:67], v[182:185], v[216:219], v[64:67]
	s_barrier
; #define PG8_STAGE(bufoff, gbase, voff) do { _Pragma("unroll") for (int _i = 0; _i < 2; ++_i) \
;         __builtin_amdgcn_global_load_lds((const unsigned*)((const char*)(gbase) + (voff)[_i]), (PG8_LAS unsigned*)(lds + (bufoff) + ldsw + _i * 8192), 16, 0, 0); } while (0)
; #define PG8_LDA(dst, b, h) do { _Pragma("unroll") for (int m = 0; m < 4; ++m) _Pragma("unroll") for (int k = 0; k < 2; ++k) dst[m][k] = *(const PG8_LAS bf16x8*)(lds + PG8_SA(b, h) + aoff + m * 2048 + k * 1024); } while (0)
; #define PG8_MMA(ai, bj, At, Bt) do { __builtin_amdgcn_s_setprio(1); _Pragma("unroll") for (int m = 0; m < 4; ++m) _Pragma("unroll") for (int n = 0; n < 2; ++n) _Pragma("unroll") for (int k = 0; k < 2; ++k) \
;         acc[ai][bj][m][n] = __builtin_amdgcn_mfma_f32_16x16x32_bf16(Bt[n][k], At[m][k], acc[ai][bj][m][n], 0, 0, 0); __builtin_amdgcn_s_setprio(0); } while (0)
; #define PG8_WAIT_V(n) asm volatile("s_waitcnt vmcnt(" #n ")" ::: "memory")
; #define PG8_WAIT_L(n) asm volatile("s_waitcnt lgkmcnt(" #n ")" ::: "memory")
; #define PG8_BAR __builtin_amdgcn_s_barrier()
; #define PG8_SCHED __builtin_amdgcn_sched_barrier(0)
; template <class Epi, class Sched, bool ALIGN_EPI = false, bool SP2 = false>
; __device__ __forceinline__ void gemm_phase(PG8_LAS unsigned char* lds, const Gemm g, const Sched& S, const Epi& E) {
;     ...
;             PG8_LDA(At, 1, 1); PG8_STAGE(PG8_SB(1, 0), b3, voffB); PG8_STAGE(PG8_SB(1, 1), b3 + hstepB, voffB); PG8_STAGE(PG8_SA(1, 0), a3, voffA);
;             PG8_WAIT_V(8); PG8_WAIT_L(0); PG8_BAR; PG8_MMA(1, 0, At, B0); PG8_MMA(1, 1, At, B1); PG8_BAR; PG8_SCHED;
;     ...
;         if constexpr (ALIGN_EPI) { if (wr == 0) PG8_BAR; }
	s_setprio 0
	s_add_i32 s30, s58, s35
	v_lshl_add_u64 v[148:149], v[148:149], 0, s[12:13]
	s_mov_b32 m0, s30
	ds_read_b128 v[188:191], v155 offset:49152
	ds_read_b128 v[192:195], v155 offset:50176
	ds_read_b128 v[196:199], v155 offset:51200
	ds_read_b128 v[200:203], v155 offset:52224
	ds_read_b128 v[204:207], v155 offset:53248
	ds_read_b128 v[208:211], v155 offset:54272
	ds_read_b128 v[212:215], v155 offset:55296
	ds_read_b128 v[216:219], v155 offset:56320
	global_load_lds_dwordx4 v[148:149], off
	s_add_i32 m0, s30, 0x2000
	s_add_u32 s28, s28, 0x40080
	v_lshl_add_u64 v[148:149], v[220:221], 0, s[12:13]
	s_addc_u32 s29, s29, 0
	s_add_i32 s30, s59, s35
	global_load_lds_dwordx4 v[148:149], off
	v_lshl_add_u64 v[148:149], s[28:29], 0, v[132:133]
	s_mov_b32 m0, s30
	s_nop 0
	global_load_lds_dwordx4 v[148:149], off
	v_lshl_add_u64 v[148:149], s[28:29], 0, v[128:129]
	s_add_i32 m0, s30, 0x2000
	s_nop 0
	global_load_lds_dwordx4 v[148:149], off
	v_lshl_add_u64 v[148:149], v[222:223], 0, s[12:13]
	s_mov_b32 m0, s42
	s_nop 0
	global_load_lds_dwordx4 v[148:149], off
	v_lshl_add_u64 v[148:149], v[224:225], 0, s[12:13]
	s_mov_b32 m0, s43
	s_nop 0
	global_load_lds_dwordx4 v[148:149], off
	s_waitcnt vmcnt(8) lgkmcnt(0)
	s_barrier
	v_mfma_f32_16x16x32_bf16 v[60:63], v[144:147], v[188:191], v[60:63]
	s_setprio 1
	v_mfma_f32_16x16x32_bf16 v[52:55], v[162:165], v[188:191], v[52:55]
	v_mfma_f32_16x16x32_bf16 v[44:47], v[144:147], v[196:199], v[44:47]
	v_mfma_f32_16x16x32_bf16 v[36:39], v[162:165], v[196:199], v[36:39]
	v_mfma_f32_16x16x32_bf16 v[28:31], v[144:147], v[204:207], v[28:31]
	v_mfma_f32_16x16x32_bf16 v[20:23], v[162:165], v[204:207], v[20:23]
	v_mfma_f32_16x16x32_bf16 v[12:15], v[144:147], v[212:215], v[12:15]
	v_mfma_f32_16x16x32_bf16 v[4:7], v[162:165], v[212:215], v[4:7]
	v_mfma_f32_16x16x32_bf16 v[60:63], v[158:161], v[192:195], v[60:63]
	v_mfma_f32_16x16x32_bf16 v[52:55], v[166:169], v[192:195], v[52:55]
	v_mfma_f32_16x16x32_bf16 v[44:47], v[158:161], v[200:203], v[44:47]
	v_mfma_f32_16x16x32_bf16 v[36:39], v[166:169], v[200:203], v[36:39]
	v_mfma_f32_16x16x32_bf16 v[28:31], v[158:161], v[208:211], v[28:31]
	v_mfma_f32_16x16x32_bf16 v[20:23], v[166:169], v[208:211], v[20:23]
	v_mfma_f32_16x16x32_bf16 v[12:15], v[158:161], v[216:219], v[12:15]
	v_mfma_f32_16x16x32_bf16 v[4:7], v[166:169], v[216:219], v[4:7]
	v_mfma_f32_16x16x32_bf16 v[56:59], v[170:173], v[188:191], v[56:59]
	v_mfma_f32_16x16x32_bf16 v[48:51], v[178:181], v[188:191], v[48:51]
	v_mfma_f32_16x16x32_bf16 v[40:43], v[170:173], v[196:199], v[40:43]
	v_mfma_f32_16x16x32_bf16 v[32:35], v[178:181], v[196:199], v[32:35]
	v_mfma_f32_16x16x32_bf16 v[24:27], v[170:173], v[204:207], v[24:27]
	v_mfma_f32_16x16x32_bf16 v[16:19], v[178:181], v[204:207], v[16:19]
	v_mfma_f32_16x16x32_bf16 v[8:11], v[170:173], v[212:215], v[8:11]
	v_mfma_f32_16x16x32_bf16 v[0:3], v[178:181], v[212:215], v[0:3]
	v_mfma_f32_16x16x32_bf16 v[56:59], v[174:177], v[192:195], v[56:59]
	v_mfma_f32_16x16x32_bf16 v[48:51], v[182:185], v[192:195], v[48:51]
	v_mfma_f32_16x16x32_bf16 v[40:43], v[174:177], v[200:203], v[40:43]
	v_mfma_f32_16x16x32_bf16 v[32:35], v[182:185], v[200:203], v[32:35]
	v_mfma_f32_16x16x32_bf16 v[24:27], v[174:177], v[208:211], v[24:27]
	v_mfma_f32_16x16x32_bf16 v[16:19], v[182:185], v[208:211], v[16:19]
	v_mfma_f32_16x16x32_bf16 v[8:11], v[174:177], v[216:219], v[8:11]
	v_mfma_f32_16x16x32_bf16 v[0:3], v[182:185], v[216:219], v[0:3]
	s_barrier
	s_setprio 0
	s_add_i32 s69, s69, 2
	s_add_u32 s26, s26, 0x100
	s_addc_u32 s27, s27, 0
	s_add_u32 s67, s67, 0x100
	s_addc_u32 s68, s68, 0
	s_cmp_gt_u32 s69, 13
	s_cbranch_scc0 .LBB0_1055
	s_and_b64 vcc, exec, s[14:15]
	s_cbranch_vccz .LBB0_1058
	s_barrier

; #define PG8_STAGE(bufoff, gbase, voff) do { _Pragma("unroll") for (int _i = 0; _i < 2; ++_i) \
;         __builtin_amdgcn_global_load_lds((const unsigned*)((const char*)(gbase) + (voff)[_i]), (PG8_LAS unsigned*)(lds + (bufoff) + ldsw + _i * 8192), 16, 0, 0); } while (0)
; #define PG8_LDA(dst, b, h) do { _Pragma("unroll") for (int m = 0; m < 4; ++m) _Pragma("unroll") for (int k = 0; k < 2; ++k) dst[m][k] = *(const PG8_LAS bf16x8*)(lds + PG8_SA(b, h) + aoff + m * 2048 + k * 1024); } while (0)
; #define PG8_LDB(dst, b, h) do { _Pragma("unroll") for (int n = 0; n < 2; ++n) _Pragma("unroll") for (int k = 0; k < 2; ++k) dst[n][k] = *(const PG8_LAS bf16x8*)(lds + PG8_SB(b, h) + boff + n * 2048 + k * 1024); } while (0)
; #define PG8_MMA(ai, bj, At, Bt) do { __builtin_amdgcn_s_setprio(1); _Pragma("unroll") for (int m = 0; m < 4; ++m) _Pragma("unroll") for (int n = 0; n < 2; ++n) _Pragma("unroll") for (int k = 0; k < 2; ++k) \
;         acc[ai][bj][m][n] = __builtin_amdgcn_mfma_f32_16x16x32_bf16(Bt[n][k], At[m][k], acc[ai][bj][m][n], 0, 0, 0); __builtin_amdgcn_s_setprio(0); } while (0)
; #define PG8_WAIT_V(n) asm volatile("s_waitcnt vmcnt(" #n ")" ::: "memory")
; #define PG8_WAIT_L(n) asm volatile("s_waitcnt lgkmcnt(" #n ")" ::: "memory")
; #define PG8_BAR __builtin_amdgcn_s_barrier()
; #define PG8_SCHED __builtin_amdgcn_sched_barrier(0)
; template <class Epi, class Sched, bool ALIGN_EPI = false, bool SP2 = false>
; __device__ __forceinline__ void gemm_phase(PG8_LAS unsigned char* lds, const Gemm g, const Sched& S, const Epi& E) {
;     ...
;             const bool last = (t == nt - 2);
;             const char* a1 = cA + (size_t)(t + 1) * kstep;
;             const char* a2 = last ? nA : cA + (size_t)(t + 2) * kstep; const char* b2 = last ? nB : cB + (size_t)(t + 2) * kstep;
;             const char* a3 = a2 + kstep; const char* b3 = b2 + kstep;
;             if (last && has_next) S.a_ready(nxt);
;             if constexpr (SP2) {
;             PG8_LDB(B0, 0, 0); PG8_LDB(B1, 0, 1); PG8_SCHED; PG8_LDA(At, 0, 0); PG8_STAGE(PG8_SA(1, 1), a1 + hstepA, voffA);
;             PG8_WAIT_V(8); PG8_WAIT_L(0); PG8_BAR; PG8_MMA(0, 0, At, B0); PG8_MMA(0, 1, At, B1); PG8_BAR; PG8_SCHED;
;             PG8_LDA(At, 0, 1); PG8_STAGE(PG8_SB(0, 0), b2, voffB); PG8_STAGE(PG8_SB(0, 1), b2 + hstepB, voffB); PG8_STAGE(PG8_SA(0, 0), a2, voffA);
.LBB0_1129:
	ds_read_b128 v[128:131], v191
	ds_read_b128 v[132:135], v191 offset:1024
	ds_read_b128 v[136:139], v191 offset:2048
	ds_read_b128 v[140:143], v191 offset:3072
	ds_read_b128 v[144:147], v192
	ds_read_b128 v[148:151], v192 offset:1024
	ds_read_b128 v[168:171], v192 offset:2048
	ds_read_b128 v[172:175], v192 offset:3072
	s_add_u32 s24, s22, 0x100
	s_addc_u32 s25, s23, 0
	s_cmp_eq_u32 s69, 40
	s_cselect_b32 s29, s11, s25
	s_cselect_b32 s28, s10, s24
	s_cselect_b32 s27, s21, s68
	s_cselect_b32 s26, s20, s67
	v_lshl_add_u64 v[184:185], s[22:23], 0, v[160:161]
	s_add_i32 m0, s34, 0xc000
	ds_read_b128 v[176:179], v193
	ds_read_b128 v[180:183], v193 offset:1024
	ds_read_b128 v[196:199], v193 offset:2048
	ds_read_b128 v[200:203], v193 offset:3072
	ds_read_b128 v[204:207], v193 offset:4096
	ds_read_b128 v[208:211], v193 offset:5120
	ds_read_b128 v[212:215], v193 offset:6144
	ds_read_b128 v[216:219], v193 offset:7168
	global_load_lds_dwordx4 v[184:185], off
	v_lshl_add_u64 v[184:185], s[22:23], 0, v[162:163]
	s_add_i32 m0, s34, 0xe000
	s_nop 0
	global_load_lds_dwordx4 v[184:185], off
	s_waitcnt vmcnt(8) lgkmcnt(0)
	s_barrier
	v_mfma_f32_16x16x32_bf16 v[124:127], v[128:131], v[176:179], v[124:127]
	s_setprio 1
	v_mfma_f32_16x16x32_bf16 v[120:123], v[136:139], v[176:179], v[120:123]
	v_mfma_f32_16x16x32_bf16 v[108:111], v[128:131], v[196:199], v[108:111]
	v_mfma_f32_16x16x32_bf16 v[104:107], v[136:139], v[196:199], v[104:107]
	v_mfma_f32_16x16x32_bf16 v[92:95], v[128:131], v[204:207], v[92:95]
	v_mfma_f32_16x16x32_bf16 v[88:91], v[136:139], v[204:207], v[88:91]
	v_mfma_f32_16x16x32_bf16 v[76:79], v[128:131], v[212:215], v[76:79]
	v_mfma_f32_16x16x32_bf16 v[72:75], v[136:139], v[212:215], v[72:75]
	v_mfma_f32_16x16x32_bf16 v[124:127], v[132:135], v[180:183], v[124:127]
	v_mfma_f32_16x16x32_bf16 v[120:123], v[140:143], v[180:183], v[120:123]
	v_mfma_f32_16x16x32_bf16 v[108:111], v[132:135], v[200:203], v[108:111]
	v_mfma_f32_16x16x32_bf16 v[104:107], v[140:143], v[200:203], v[104:107]
	v_mfma_f32_16x16x32_bf16 v[92:95], v[132:135], v[208:211], v[92:95]
	v_mfma_f32_16x16x32_bf16 v[88:91], v[140:143], v[208:211], v[88:91]
	v_mfma_f32_16x16x32_bf16 v[76:79], v[132:135], v[216:219], v[76:79]
	v_mfma_f32_16x16x32_bf16 v[72:75], v[140:143], v[216:219], v[72:75]
	v_mfma_f32_16x16x32_bf16 v[116:119], v[144:147], v[176:179], v[116:119]
	v_mfma_f32_16x16x32_bf16 v[112:115], v[168:171], v[176:179], v[112:115]
	v_mfma_f32_16x16x32_bf16 v[100:103], v[144:147], v[196:199], v[100:103]
	v_mfma_f32_16x16x32_bf16 v[96:99], v[168:171], v[196:199], v[96:99]
	v_mfma_f32_16x16x32_bf16 v[84:87], v[144:147], v[204:207], v[84:87]
	v_mfma_f32_16x16x32_bf16 v[80:83], v[168:171], v[204:207], v[80:83]
	v_mfma_f32_16x16x32_bf16 v[68:71], v[144:147], v[212:215], v[68:71]
	v_mfma_f32_16x16x32_bf16 v[64:67], v[168:171], v[212:215], v[64:67]
	v_mfma_f32_16x16x32_bf16 v[116:119], v[148:151], v[180:183], v[116:119]
	v_mfma_f32_16x16x32_bf16 v[112:115], v[172:175], v[180:183], v[112:115]
	v_mfma_f32_16x16x32_bf16 v[100:103], v[148:151], v[200:203], v[100:103]
	v_mfma_f32_16x16x32_bf16 v[96:99], v[172:175], v[200:203], v[96:99]
	v_mfma_f32_16x16x32_bf16 v[84:87], v[148:151], v[208:211], v[84:87]
	v_mfma_f32_16x16x32_bf16 v[80:83], v[172:175], v[208:211], v[80:83]
	v_mfma_f32_16x16x32_bf16 v[68:71], v[148:151], v[216:219], v[68:71]
	v_mfma_f32_16x16x32_bf16 v[64:67], v[172:175], v[216:219], v[64:67]
	s_barrier
	s_setprio 0
	s_add_i32 s22, s44, s31
	v_lshl_add_u64 v[184:185], s[26:27], 0, v[154:155]
	s_mov_b32 m0, s22
	ds_read_b128 v[176:179], v193 offset:16384
	ds_read_b128 v[180:183], v193 offset:17408
	ds_read_b128 v[196:199], v193 offset:18432
	ds_read_b128 v[200:203], v193 offset:19456
	ds_read_b128 v[204:207], v193 offset:20480
	ds_read_b128 v[208:211], v193 offset:21504
	ds_read_b128 v[212:215], v193 offset:22528
	ds_read_b128 v[216:219], v193 offset:23552
	global_load_lds_dwordx4 v[184:185], off
	s_add_i32 m0, s22, 0x2000
	s_add_u32 s22, s26, 0xb0000
	v_lshl_add_u64 v[220:221], s[26:27], 0, v[158:159]
	s_addc_u32 s23, s27, 0
	s_add_i32 s58, s45, s31
	global_load_lds_dwordx4 v[220:221], off
	v_lshl_add_u64 v[222:223], s[22:23], 0, v[154:155]
	s_mov_b32 m0, s58
	v_lshl_add_u64 v[224:225], s[28:29], 0, v[156:157]
	global_load_lds_dwordx4 v[222:223], off
	v_lshl_add_u64 v[222:223], s[22:23], 0, v[158:159]
	s_add_i32 m0, s58, 0x2000
	s_nop 0
	global_load_lds_dwordx4 v[222:223], off
	v_lshl_add_u64 v[222:223], s[28:29], 0, v[152:153]
	s_mov_b32 m0, s34
	s_nop 0
	global_load_lds_dwordx4 v[222:223], off
	s_mov_b32 m0, s35
	s_nop 0
	global_load_lds_dwordx4 v[224:225], off
	s_waitcnt vmcnt(8) lgkmcnt(0)
	s_barrier
; #define PG8_STAGE(bufoff, gbase, voff) do { _Pragma("unroll") for (int _i = 0; _i < 2; ++_i) \
;         __builtin_amdgcn_global_load_lds((const unsigned*)((const char*)(gbase) + (voff)[_i]), (PG8_LAS unsigned*)(lds + (bufoff) + ldsw + _i * 8192), 16, 0, 0); } while (0)
; #define PG8_LDA(dst, b, h) do { _Pragma("unroll") for (int m = 0; m < 4; ++m) _Pragma("unroll") for (int k = 0; k < 2; ++k) dst[m][k] = *(const PG8_LAS bf16x8*)(lds + PG8_SA(b, h) + aoff + m * 2048 + k * 1024); } while (0)
; #define PG8_LDB(dst, b, h) do { _Pragma("unroll") for (int n = 0; n < 2; ++n) _Pragma("unroll") for (int k = 0; k < 2; ++k) dst[n][k] = *(const PG8_LAS bf16x8*)(lds + PG8_SB(b, h) + boff + n * 2048 + k * 1024); } while (0)
; #define PG8_MMA(ai, bj, At, Bt) do { __builtin_amdgcn_s_setprio(1); _Pragma("unroll") for (int m = 0; m < 4; ++m) _Pragma("unroll") for (int n = 0; n < 2; ++n) _Pragma("unroll") for (int k = 0; k < 2; ++k) \
;         acc[ai][bj][m][n] = __builtin_amdgcn_mfma_f32_16x16x32_bf16(Bt[n][k], At[m][k], acc[ai][bj][m][n], 0, 0, 0); __builtin_amdgcn_s_setprio(0); } while (0)
; #define PG8_WAIT_V(n) asm volatile("s_waitcnt vmcnt(" #n ")" ::: "memory")
; #define PG8_WAIT_L(n) asm volatile("s_waitcnt lgkmcnt(" #n ")" ::: "memory")
; #define PG8_BAR __builtin_amdgcn_s_barrier()
; #define PG8_SCHED __builtin_amdgcn_sched_barrier(0)
; template <class Epi, class Sched, bool ALIGN_EPI = false, bool SP2 = false>
; __device__ __forceinline__ void gemm_phase(PG8_LAS unsigned char* lds, const Gemm g, const Sched& S, const Epi& E) {
;     ...
;             PG8_WAIT_V(8); PG8_WAIT_L(0); PG8_BAR; PG8_MMA(1, 0, At, B0); PG8_MMA(1, 1, At, B1); PG8_BAR; PG8_SCHED;
;             PG8_LDB(B0, 1, 0); PG8_LDB(B1, 1, 1); PG8_SCHED; PG8_LDA(At, 1, 0); PG8_STAGE(PG8_SA(0, 1), a2 + hstepA, voffA);
;             PG8_WAIT_V(8); PG8_WAIT_L(0); PG8_BAR; PG8_MMA(0, 0, At, B0); PG8_MMA(0, 1, At, B1); PG8_BAR; PG8_SCHED;
	v_mfma_f32_16x16x32_bf16 v[60:63], v[128:131], v[176:179], v[60:63]
	s_setprio 1
	v_mfma_f32_16x16x32_bf16 v[56:59], v[136:139], v[176:179], v[56:59]
	v_mfma_f32_16x16x32_bf16 v[44:47], v[128:131], v[196:199], v[44:47]
	v_mfma_f32_16x16x32_bf16 v[40:43], v[136:139], v[196:199], v[40:43]
	v_mfma_f32_16x16x32_bf16 v[28:31], v[128:131], v[204:207], v[28:31]
	v_mfma_f32_16x16x32_bf16 v[24:27], v[136:139], v[204:207], v[24:27]
	v_mfma_f32_16x16x32_bf16 v[12:15], v[128:131], v[212:215], v[12:15]
	v_mfma_f32_16x16x32_bf16 v[8:11], v[136:139], v[212:215], v[8:11]
	v_mfma_f32_16x16x32_bf16 v[60:63], v[132:135], v[180:183], v[60:63]
	v_mfma_f32_16x16x32_bf16 v[56:59], v[140:143], v[180:183], v[56:59]
	v_mfma_f32_16x16x32_bf16 v[44:47], v[132:135], v[200:203], v[44:47]
	v_mfma_f32_16x16x32_bf16 v[40:43], v[140:143], v[200:203], v[40:43]
	v_mfma_f32_16x16x32_bf16 v[28:31], v[132:135], v[208:211], v[28:31]
	v_mfma_f32_16x16x32_bf16 v[24:27], v[140:143], v[208:211], v[24:27]
	v_mfma_f32_16x16x32_bf16 v[12:15], v[132:135], v[216:219], v[12:15]
	v_mfma_f32_16x16x32_bf16 v[8:11], v[140:143], v[216:219], v[8:11]
	v_mfma_f32_16x16x32_bf16 v[52:55], v[144:147], v[176:179], v[52:55]
	v_mfma_f32_16x16x32_bf16 v[48:51], v[168:171], v[176:179], v[48:51]
	v_mfma_f32_16x16x32_bf16 v[36:39], v[144:147], v[196:199], v[36:39]
	v_mfma_f32_16x16x32_bf16 v[32:35], v[168:171], v[196:199], v[32:35]
	v_mfma_f32_16x16x32_bf16 v[20:23], v[144:147], v[204:207], v[20:23]
	v_mfma_f32_16x16x32_bf16 v[16:19], v[168:171], v[204:207], v[16:19]
	v_mfma_f32_16x16x32_bf16 v[4:7], v[144:147], v[212:215], v[4:7]
	v_mfma_f32_16x16x32_bf16 v[0:3], v[168:171], v[212:215], v[0:3]
	v_mfma_f32_16x16x32_bf16 v[52:55], v[148:151], v[180:183], v[52:55]
	v_mfma_f32_16x16x32_bf16 v[48:51], v[172:175], v[180:183], v[48:51]
	v_mfma_f32_16x16x32_bf16 v[36:39], v[148:151], v[200:203], v[36:39]
	v_mfma_f32_16x16x32_bf16 v[32:35], v[172:175], v[200:203], v[32:35]
	v_mfma_f32_16x16x32_bf16 v[20:23], v[148:151], v[208:211], v[20:23]
	v_mfma_f32_16x16x32_bf16 v[16:19], v[172:175], v[208:211], v[16:19]
	v_mfma_f32_16x16x32_bf16 v[4:7], v[148:151], v[216:219], v[4:7]
	v_mfma_f32_16x16x32_bf16 v[0:3], v[172:175], v[216:219], v[0:3]
	s_barrier
	s_setprio 0
	s_add_i32 s58, 0, 0x18000
	s_add_i32 s59, 0, 0x1c000
	v_add_u32_e32 v140, s58, v189
	v_add_u32_e32 v172, s59, v189
	ds_read_b128 v[128:131], v140
	ds_read_b128 v[132:135], v140 offset:1024
	ds_read_b128 v[136:139], v140 offset:2048
	ds_read_b128 v[140:143], v140 offset:3072
	ds_read_b128 v[144:147], v172
	ds_read_b128 v[148:151], v172 offset:1024
	ds_read_b128 v[168:171], v172 offset:2048
	ds_read_b128 v[172:175], v172 offset:3072
	s_add_u32 s22, s28, 0xb0000
	s_addc_u32 s23, s29, 0
	s_mov_b32 m0, s36
	v_lshl_add_u64 v[226:227], s[22:23], 0, v[152:153]
	ds_read_b128 v[176:179], v193 offset:32768
	ds_read_b128 v[180:183], v193 offset:33792
	ds_read_b128 v[196:199], v193 offset:34816
	ds_read_b128 v[200:203], v193 offset:35840
	ds_read_b128 v[204:207], v193 offset:36864
	ds_read_b128 v[208:211], v193 offset:37888
	ds_read_b128 v[212:215], v193 offset:38912
	ds_read_b128 v[216:219], v193 offset:39936
	global_load_lds_dwordx4 v[226:227], off
	v_lshl_add_u64 v[226:227], s[22:23], 0, v[156:157]
	s_mov_b32 m0, s37
	s_nop 0
	global_load_lds_dwordx4 v[226:227], off
	s_waitcnt vmcnt(8) lgkmcnt(0)
	s_barrier
	v_mfma_f32_16x16x32_bf16 v[124:127], v[128:131], v[176:179], v[124:127]
	s_setprio 1
	v_mfma_f32_16x16x32_bf16 v[120:123], v[136:139], v[176:179], v[120:123]
	v_mfma_f32_16x16x32_bf16 v[108:111], v[128:131], v[196:199], v[108:111]
	v_mfma_f32_16x16x32_bf16 v[104:107], v[136:139], v[196:199], v[104:107]
	v_mfma_f32_16x16x32_bf16 v[92:95], v[128:131], v[204:207], v[92:95]
	v_mfma_f32_16x16x32_bf16 v[88:91], v[136:139], v[204:207], v[88:91]
	v_mfma_f32_16x16x32_bf16 v[76:79], v[128:131], v[212:215], v[76:79]
	v_mfma_f32_16x16x32_bf16 v[72:75], v[136:139], v[212:215], v[72:75]
	v_mfma_f32_16x16x32_bf16 v[124:127], v[132:135], v[180:183], v[124:127]
	v_mfma_f32_16x16x32_bf16 v[120:123], v[140:143], v[180:183], v[120:123]
	v_mfma_f32_16x16x32_bf16 v[108:111], v[132:135], v[200:203], v[108:111]
	v_mfma_f32_16x16x32_bf16 v[104:107], v[140:143], v[200:203], v[104:107]
	v_mfma_f32_16x16x32_bf16 v[92:95], v[132:135], v[208:211], v[92:95]
	v_mfma_f32_16x16x32_bf16 v[88:91], v[140:143], v[208:211], v[88:91]
	v_mfma_f32_16x16x32_bf16 v[76:79], v[132:135], v[216:219], v[76:79]
	v_mfma_f32_16x16x32_bf16 v[72:75], v[140:143], v[216:219], v[72:75]
	v_mfma_f32_16x16x32_bf16 v[116:119], v[144:147], v[176:179], v[116:119]
	v_mfma_f32_16x16x32_bf16 v[112:115], v[168:171], v[176:179], v[112:115]
	v_mfma_f32_16x16x32_bf16 v[100:103], v[144:147], v[196:199], v[100:103]
	v_mfma_f32_16x16x32_bf16 v[96:99], v[168:171], v[196:199], v[96:99]
	v_mfma_f32_16x16x32_bf16 v[84:87], v[144:147], v[204:207], v[84:87]
	v_mfma_f32_16x16x32_bf16 v[80:83], v[168:171], v[204:207], v[80:83]
	v_mfma_f32_16x16x32_bf16 v[68:71], v[144:147], v[212:215], v[68:71]
	v_mfma_f32_16x16x32_bf16 v[64:67], v[168:171], v[212:215], v[64:67]
	v_mfma_f32_16x16x32_bf16 v[116:119], v[148:151], v[180:183], v[116:119]
	v_mfma_f32_16x16x32_bf16 v[112:115], v[172:175], v[180:183], v[112:115]
	v_mfma_f32_16x16x32_bf16 v[100:103], v[148:151], v[200:203], v[100:103]
	v_mfma_f32_16x16x32_bf16 v[96:99], v[172:175], v[200:203], v[96:99]
	v_mfma_f32_16x16x32_bf16 v[84:87], v[148:151], v[208:211], v[84:87]
	v_mfma_f32_16x16x32_bf16 v[80:83], v[172:175], v[208:211], v[80:83]
	v_mfma_f32_16x16x32_bf16 v[68:71], v[148:151], v[216:219], v[68:71]
	v_mfma_f32_16x16x32_bf16 v[64:67], v[172:175], v[216:219], v[64:67]
	s_barrier
; #define PG8_STAGE(bufoff, gbase, voff) do { _Pragma("unroll") for (int _i = 0; _i < 2; ++_i) \
;         __builtin_amdgcn_global_load_lds((const unsigned*)((const char*)(gbase) + (voff)[_i]), (PG8_LAS unsigned*)(lds + (bufoff) + ldsw + _i * 8192), 16, 0, 0); } while (0)
; #define PG8_LDA(dst, b, h) do { _Pragma("unroll") for (int m = 0; m < 4; ++m) _Pragma("unroll") for (int k = 0; k < 2; ++k) dst[m][k] = *(const PG8_LAS bf16x8*)(lds + PG8_SA(b, h) + aoff + m * 2048 + k * 1024); } while (0)
; #define PG8_MMA(ai, bj, At, Bt) do { __builtin_amdgcn_s_setprio(1); _Pragma("unroll") for (int m = 0; m < 4; ++m) _Pragma("unroll") for (int n = 0; n < 2; ++n) _Pragma("unroll") for (int k = 0; k < 2; ++k) \
;         acc[ai][bj][m][n] = __builtin_amdgcn_mfma_f32_16x16x32_bf16(Bt[n][k], At[m][k], acc[ai][bj][m][n], 0, 0, 0); __builtin_amdgcn_s_setprio(0); } while (0)
; #define PG8_WAIT_V(n) asm volatile("s_waitcnt vmcnt(" #n ")" ::: "memory")
; #define PG8_WAIT_L(n) asm volatile("s_waitcnt lgkmcnt(" #n ")" ::: "memory")
; #define PG8_BAR __builtin_amdgcn_s_barrier()
; #define PG8_SCHED __builtin_amdgcn_sched_barrier(0)
; template <class Epi, class Sched, bool ALIGN_EPI = false, bool SP2 = false>
; __device__ __forceinline__ void gemm_phase(PG8_LAS unsigned char* lds, const Gemm g, const Sched& S, const Epi& E) {
;     ...
;             PG8_LDA(At, 1, 1); PG8_STAGE(PG8_SB(1, 0), b3, voffB); PG8_STAGE(PG8_SB(1, 1), b3 + hstepB, voffB); PG8_STAGE(PG8_SA(1, 0), a3, voffA);
;             PG8_WAIT_V(8); PG8_WAIT_L(0); PG8_BAR; PG8_MMA(1, 0, At, B0); PG8_MMA(1, 1, At, B1); PG8_BAR; PG8_SCHED;
;     ...
;         if constexpr (ALIGN_EPI) { if (wr == 0) PG8_BAR; }
	s_setprio 0
	s_add_i32 s22, s58, s31
	v_lshl_add_u64 v[184:185], v[184:185], 0, s[16:17]
	s_mov_b32 m0, s22
	ds_read_b128 v[176:179], v193 offset:49152
	ds_read_b128 v[180:183], v193 offset:50176
	ds_read_b128 v[196:199], v193 offset:51200
	ds_read_b128 v[200:203], v193 offset:52224
	ds_read_b128 v[204:207], v193 offset:53248
	ds_read_b128 v[208:211], v193 offset:54272
	ds_read_b128 v[212:215], v193 offset:55296
	ds_read_b128 v[216:219], v193 offset:56320
	global_load_lds_dwordx4 v[184:185], off
	s_add_i32 m0, s22, 0x2000
	s_add_u32 s22, s26, 0xb0080
	v_lshl_add_u64 v[184:185], v[220:221], 0, s[16:17]
	s_addc_u32 s23, s27, 0
	s_add_i32 s26, s59, s31
	global_load_lds_dwordx4 v[184:185], off
	v_lshl_add_u64 v[184:185], s[22:23], 0, v[154:155]
	s_mov_b32 m0, s26
	s_nop 0
	global_load_lds_dwordx4 v[184:185], off
	v_lshl_add_u64 v[184:185], s[22:23], 0, v[158:159]
	s_add_i32 m0, s26, 0x2000
	s_nop 0
	global_load_lds_dwordx4 v[184:185], off
	v_lshl_add_u64 v[184:185], v[222:223], 0, s[16:17]
	s_mov_b32 m0, s39
	s_nop 0
	global_load_lds_dwordx4 v[184:185], off
	v_lshl_add_u64 v[184:185], v[224:225], 0, s[16:17]
	s_mov_b32 m0, s40
	s_nop 0
	global_load_lds_dwordx4 v[184:185], off
	s_waitcnt vmcnt(8) lgkmcnt(0)
	s_barrier
	v_mfma_f32_16x16x32_bf16 v[60:63], v[128:131], v[176:179], v[60:63]
	s_setprio 1
	v_mfma_f32_16x16x32_bf16 v[56:59], v[136:139], v[176:179], v[56:59]
	v_mfma_f32_16x16x32_bf16 v[44:47], v[128:131], v[196:199], v[44:47]
	v_mfma_f32_16x16x32_bf16 v[40:43], v[136:139], v[196:199], v[40:43]
	v_mfma_f32_16x16x32_bf16 v[28:31], v[128:131], v[204:207], v[28:31]
	v_mfma_f32_16x16x32_bf16 v[24:27], v[136:139], v[204:207], v[24:27]
	v_mfma_f32_16x16x32_bf16 v[12:15], v[128:131], v[212:215], v[12:15]
	v_mfma_f32_16x16x32_bf16 v[8:11], v[136:139], v[212:215], v[8:11]
	v_mfma_f32_16x16x32_bf16 v[60:63], v[132:135], v[180:183], v[60:63]
	v_mfma_f32_16x16x32_bf16 v[56:59], v[140:143], v[180:183], v[56:59]
	v_mfma_f32_16x16x32_bf16 v[44:47], v[132:135], v[200:203], v[44:47]
	v_mfma_f32_16x16x32_bf16 v[40:43], v[140:143], v[200:203], v[40:43]
	v_mfma_f32_16x16x32_bf16 v[28:31], v[132:135], v[208:211], v[28:31]
	v_mfma_f32_16x16x32_bf16 v[24:27], v[140:143], v[208:211], v[24:27]
	v_mfma_f32_16x16x32_bf16 v[12:15], v[132:135], v[216:219], v[12:15]
	v_mfma_f32_16x16x32_bf16 v[8:11], v[140:143], v[216:219], v[8:11]
	v_mfma_f32_16x16x32_bf16 v[52:55], v[144:147], v[176:179], v[52:55]
	v_mfma_f32_16x16x32_bf16 v[48:51], v[168:171], v[176:179], v[48:51]
	v_mfma_f32_16x16x32_bf16 v[36:39], v[144:147], v[196:199], v[36:39]
	v_mfma_f32_16x16x32_bf16 v[32:35], v[168:171], v[196:199], v[32:35]
	v_mfma_f32_16x16x32_bf16 v[20:23], v[144:147], v[204:207], v[20:23]
	v_mfma_f32_16x16x32_bf16 v[16:19], v[168:171], v[204:207], v[16:19]
	v_mfma_f32_16x16x32_bf16 v[4:7], v[144:147], v[212:215], v[4:7]
	v_mfma_f32_16x16x32_bf16 v[0:3], v[168:171], v[212:215], v[0:3]
	v_mfma_f32_16x16x32_bf16 v[52:55], v[148:151], v[180:183], v[52:55]
	v_mfma_f32_16x16x32_bf16 v[48:51], v[172:175], v[180:183], v[48:51]
	v_mfma_f32_16x16x32_bf16 v[36:39], v[148:151], v[200:203], v[36:39]
	v_mfma_f32_16x16x32_bf16 v[32:35], v[172:175], v[200:203], v[32:35]
	v_mfma_f32_16x16x32_bf16 v[20:23], v[148:151], v[208:211], v[20:23]
	v_mfma_f32_16x16x32_bf16 v[16:19], v[172:175], v[208:211], v[16:19]
	v_mfma_f32_16x16x32_bf16 v[4:7], v[148:151], v[216:219], v[4:7]
	v_mfma_f32_16x16x32_bf16 v[0:3], v[172:175], v[216:219], v[0:3]
	s_barrier
	s_setprio 0
	s_add_i32 s69, s69, 2
	s_add_u32 s67, s67, 0x100
	s_addc_u32 s68, s68, 0
	s_cmp_gt_u32 s69, 41
	s_mov_b64 s[22:23], s[24:25]
	s_cbranch_scc0 .LBB0_1129
	s_and_b64 vcc, exec, s[18:19]
	s_cbranch_vccz .LBB0_1132
	s_barrier

; #define PG8_STAGE(bufoff, gbase, voff) do { _Pragma("unroll") for (int _i = 0; _i < 2; ++_i) \
;         __builtin_amdgcn_global_load_lds((const unsigned*)((const char*)(gbase) + (voff)[_i]), (PG8_LAS unsigned*)(lds + (bufoff) + ldsw + _i * 8192), 16, 0, 0); } while (0)
; #define PG8_LDA(dst, b, h) do { _Pragma("unroll") for (int m = 0; m < 4; ++m) _Pragma("unroll") for (int k = 0; k < 2; ++k) dst[m][k] = *(const PG8_LAS bf16x8*)(lds + PG8_SA(b, h) + aoff + m * 2048 + k * 1024); } while (0)
; #define PG8_LDB(dst, b, h) do { _Pragma("unroll") for (int n = 0; n < 2; ++n) _Pragma("unroll") for (int k = 0; k < 2; ++k) dst[n][k] = *(const PG8_LAS bf16x8*)(lds + PG8_SB(b, h) + boff + n * 2048 + k * 1024); } while (0)
; #define PG8_MMA(ai, bj, At, Bt) do { __builtin_amdgcn_s_setprio(1); _Pragma("unroll") for (int m = 0; m < 4; ++m) _Pragma("unroll") for (int n = 0; n < 2; ++n) _Pragma("unroll") for (int k = 0; k < 2; ++k) \
;         acc[ai][bj][m][n] = __builtin_amdgcn_mfma_f32_16x16x32_bf16(Bt[n][k], At[m][k], acc[ai][bj][m][n], 0, 0, 0); __builtin_amdgcn_s_setprio(0); } while (0)
; #define PG8_WAIT_V(n) asm volatile("s_waitcnt vmcnt(" #n ")" ::: "memory")
; #define PG8_WAIT_L(n) asm volatile("s_waitcnt lgkmcnt(" #n ")" ::: "memory")
; #define PG8_BAR __builtin_amdgcn_s_barrier()
; #define PG8_SCHED __builtin_amdgcn_sched_barrier(0)
; template <class Epi, class Sched, bool ALIGN_EPI = false, bool SP2 = false>
; __device__ __forceinline__ void gemm_phase(PG8_LAS unsigned char* lds, const Gemm g, const Sched& S, const Epi& E) {
;     ...
;             const bool last = (t == nt - 2);
;             const char* a1 = cA + (size_t)(t + 1) * kstep;
;             const char* a2 = last ? nA : cA + (size_t)(t + 2) * kstep; const char* b2 = last ? nB : cB + (size_t)(t + 2) * kstep;
;             const char* a3 = a2 + kstep; const char* b3 = b2 + kstep;
;             if (last && has_next) S.a_ready(nxt);
;             if constexpr (SP2) {
;             PG8_LDB(B0, 0, 0); PG8_LDB(B1, 0, 1); PG8_SCHED; PG8_LDA(At, 0, 0); PG8_STAGE(PG8_SA(1, 1), a1 + hstepA, voffA);
;             PG8_WAIT_V(8); PG8_WAIT_L(0); PG8_BAR; PG8_MMA(0, 0, At, B0); PG8_MMA(0, 1, At, B1); PG8_BAR; PG8_SCHED;
;             PG8_LDA(At, 0, 1); PG8_STAGE(PG8_SB(0, 0), b2, voffB); PG8_STAGE(PG8_SB(0, 1), b2 + hstepB, voffB); PG8_STAGE(PG8_SA(0, 0), a2, voffA);
.LBB0_1161:
	s_add_u32 s43, s36, s42
	s_addc_u32 s48, s37, 0
	s_add_u32 s46, s43, 0x100
	s_addc_u32 s47, s48, 0
	s_and_b64 s[44:45], s[40:41], exec
	s_cselect_b32 s45, s25, s47
	s_cselect_b32 s44, s89, s46
	s_add_u32 s42, s34, s42
	s_addc_u32 s46, s35, 0
	s_add_u32 s42, s42, 0x100
	s_addc_u32 s46, s46, 0
	s_and_b64 s[40:41], s[40:41], exec
	s_cselect_b32 s47, s23, s46
	s_cselect_b32 s46, s90, s42
	s_add_u32 s64, s43, 0x10080
	ds_read_b128 v[146:149], v143
	ds_read_b128 v[150:153], v143 offset:1024
	ds_read_b128 v[154:157], v143 offset:2048
	ds_read_b128 v[158:161], v143 offset:3072
	ds_read_b128 v[162:165], v144
	ds_read_b128 v[166:169], v144 offset:1024
	ds_read_b128 v[170:173], v144 offset:2048
	ds_read_b128 v[174:177], v144 offset:3072
	s_addc_u32 s65, s48, 0
	s_add_i32 s97, s82, s67
	s_add_i32 m0, s31, 0xc000
	s_add_i32 s59, s31, 0xe000
	s_add_i32 s58, s97, 0x2000
	s_add_u32 s48, s46, 0x10000
	s_addc_u32 s49, s47, 0
	s_add_i32 vcc_hi, s83, s67
	s_add_i32 vcc_lo, vcc_hi, 0x2000
	s_add_i32 s96, 0, 0x18000
	s_add_i32 s95, 0, 0x1c000
	s_add_u32 s42, s44, 0x10000
	s_addc_u32 s43, s45, 0
	s_add_i32 s94, s96, s67
	s_add_i32 s92, s94, 0x2000
	s_add_u32 s40, s46, 0x10080
	s_addc_u32 s41, s47, 0
	s_add_i32 s93, s95, s67
	s_add_i32 s91, s93, 0x2000
	v_lshl_add_u64 v[212:213], s[64:65], 0, v[134:135]
	ds_read_b128 v[178:181], v145
	ds_read_b128 v[182:185], v145 offset:1024
	ds_read_b128 v[188:191], v145 offset:2048
	ds_read_b128 v[192:195], v145 offset:3072
	ds_read_b128 v[196:199], v145 offset:4096
	ds_read_b128 v[200:203], v145 offset:5120
	ds_read_b128 v[204:207], v145 offset:6144
	ds_read_b128 v[208:211], v145 offset:7168
	global_load_lds_dwordx4 v[212:213], off
	v_lshl_add_u64 v[212:213], s[64:65], 0, v[130:131]
	s_mov_b32 m0, s59
	s_nop 0
	global_load_lds_dwordx4 v[212:213], off
	s_waitcnt vmcnt(8) lgkmcnt(0)
	s_barrier
	v_mfma_f32_16x16x32_bf16 v[124:127], v[146:149], v[178:181], v[124:127]
	s_setprio 1
	v_mfma_f32_16x16x32_bf16 v[120:123], v[154:157], v[178:181], v[120:123]
	v_mfma_f32_16x16x32_bf16 v[116:119], v[146:149], v[188:191], v[116:119]
	v_mfma_f32_16x16x32_bf16 v[108:111], v[154:157], v[188:191], v[108:111]
	v_mfma_f32_16x16x32_bf16 v[100:103], v[146:149], v[196:199], v[100:103]
	v_mfma_f32_16x16x32_bf16 v[92:95], v[154:157], v[196:199], v[92:95]
	v_mfma_f32_16x16x32_bf16 v[84:87], v[146:149], v[204:207], v[84:87]
	v_mfma_f32_16x16x32_bf16 v[76:79], v[154:157], v[204:207], v[76:79]
	v_mfma_f32_16x16x32_bf16 v[124:127], v[150:153], v[182:185], v[124:127]
	v_mfma_f32_16x16x32_bf16 v[120:123], v[158:161], v[182:185], v[120:123]
	v_mfma_f32_16x16x32_bf16 v[116:119], v[150:153], v[192:195], v[116:119]
	v_mfma_f32_16x16x32_bf16 v[108:111], v[158:161], v[192:195], v[108:111]
	v_mfma_f32_16x16x32_bf16 v[100:103], v[150:153], v[200:203], v[100:103]
	v_mfma_f32_16x16x32_bf16 v[92:95], v[158:161], v[200:203], v[92:95]
	v_mfma_f32_16x16x32_bf16 v[84:87], v[150:153], v[208:211], v[84:87]
	v_mfma_f32_16x16x32_bf16 v[76:79], v[158:161], v[208:211], v[76:79]
	v_mfma_f32_16x16x32_bf16 v[112:115], v[162:165], v[178:181], v[112:115]
	v_mfma_f32_16x16x32_bf16 v[104:107], v[170:173], v[178:181], v[104:107]
	v_mfma_f32_16x16x32_bf16 v[96:99], v[162:165], v[188:191], v[96:99]
	v_mfma_f32_16x16x32_bf16 v[88:91], v[170:173], v[188:191], v[88:91]
	v_mfma_f32_16x16x32_bf16 v[80:83], v[162:165], v[196:199], v[80:83]
	v_mfma_f32_16x16x32_bf16 v[72:75], v[170:173], v[196:199], v[72:75]
	v_mfma_f32_16x16x32_bf16 v[68:71], v[162:165], v[204:207], v[68:71]
	v_mfma_f32_16x16x32_bf16 v[64:67], v[170:173], v[204:207], v[64:67]
	v_mfma_f32_16x16x32_bf16 v[112:115], v[166:169], v[182:185], v[112:115]
	v_mfma_f32_16x16x32_bf16 v[104:107], v[174:177], v[182:185], v[104:107]
	v_mfma_f32_16x16x32_bf16 v[96:99], v[166:169], v[192:195], v[96:99]
	v_mfma_f32_16x16x32_bf16 v[88:91], v[174:177], v[192:195], v[88:91]
	v_mfma_f32_16x16x32_bf16 v[80:83], v[166:169], v[200:203], v[80:83]
	v_mfma_f32_16x16x32_bf16 v[72:75], v[174:177], v[200:203], v[72:75]
	v_mfma_f32_16x16x32_bf16 v[68:71], v[166:169], v[208:211], v[68:71]
	v_mfma_f32_16x16x32_bf16 v[64:67], v[174:177], v[208:211], v[64:67]
	s_barrier
	s_setprio 0
	s_mov_b32 m0, s97
	v_lshl_add_u64 v[212:213], s[46:47], 0, v[132:133]
	ds_read_b128 v[178:181], v145 offset:16384
	ds_read_b128 v[182:185], v145 offset:17408
	ds_read_b128 v[188:191], v145 offset:18432
	ds_read_b128 v[192:195], v145 offset:19456
	ds_read_b128 v[196:199], v145 offset:20480
	ds_read_b128 v[200:203], v145 offset:21504
	ds_read_b128 v[204:207], v145 offset:22528
	ds_read_b128 v[208:211], v145 offset:23552
	global_load_lds_dwordx4 v[212:213], off
	v_lshl_add_u64 v[214:215], s[46:47], 0, v[128:129]
	s_mov_b32 m0, s58
	v_lshl_add_u64 v[216:217], s[48:49], 0, v[132:133]
	global_load_lds_dwordx4 v[214:215], off
	s_mov_b32 m0, vcc_hi
	v_lshl_add_u64 v[218:219], s[44:45], 0, v[130:131]
	global_load_lds_dwordx4 v[216:217], off
	v_lshl_add_u64 v[216:217], s[48:49], 0, v[128:129]
	s_mov_b32 m0, vcc_lo
	s_nop 0
	global_load_lds_dwordx4 v[216:217], off
	v_lshl_add_u64 v[216:217], s[44:45], 0, v[134:135]
	s_mov_b32 m0, s31
	s_nop 0
	global_load_lds_dwordx4 v[216:217], off
	s_mov_b32 m0, s74
	s_nop 0
	global_load_lds_dwordx4 v[218:219], off
	s_waitcnt vmcnt(8) lgkmcnt(0)
	s_barrier
; #define PG8_STAGE(bufoff, gbase, voff) do { _Pragma("unroll") for (int _i = 0; _i < 2; ++_i) \
;         __builtin_amdgcn_global_load_lds((const unsigned*)((const char*)(gbase) + (voff)[_i]), (PG8_LAS unsigned*)(lds + (bufoff) + ldsw + _i * 8192), 16, 0, 0); } while (0)
; #define PG8_LDA(dst, b, h) do { _Pragma("unroll") for (int m = 0; m < 4; ++m) _Pragma("unroll") for (int k = 0; k < 2; ++k) dst[m][k] = *(const PG8_LAS bf16x8*)(lds + PG8_SA(b, h) + aoff + m * 2048 + k * 1024); } while (0)
; #define PG8_LDB(dst, b, h) do { _Pragma("unroll") for (int n = 0; n < 2; ++n) _Pragma("unroll") for (int k = 0; k < 2; ++k) dst[n][k] = *(const PG8_LAS bf16x8*)(lds + PG8_SB(b, h) + boff + n * 2048 + k * 1024); } while (0)
; #define PG8_MMA(ai, bj, At, Bt) do { __builtin_amdgcn_s_setprio(1); _Pragma("unroll") for (int m = 0; m < 4; ++m) _Pragma("unroll") for (int n = 0; n < 2; ++n) _Pragma("unroll") for (int k = 0; k < 2; ++k) \
;         acc[ai][bj][m][n] = __builtin_amdgcn_mfma_f32_16x16x32_bf16(Bt[n][k], At[m][k], acc[ai][bj][m][n], 0, 0, 0); __builtin_amdgcn_s_setprio(0); } while (0)
; #define PG8_WAIT_V(n) asm volatile("s_waitcnt vmcnt(" #n ")" ::: "memory")
; #define PG8_WAIT_L(n) asm volatile("s_waitcnt lgkmcnt(" #n ")" ::: "memory")
; #define PG8_BAR __builtin_amdgcn_s_barrier()
; #define PG8_SCHED __builtin_amdgcn_sched_barrier(0)
; template <class Epi, class Sched, bool ALIGN_EPI = false, bool SP2 = false>
; __device__ __forceinline__ void gemm_phase(PG8_LAS unsigned char* lds, const Gemm g, const Sched& S, const Epi& E) {
;     ...
;             PG8_WAIT_V(8); PG8_WAIT_L(0); PG8_BAR; PG8_MMA(1, 0, At, B0); PG8_MMA(1, 1, At, B1); PG8_BAR; PG8_SCHED;
;             PG8_LDB(B0, 1, 0); PG8_LDB(B1, 1, 1); PG8_SCHED; PG8_LDA(At, 1, 0); PG8_STAGE(PG8_SA(0, 1), a2 + hstepA, voffA);
;             PG8_WAIT_V(8); PG8_WAIT_L(0); PG8_BAR; PG8_MMA(0, 0, At, B0); PG8_MMA(0, 1, At, B1); PG8_BAR; PG8_SCHED;
	v_mfma_f32_16x16x32_bf16 v[60:63], v[146:149], v[178:181], v[60:63]
	s_setprio 1
	v_mfma_f32_16x16x32_bf16 v[56:59], v[154:157], v[178:181], v[56:59]
	v_mfma_f32_16x16x32_bf16 v[52:55], v[146:149], v[188:191], v[52:55]
	v_mfma_f32_16x16x32_bf16 v[44:47], v[154:157], v[188:191], v[44:47]
	v_mfma_f32_16x16x32_bf16 v[36:39], v[146:149], v[196:199], v[36:39]
	v_mfma_f32_16x16x32_bf16 v[28:31], v[154:157], v[196:199], v[28:31]
	v_mfma_f32_16x16x32_bf16 v[20:23], v[146:149], v[204:207], v[20:23]
	v_mfma_f32_16x16x32_bf16 v[12:15], v[154:157], v[204:207], v[12:15]
	v_mfma_f32_16x16x32_bf16 v[60:63], v[150:153], v[182:185], v[60:63]
	v_mfma_f32_16x16x32_bf16 v[56:59], v[158:161], v[182:185], v[56:59]
	v_mfma_f32_16x16x32_bf16 v[52:55], v[150:153], v[192:195], v[52:55]
	v_mfma_f32_16x16x32_bf16 v[44:47], v[158:161], v[192:195], v[44:47]
	v_mfma_f32_16x16x32_bf16 v[36:39], v[150:153], v[200:203], v[36:39]
	v_mfma_f32_16x16x32_bf16 v[28:31], v[158:161], v[200:203], v[28:31]
	v_mfma_f32_16x16x32_bf16 v[20:23], v[150:153], v[208:211], v[20:23]
	v_mfma_f32_16x16x32_bf16 v[12:15], v[158:161], v[208:211], v[12:15]
	v_mfma_f32_16x16x32_bf16 v[48:51], v[162:165], v[178:181], v[48:51]
	v_mfma_f32_16x16x32_bf16 v[40:43], v[170:173], v[178:181], v[40:43]
	v_mfma_f32_16x16x32_bf16 v[32:35], v[162:165], v[188:191], v[32:35]
	v_mfma_f32_16x16x32_bf16 v[24:27], v[170:173], v[188:191], v[24:27]
	v_mfma_f32_16x16x32_bf16 v[16:19], v[162:165], v[196:199], v[16:19]
	v_mfma_f32_16x16x32_bf16 v[8:11], v[170:173], v[196:199], v[8:11]
	v_mfma_f32_16x16x32_bf16 v[4:7], v[162:165], v[204:207], v[4:7]
	v_mfma_f32_16x16x32_bf16 v[0:3], v[170:173], v[204:207], v[0:3]
	v_mfma_f32_16x16x32_bf16 v[48:51], v[166:169], v[182:185], v[48:51]
	v_mfma_f32_16x16x32_bf16 v[40:43], v[174:177], v[182:185], v[40:43]
	v_mfma_f32_16x16x32_bf16 v[32:35], v[166:169], v[192:195], v[32:35]
	v_mfma_f32_16x16x32_bf16 v[24:27], v[174:177], v[192:195], v[24:27]
	v_mfma_f32_16x16x32_bf16 v[16:19], v[166:169], v[200:203], v[16:19]
	v_mfma_f32_16x16x32_bf16 v[8:11], v[174:177], v[200:203], v[8:11]
	v_mfma_f32_16x16x32_bf16 v[4:7], v[166:169], v[208:211], v[4:7]
	v_mfma_f32_16x16x32_bf16 v[0:3], v[174:177], v[208:211], v[0:3]
	s_barrier
	s_setprio 0
	v_add_u32_e32 v158, s96, v141
	v_add_u32_e32 v174, s95, v141
	ds_read_b128 v[146:149], v158
	ds_read_b128 v[150:153], v158 offset:1024
	ds_read_b128 v[154:157], v158 offset:2048
	ds_read_b128 v[158:161], v158 offset:3072
	ds_read_b128 v[162:165], v174
	ds_read_b128 v[166:169], v174 offset:1024
	ds_read_b128 v[170:173], v174 offset:2048
	ds_read_b128 v[174:177], v174 offset:3072
	s_mov_b32 m0, s75
	v_lshl_add_u64 v[220:221], s[42:43], 0, v[134:135]
	ds_read_b128 v[178:181], v145 offset:32768
	ds_read_b128 v[182:185], v145 offset:33792
	ds_read_b128 v[188:191], v145 offset:34816
	ds_read_b128 v[192:195], v145 offset:35840
	ds_read_b128 v[196:199], v145 offset:36864
	ds_read_b128 v[200:203], v145 offset:37888
	ds_read_b128 v[204:207], v145 offset:38912
	ds_read_b128 v[208:211], v145 offset:39936
	global_load_lds_dwordx4 v[220:221], off
	v_lshl_add_u64 v[220:221], s[42:43], 0, v[130:131]
	s_mov_b32 m0, s76
	s_nop 0
	global_load_lds_dwordx4 v[220:221], off
	s_waitcnt vmcnt(8) lgkmcnt(0)
	s_barrier
	v_mfma_f32_16x16x32_bf16 v[124:127], v[146:149], v[178:181], v[124:127]
	s_setprio 1
	v_mfma_f32_16x16x32_bf16 v[120:123], v[154:157], v[178:181], v[120:123]
	v_mfma_f32_16x16x32_bf16 v[116:119], v[146:149], v[188:191], v[116:119]
	v_mfma_f32_16x16x32_bf16 v[108:111], v[154:157], v[188:191], v[108:111]
	v_mfma_f32_16x16x32_bf16 v[100:103], v[146:149], v[196:199], v[100:103]
	v_mfma_f32_16x16x32_bf16 v[92:95], v[154:157], v[196:199], v[92:95]
	v_mfma_f32_16x16x32_bf16 v[84:87], v[146:149], v[204:207], v[84:87]
	v_mfma_f32_16x16x32_bf16 v[76:79], v[154:157], v[204:207], v[76:79]
	v_mfma_f32_16x16x32_bf16 v[124:127], v[150:153], v[182:185], v[124:127]
	v_mfma_f32_16x16x32_bf16 v[120:123], v[158:161], v[182:185], v[120:123]
	v_mfma_f32_16x16x32_bf16 v[116:119], v[150:153], v[192:195], v[116:119]
	v_mfma_f32_16x16x32_bf16 v[108:111], v[158:161], v[192:195], v[108:111]
	v_mfma_f32_16x16x32_bf16 v[100:103], v[150:153], v[200:203], v[100:103]
	v_mfma_f32_16x16x32_bf16 v[92:95], v[158:161], v[200:203], v[92:95]
	v_mfma_f32_16x16x32_bf16 v[84:87], v[150:153], v[208:211], v[84:87]
	v_mfma_f32_16x16x32_bf16 v[76:79], v[158:161], v[208:211], v[76:79]
	v_mfma_f32_16x16x32_bf16 v[112:115], v[162:165], v[178:181], v[112:115]
	v_mfma_f32_16x16x32_bf16 v[104:107], v[170:173], v[178:181], v[104:107]
	v_mfma_f32_16x16x32_bf16 v[96:99], v[162:165], v[188:191], v[96:99]
	v_mfma_f32_16x16x32_bf16 v[88:91], v[170:173], v[188:191], v[88:91]
	v_mfma_f32_16x16x32_bf16 v[80:83], v[162:165], v[196:199], v[80:83]
	v_mfma_f32_16x16x32_bf16 v[72:75], v[170:173], v[196:199], v[72:75]
	v_mfma_f32_16x16x32_bf16 v[68:71], v[162:165], v[204:207], v[68:71]
	v_mfma_f32_16x16x32_bf16 v[64:67], v[170:173], v[204:207], v[64:67]
	v_mfma_f32_16x16x32_bf16 v[112:115], v[166:169], v[182:185], v[112:115]
	v_mfma_f32_16x16x32_bf16 v[104:107], v[174:177], v[182:185], v[104:107]
	v_mfma_f32_16x16x32_bf16 v[96:99], v[166:169], v[192:195], v[96:99]
	v_mfma_f32_16x16x32_bf16 v[88:91], v[174:177], v[192:195], v[88:91]
	v_mfma_f32_16x16x32_bf16 v[80:83], v[166:169], v[200:203], v[80:83]
	v_mfma_f32_16x16x32_bf16 v[72:75], v[174:177], v[200:203], v[72:75]
	v_mfma_f32_16x16x32_bf16 v[68:71], v[166:169], v[208:211], v[68:71]
	v_mfma_f32_16x16x32_bf16 v[64:67], v[174:177], v[208:211], v[64:67]
	s_barrier
; #define PG8_STAGE(bufoff, gbase, voff) do { _Pragma("unroll") for (int _i = 0; _i < 2; ++_i) \
;         __builtin_amdgcn_global_load_lds((const unsigned*)((const char*)(gbase) + (voff)[_i]), (PG8_LAS unsigned*)(lds + (bufoff) + ldsw + _i * 8192), 16, 0, 0); } while (0)
; #define PG8_LDA(dst, b, h) do { _Pragma("unroll") for (int m = 0; m < 4; ++m) _Pragma("unroll") for (int k = 0; k < 2; ++k) dst[m][k] = *(const PG8_LAS bf16x8*)(lds + PG8_SA(b, h) + aoff + m * 2048 + k * 1024); } while (0)
; #define PG8_MMA(ai, bj, At, Bt) do { __builtin_amdgcn_s_setprio(1); _Pragma("unroll") for (int m = 0; m < 4; ++m) _Pragma("unroll") for (int n = 0; n < 2; ++n) _Pragma("unroll") for (int k = 0; k < 2; ++k) \
;         acc[ai][bj][m][n] = __builtin_amdgcn_mfma_f32_16x16x32_bf16(Bt[n][k], At[m][k], acc[ai][bj][m][n], 0, 0, 0); __builtin_amdgcn_s_setprio(0); } while (0)
; #define PG8_WAIT_V(n) asm volatile("s_waitcnt vmcnt(" #n ")" ::: "memory")
; #define PG8_WAIT_L(n) asm volatile("s_waitcnt lgkmcnt(" #n ")" ::: "memory")
; #define PG8_BAR __builtin_amdgcn_s_barrier()
; #define PG8_SCHED __builtin_amdgcn_sched_barrier(0)
; template <class Epi, class Sched, bool ALIGN_EPI = false, bool SP2 = false>
; __device__ __forceinline__ void gemm_phase(PG8_LAS unsigned char* lds, const Gemm g, const Sched& S, const Epi& E) {
;     ...
;             PG8_LDA(At, 1, 1); PG8_STAGE(PG8_SB(1, 0), b3, voffB); PG8_STAGE(PG8_SB(1, 1), b3 + hstepB, voffB); PG8_STAGE(PG8_SA(1, 0), a3, voffA);
;             PG8_WAIT_V(8); PG8_WAIT_L(0); PG8_BAR; PG8_MMA(1, 0, At, B0); PG8_MMA(1, 1, At, B1); PG8_BAR; PG8_SCHED;
;     ...
;         if constexpr (ALIGN_EPI) { if (wr == 0) PG8_BAR; }
	s_setprio 0
	s_mov_b32 m0, s94
	v_lshl_add_u64 v[212:213], v[212:213], 0, s[10:11]
	ds_read_b128 v[178:181], v145 offset:49152
	ds_read_b128 v[182:185], v145 offset:50176
	ds_read_b128 v[188:191], v145 offset:51200
	ds_read_b128 v[192:195], v145 offset:52224
	ds_read_b128 v[196:199], v145 offset:53248
	ds_read_b128 v[200:203], v145 offset:54272
	ds_read_b128 v[204:207], v145 offset:55296
	ds_read_b128 v[208:211], v145 offset:56320
	global_load_lds_dwordx4 v[212:213], off
	v_lshl_add_u64 v[212:213], v[214:215], 0, s[10:11]
	s_mov_b32 m0, s92
	s_nop 0
	global_load_lds_dwordx4 v[212:213], off
	v_lshl_add_u64 v[212:213], s[40:41], 0, v[132:133]
	s_mov_b32 m0, s93
	s_nop 0
	global_load_lds_dwordx4 v[212:213], off
	v_lshl_add_u64 v[212:213], s[40:41], 0, v[128:129]
	s_mov_b32 m0, s91
	s_nop 0
	global_load_lds_dwordx4 v[212:213], off
	v_lshl_add_u64 v[212:213], v[216:217], 0, s[10:11]
	s_mov_b32 m0, s78
	s_nop 0
	global_load_lds_dwordx4 v[212:213], off
	v_lshl_add_u64 v[212:213], v[218:219], 0, s[10:11]
	s_mov_b32 m0, s79
	s_nop 0
	global_load_lds_dwordx4 v[212:213], off
	s_waitcnt vmcnt(8) lgkmcnt(0)
	s_barrier
	v_mfma_f32_16x16x32_bf16 v[60:63], v[146:149], v[178:181], v[60:63]
	s_setprio 1
	v_mfma_f32_16x16x32_bf16 v[56:59], v[154:157], v[178:181], v[56:59]
	v_mfma_f32_16x16x32_bf16 v[52:55], v[146:149], v[188:191], v[52:55]
	v_mfma_f32_16x16x32_bf16 v[44:47], v[154:157], v[188:191], v[44:47]
	v_mfma_f32_16x16x32_bf16 v[36:39], v[146:149], v[196:199], v[36:39]
	v_mfma_f32_16x16x32_bf16 v[28:31], v[154:157], v[196:199], v[28:31]
	v_mfma_f32_16x16x32_bf16 v[20:23], v[146:149], v[204:207], v[20:23]
	v_mfma_f32_16x16x32_bf16 v[12:15], v[154:157], v[204:207], v[12:15]
	v_mfma_f32_16x16x32_bf16 v[60:63], v[150:153], v[182:185], v[60:63]
	v_mfma_f32_16x16x32_bf16 v[56:59], v[158:161], v[182:185], v[56:59]
	v_mfma_f32_16x16x32_bf16 v[52:55], v[150:153], v[192:195], v[52:55]
	v_mfma_f32_16x16x32_bf16 v[44:47], v[158:161], v[192:195], v[44:47]
	v_mfma_f32_16x16x32_bf16 v[36:39], v[150:153], v[200:203], v[36:39]
	v_mfma_f32_16x16x32_bf16 v[28:31], v[158:161], v[200:203], v[28:31]
	v_mfma_f32_16x16x32_bf16 v[20:23], v[150:153], v[208:211], v[20:23]
	v_mfma_f32_16x16x32_bf16 v[12:15], v[158:161], v[208:211], v[12:15]
	v_mfma_f32_16x16x32_bf16 v[48:51], v[162:165], v[178:181], v[48:51]
	v_mfma_f32_16x16x32_bf16 v[40:43], v[170:173], v[178:181], v[40:43]
	v_mfma_f32_16x16x32_bf16 v[32:35], v[162:165], v[188:191], v[32:35]
	v_mfma_f32_16x16x32_bf16 v[24:27], v[170:173], v[188:191], v[24:27]
	v_mfma_f32_16x16x32_bf16 v[16:19], v[162:165], v[196:199], v[16:19]
	v_mfma_f32_16x16x32_bf16 v[8:11], v[170:173], v[196:199], v[8:11]
	v_mfma_f32_16x16x32_bf16 v[4:7], v[162:165], v[204:207], v[4:7]
	v_mfma_f32_16x16x32_bf16 v[0:3], v[170:173], v[204:207], v[0:3]
	v_mfma_f32_16x16x32_bf16 v[48:51], v[166:169], v[182:185], v[48:51]
	v_mfma_f32_16x16x32_bf16 v[40:43], v[174:177], v[182:185], v[40:43]
	v_mfma_f32_16x16x32_bf16 v[32:35], v[166:169], v[192:195], v[32:35]
	v_mfma_f32_16x16x32_bf16 v[24:27], v[174:177], v[192:195], v[24:27]
	v_mfma_f32_16x16x32_bf16 v[16:19], v[166:169], v[200:203], v[16:19]
	v_mfma_f32_16x16x32_bf16 v[8:11], v[174:177], v[200:203], v[8:11]
	v_mfma_f32_16x16x32_bf16 v[4:7], v[166:169], v[208:211], v[4:7]
	v_mfma_f32_16x16x32_bf16 v[0:3], v[174:177], v[208:211], v[0:3]
	s_barrier
	s_setprio 0
	s_movk_i32 s42, 0x100
	s_andn2_b64 vcc, exec, s[38:39]
	s_mov_b64 s[40:41], -1
	s_mov_b64 s[38:39], 0
	s_cbranch_vccz .LBB0_1161
	s_and_b64 vcc, exec, s[14:15]
	s_cbranch_vccz .LBB0_1164
	s_barrier

; #define PG8_STAGE(bufoff, gbase, voff) do { _Pragma("unroll") for (int _i = 0; _i < 2; ++_i) \
;         __builtin_amdgcn_global_load_lds((const unsigned*)((const char*)(gbase) + (voff)[_i]), (PG8_LAS unsigned*)(lds + (bufoff) + ldsw + _i * 8192), 16, 0, 0); } while (0)
; #define PG8_LDA(dst, b, h) do { _Pragma("unroll") for (int m = 0; m < 4; ++m) _Pragma("unroll") for (int k = 0; k < 2; ++k) dst[m][k] = *(const PG8_LAS bf16x8*)(lds + PG8_SA(b, h) + aoff + m * 2048 + k * 1024); } while (0)
; #define PG8_LDB(dst, b, h) do { _Pragma("unroll") for (int n = 0; n < 2; ++n) _Pragma("unroll") for (int k = 0; k < 2; ++k) dst[n][k] = *(const PG8_LAS bf16x8*)(lds + PG8_SB(b, h) + boff + n * 2048 + k * 1024); } while (0)
; #define PG8_MMA(ai, bj, At, Bt) do { __builtin_amdgcn_s_setprio(1); _Pragma("unroll") for (int m = 0; m < 4; ++m) _Pragma("unroll") for (int n = 0; n < 2; ++n) _Pragma("unroll") for (int k = 0; k < 2; ++k) \
;         acc[ai][bj][m][n] = __builtin_amdgcn_mfma_f32_16x16x32_bf16(Bt[n][k], At[m][k], acc[ai][bj][m][n], 0, 0, 0); __builtin_amdgcn_s_setprio(0); } while (0)
; #define PG8_WAIT_V(n) asm volatile("s_waitcnt vmcnt(" #n ")" ::: "memory")
; #define PG8_WAIT_L(n) asm volatile("s_waitcnt lgkmcnt(" #n ")" ::: "memory")
; #define PG8_BAR __builtin_amdgcn_s_barrier()
; #define PG8_SCHED __builtin_amdgcn_sched_barrier(0)
; template <class Epi, class Sched, bool ALIGN_EPI = false, bool SP2 = false>
; __device__ __forceinline__ void gemm_phase(PG8_LAS unsigned char* lds, const Gemm g, const Sched& S, const Epi& E) {
;     ...
;             const bool last = (t == nt - 2);
;             const char* a1 = cA + (size_t)(t + 1) * kstep;
;             const char* a2 = last ? nA : cA + (size_t)(t + 2) * kstep; const char* b2 = last ? nB : cB + (size_t)(t + 2) * kstep;
;             const char* a3 = a2 + kstep; const char* b3 = b2 + kstep;
;             if (last && has_next) S.a_ready(nxt);
;             if constexpr (SP2) {
;             PG8_LDB(B0, 0, 0); PG8_LDB(B1, 0, 1); PG8_SCHED; PG8_LDA(At, 0, 0); PG8_STAGE(PG8_SA(1, 1), a1 + hstepA, voffA);
;             PG8_WAIT_V(8); PG8_WAIT_L(0); PG8_BAR; PG8_MMA(0, 0, At, B0); PG8_MMA(0, 1, At, B1); PG8_BAR; PG8_SCHED;
;             PG8_LDA(At, 0, 1); PG8_STAGE(PG8_SB(0, 0), b2, voffB); PG8_STAGE(PG8_SB(0, 1), b2 + hstepB, voffB); PG8_STAGE(PG8_SA(0, 0), a2, voffA);
.LBB0_1231:
	ds_read_b128 v[112:115], v185
	ds_read_b128 v[116:119], v185 offset:1024
	ds_read_b128 v[128:131], v185 offset:2048
	ds_read_b128 v[140:143], v185 offset:3072
	ds_read_b128 v[144:147], v188
	ds_read_b128 v[148:151], v188 offset:1024
	ds_read_b128 v[168:171], v188 offset:2048
	ds_read_b128 v[172:175], v188 offset:3072
	s_add_u32 s34, s30, 0xfffc0080
	s_addc_u32 s35, s31, -1
	s_cmp_eq_u32 s69, 12
	s_cselect_b32 s37, s21, s35
	s_cselect_b32 s36, s27, s34
	s_cselect_b32 s35, s19, s68
	s_cselect_b32 s34, s66, s67
	v_lshl_add_u64 v[180:181], s[30:31], 0, v[160:161]
	s_add_i32 m0, s29, 0xc000
	ds_read_b128 v[176:179], v189
	ds_read_b128 v[192:195], v189 offset:1024
	ds_read_b128 v[196:199], v189 offset:2048
	ds_read_b128 v[200:203], v189 offset:3072
	ds_read_b128 v[204:207], v189 offset:4096
	ds_read_b128 v[208:211], v189 offset:5120
	ds_read_b128 v[212:215], v189 offset:6144
	ds_read_b128 v[216:219], v189 offset:7168
	global_load_lds_dwordx4 v[180:181], off
	v_lshl_add_u64 v[180:181], s[30:31], 0, v[162:163]
	s_add_i32 m0, s29, 0xe000
	s_nop 0
	global_load_lds_dwordx4 v[180:181], off
	s_waitcnt vmcnt(8) lgkmcnt(0)
	s_barrier
	v_mfma_f32_16x16x32_bf16 v[136:139], v[112:115], v[176:179], v[136:139]
	s_setprio 1
	v_mfma_f32_16x16x32_bf16 v[132:135], v[128:131], v[176:179], v[132:135]
	v_mfma_f32_16x16x32_bf16 v[108:111], v[112:115], v[196:199], v[108:111]
	v_mfma_f32_16x16x32_bf16 v[104:107], v[128:131], v[196:199], v[104:107]
	v_mfma_f32_16x16x32_bf16 v[92:95], v[112:115], v[204:207], v[92:95]
	v_mfma_f32_16x16x32_bf16 v[88:91], v[128:131], v[204:207], v[88:91]
	v_mfma_f32_16x16x32_bf16 v[76:79], v[112:115], v[212:215], v[76:79]
	v_mfma_f32_16x16x32_bf16 v[72:75], v[128:131], v[212:215], v[72:75]
	v_mfma_f32_16x16x32_bf16 v[136:139], v[116:119], v[192:195], v[136:139]
	v_mfma_f32_16x16x32_bf16 v[132:135], v[140:143], v[192:195], v[132:135]
	v_mfma_f32_16x16x32_bf16 v[108:111], v[116:119], v[200:203], v[108:111]
	v_mfma_f32_16x16x32_bf16 v[104:107], v[140:143], v[200:203], v[104:107]
	v_mfma_f32_16x16x32_bf16 v[92:95], v[116:119], v[208:211], v[92:95]
	v_mfma_f32_16x16x32_bf16 v[88:91], v[140:143], v[208:211], v[88:91]
	v_mfma_f32_16x16x32_bf16 v[76:79], v[116:119], v[216:219], v[76:79]
	v_mfma_f32_16x16x32_bf16 v[72:75], v[140:143], v[216:219], v[72:75]
	v_mfma_f32_16x16x32_bf16 v[124:127], v[144:147], v[176:179], v[124:127]
	v_mfma_f32_16x16x32_bf16 v[120:123], v[168:171], v[176:179], v[120:123]
	v_mfma_f32_16x16x32_bf16 v[100:103], v[144:147], v[196:199], v[100:103]
	v_mfma_f32_16x16x32_bf16 v[96:99], v[168:171], v[196:199], v[96:99]
	v_mfma_f32_16x16x32_bf16 v[84:87], v[144:147], v[204:207], v[84:87]
	v_mfma_f32_16x16x32_bf16 v[80:83], v[168:171], v[204:207], v[80:83]
	v_mfma_f32_16x16x32_bf16 v[68:71], v[144:147], v[212:215], v[68:71]
	v_mfma_f32_16x16x32_bf16 v[64:67], v[168:171], v[212:215], v[64:67]
	v_mfma_f32_16x16x32_bf16 v[124:127], v[148:151], v[192:195], v[124:127]
	v_mfma_f32_16x16x32_bf16 v[120:123], v[172:175], v[192:195], v[120:123]
	v_mfma_f32_16x16x32_bf16 v[100:103], v[148:151], v[200:203], v[100:103]
	v_mfma_f32_16x16x32_bf16 v[96:99], v[172:175], v[200:203], v[96:99]
	v_mfma_f32_16x16x32_bf16 v[84:87], v[148:151], v[208:211], v[84:87]
	v_mfma_f32_16x16x32_bf16 v[80:83], v[172:175], v[208:211], v[80:83]
	v_mfma_f32_16x16x32_bf16 v[68:71], v[148:151], v[216:219], v[68:71]
	v_mfma_f32_16x16x32_bf16 v[64:67], v[172:175], v[216:219], v[64:67]
	s_barrier
	s_setprio 0
	s_add_i32 s58, s49, s39
	v_lshl_add_u64 v[180:181], s[34:35], 0, v[154:155]
	s_mov_b32 m0, s58
	ds_read_b128 v[176:179], v189 offset:16384
	ds_read_b128 v[192:195], v189 offset:17408
	ds_read_b128 v[196:199], v189 offset:18432
	ds_read_b128 v[200:203], v189 offset:19456
	ds_read_b128 v[204:207], v189 offset:20480
	ds_read_b128 v[208:211], v189 offset:21504
	ds_read_b128 v[212:215], v189 offset:22528
	ds_read_b128 v[216:219], v189 offset:23552
	global_load_lds_dwordx4 v[180:181], off
	s_add_i32 m0, s58, 0x2000
	s_add_u32 s58, s34, 0x40000
	v_lshl_add_u64 v[220:221], s[34:35], 0, v[158:159]
	s_addc_u32 s59, s35, 0
	s_add_i32 s73, s64, s39
	global_load_lds_dwordx4 v[220:221], off
	v_lshl_add_u64 v[222:223], s[58:59], 0, v[154:155]
	s_mov_b32 m0, s73
	v_lshl_add_u64 v[224:225], s[36:37], 0, v[156:157]
	global_load_lds_dwordx4 v[222:223], off
	v_lshl_add_u64 v[222:223], s[58:59], 0, v[158:159]
	s_add_i32 m0, s73, 0x2000
	s_nop 0
	global_load_lds_dwordx4 v[222:223], off
	v_lshl_add_u64 v[222:223], s[36:37], 0, v[152:153]
	s_mov_b32 m0, s29
	s_nop 0
	global_load_lds_dwordx4 v[222:223], off
	s_mov_b32 m0, s40
	s_nop 0
	global_load_lds_dwordx4 v[224:225], off
	s_waitcnt vmcnt(8) lgkmcnt(0)
	s_barrier
; #define PG8_STAGE(bufoff, gbase, voff) do { _Pragma("unroll") for (int _i = 0; _i < 2; ++_i) \
;         __builtin_amdgcn_global_load_lds((const unsigned*)((const char*)(gbase) + (voff)[_i]), (PG8_LAS unsigned*)(lds + (bufoff) + ldsw + _i * 8192), 16, 0, 0); } while (0)
; #define PG8_LDA(dst, b, h) do { _Pragma("unroll") for (int m = 0; m < 4; ++m) _Pragma("unroll") for (int k = 0; k < 2; ++k) dst[m][k] = *(const PG8_LAS bf16x8*)(lds + PG8_SA(b, h) + aoff + m * 2048 + k * 1024); } while (0)
; #define PG8_LDB(dst, b, h) do { _Pragma("unroll") for (int n = 0; n < 2; ++n) _Pragma("unroll") for (int k = 0; k < 2; ++k) dst[n][k] = *(const PG8_LAS bf16x8*)(lds + PG8_SB(b, h) + boff + n * 2048 + k * 1024); } while (0)
; #define PG8_MMA(ai, bj, At, Bt) do { __builtin_amdgcn_s_setprio(1); _Pragma("unroll") for (int m = 0; m < 4; ++m) _Pragma("unroll") for (int n = 0; n < 2; ++n) _Pragma("unroll") for (int k = 0; k < 2; ++k) \
;         acc[ai][bj][m][n] = __builtin_amdgcn_mfma_f32_16x16x32_bf16(Bt[n][k], At[m][k], acc[ai][bj][m][n], 0, 0, 0); __builtin_amdgcn_s_setprio(0); } while (0)
; #define PG8_WAIT_V(n) asm volatile("s_waitcnt vmcnt(" #n ")" ::: "memory")
; #define PG8_WAIT_L(n) asm volatile("s_waitcnt lgkmcnt(" #n ")" ::: "memory")
; #define PG8_BAR __builtin_amdgcn_s_barrier()
; #define PG8_SCHED __builtin_amdgcn_sched_barrier(0)
; template <class Epi, class Sched, bool ALIGN_EPI = false, bool SP2 = false>
; __device__ __forceinline__ void gemm_phase(PG8_LAS unsigned char* lds, const Gemm g, const Sched& S, const Epi& E) {
;     ...
;             PG8_WAIT_V(8); PG8_WAIT_L(0); PG8_BAR; PG8_MMA(1, 0, At, B0); PG8_MMA(1, 1, At, B1); PG8_BAR; PG8_SCHED;
;             PG8_LDB(B0, 1, 0); PG8_LDB(B1, 1, 1); PG8_SCHED; PG8_LDA(At, 1, 0); PG8_STAGE(PG8_SA(0, 1), a2 + hstepA, voffA);
;             PG8_WAIT_V(8); PG8_WAIT_L(0); PG8_BAR; PG8_MMA(0, 0, At, B0); PG8_MMA(0, 1, At, B1); PG8_BAR; PG8_SCHED;
	v_mfma_f32_16x16x32_bf16 v[60:63], v[112:115], v[176:179], v[60:63]
	s_setprio 1
	v_mfma_f32_16x16x32_bf16 v[56:59], v[128:131], v[176:179], v[56:59]
	v_mfma_f32_16x16x32_bf16 v[44:47], v[112:115], v[196:199], v[44:47]
	v_mfma_f32_16x16x32_bf16 v[40:43], v[128:131], v[196:199], v[40:43]
	v_mfma_f32_16x16x32_bf16 v[28:31], v[112:115], v[204:207], v[28:31]
	v_mfma_f32_16x16x32_bf16 v[24:27], v[128:131], v[204:207], v[24:27]
	v_mfma_f32_16x16x32_bf16 v[12:15], v[112:115], v[212:215], v[12:15]
	v_mfma_f32_16x16x32_bf16 v[8:11], v[128:131], v[212:215], v[8:11]
	v_mfma_f32_16x16x32_bf16 v[60:63], v[116:119], v[192:195], v[60:63]
	v_mfma_f32_16x16x32_bf16 v[56:59], v[140:143], v[192:195], v[56:59]
	v_mfma_f32_16x16x32_bf16 v[44:47], v[116:119], v[200:203], v[44:47]
	v_mfma_f32_16x16x32_bf16 v[40:43], v[140:143], v[200:203], v[40:43]
	v_mfma_f32_16x16x32_bf16 v[28:31], v[116:119], v[208:211], v[28:31]
	v_mfma_f32_16x16x32_bf16 v[24:27], v[140:143], v[208:211], v[24:27]
	v_mfma_f32_16x16x32_bf16 v[12:15], v[116:119], v[216:219], v[12:15]
	v_mfma_f32_16x16x32_bf16 v[8:11], v[140:143], v[216:219], v[8:11]
	v_mfma_f32_16x16x32_bf16 v[52:55], v[144:147], v[176:179], v[52:55]
	v_mfma_f32_16x16x32_bf16 v[48:51], v[168:171], v[176:179], v[48:51]
	v_mfma_f32_16x16x32_bf16 v[36:39], v[144:147], v[196:199], v[36:39]
	v_mfma_f32_16x16x32_bf16 v[32:35], v[168:171], v[196:199], v[32:35]
	v_mfma_f32_16x16x32_bf16 v[20:23], v[144:147], v[204:207], v[20:23]
	v_mfma_f32_16x16x32_bf16 v[16:19], v[168:171], v[204:207], v[16:19]
	v_mfma_f32_16x16x32_bf16 v[4:7], v[144:147], v[212:215], v[4:7]
	v_mfma_f32_16x16x32_bf16 v[0:3], v[168:171], v[212:215], v[0:3]
	v_mfma_f32_16x16x32_bf16 v[52:55], v[148:151], v[192:195], v[52:55]
	v_mfma_f32_16x16x32_bf16 v[48:51], v[172:175], v[192:195], v[48:51]
	v_mfma_f32_16x16x32_bf16 v[36:39], v[148:151], v[200:203], v[36:39]
	v_mfma_f32_16x16x32_bf16 v[32:35], v[172:175], v[200:203], v[32:35]
	v_mfma_f32_16x16x32_bf16 v[20:23], v[148:151], v[208:211], v[20:23]
	v_mfma_f32_16x16x32_bf16 v[16:19], v[172:175], v[208:211], v[16:19]
	v_mfma_f32_16x16x32_bf16 v[4:7], v[148:151], v[216:219], v[4:7]
	v_mfma_f32_16x16x32_bf16 v[0:3], v[172:175], v[216:219], v[0:3]
	s_barrier
	s_setprio 0
	s_add_i32 s58, 0, 0x18000
	s_add_i32 s59, 0, 0x1c000
	v_add_u32_e32 v140, s58, v183
	v_add_u32_e32 v172, s59, v183
	ds_read_b128 v[112:115], v140
	ds_read_b128 v[116:119], v140 offset:1024
	ds_read_b128 v[128:131], v140 offset:2048
	ds_read_b128 v[140:143], v140 offset:3072
	ds_read_b128 v[144:147], v172
	ds_read_b128 v[148:151], v172 offset:1024
	ds_read_b128 v[168:171], v172 offset:2048
	ds_read_b128 v[172:175], v172 offset:3072
	s_add_u32 s36, s36, 0x40000
	s_addc_u32 s37, s37, 0
	s_mov_b32 m0, s41
	v_lshl_add_u64 v[226:227], s[36:37], 0, v[152:153]
	ds_read_b128 v[176:179], v189 offset:32768
	ds_read_b128 v[192:195], v189 offset:33792
	ds_read_b128 v[196:199], v189 offset:34816
	ds_read_b128 v[200:203], v189 offset:35840
	ds_read_b128 v[204:207], v189 offset:36864
	ds_read_b128 v[208:211], v189 offset:37888
	ds_read_b128 v[212:215], v189 offset:38912
	ds_read_b128 v[216:219], v189 offset:39936
	global_load_lds_dwordx4 v[226:227], off
	v_lshl_add_u64 v[226:227], s[36:37], 0, v[156:157]
	s_mov_b32 m0, s42
	s_nop 0
	global_load_lds_dwordx4 v[226:227], off
	s_waitcnt vmcnt(8) lgkmcnt(0)
	s_barrier
	v_mfma_f32_16x16x32_bf16 v[136:139], v[112:115], v[176:179], v[136:139]
	s_setprio 1
	v_mfma_f32_16x16x32_bf16 v[132:135], v[128:131], v[176:179], v[132:135]
	v_mfma_f32_16x16x32_bf16 v[108:111], v[112:115], v[196:199], v[108:111]
	v_mfma_f32_16x16x32_bf16 v[104:107], v[128:131], v[196:199], v[104:107]
	v_mfma_f32_16x16x32_bf16 v[92:95], v[112:115], v[204:207], v[92:95]
	v_mfma_f32_16x16x32_bf16 v[88:91], v[128:131], v[204:207], v[88:91]
	v_mfma_f32_16x16x32_bf16 v[76:79], v[112:115], v[212:215], v[76:79]
	v_mfma_f32_16x16x32_bf16 v[72:75], v[128:131], v[212:215], v[72:75]
	v_mfma_f32_16x16x32_bf16 v[136:139], v[116:119], v[192:195], v[136:139]
	v_mfma_f32_16x16x32_bf16 v[132:135], v[140:143], v[192:195], v[132:135]
	v_mfma_f32_16x16x32_bf16 v[108:111], v[116:119], v[200:203], v[108:111]
	v_mfma_f32_16x16x32_bf16 v[104:107], v[140:143], v[200:203], v[104:107]
	v_mfma_f32_16x16x32_bf16 v[92:95], v[116:119], v[208:211], v[92:95]
	v_mfma_f32_16x16x32_bf16 v[88:91], v[140:143], v[208:211], v[88:91]
	v_mfma_f32_16x16x32_bf16 v[76:79], v[116:119], v[216:219], v[76:79]
	v_mfma_f32_16x16x32_bf16 v[72:75], v[140:143], v[216:219], v[72:75]
	v_mfma_f32_16x16x32_bf16 v[124:127], v[144:147], v[176:179], v[124:127]
	v_mfma_f32_16x16x32_bf16 v[120:123], v[168:171], v[176:179], v[120:123]
	v_mfma_f32_16x16x32_bf16 v[100:103], v[144:147], v[196:199], v[100:103]
	v_mfma_f32_16x16x32_bf16 v[96:99], v[168:171], v[196:199], v[96:99]
	v_mfma_f32_16x16x32_bf16 v[84:87], v[144:147], v[204:207], v[84:87]
	v_mfma_f32_16x16x32_bf16 v[80:83], v[168:171], v[204:207], v[80:83]
	v_mfma_f32_16x16x32_bf16 v[68:71], v[144:147], v[212:215], v[68:71]
	v_mfma_f32_16x16x32_bf16 v[64:67], v[168:171], v[212:215], v[64:67]
	v_mfma_f32_16x16x32_bf16 v[124:127], v[148:151], v[192:195], v[124:127]
	v_mfma_f32_16x16x32_bf16 v[120:123], v[172:175], v[192:195], v[120:123]
	v_mfma_f32_16x16x32_bf16 v[100:103], v[148:151], v[200:203], v[100:103]
	v_mfma_f32_16x16x32_bf16 v[96:99], v[172:175], v[200:203], v[96:99]
	v_mfma_f32_16x16x32_bf16 v[84:87], v[148:151], v[208:211], v[84:87]
	v_mfma_f32_16x16x32_bf16 v[80:83], v[172:175], v[208:211], v[80:83]
	v_mfma_f32_16x16x32_bf16 v[68:71], v[148:151], v[216:219], v[68:71]
	v_mfma_f32_16x16x32_bf16 v[64:67], v[172:175], v[216:219], v[64:67]
	s_barrier
; #define PG8_STAGE(bufoff, gbase, voff) do { _Pragma("unroll") for (int _i = 0; _i < 2; ++_i) \
;         __builtin_amdgcn_global_load_lds((const unsigned*)((const char*)(gbase) + (voff)[_i]), (PG8_LAS unsigned*)(lds + (bufoff) + ldsw + _i * 8192), 16, 0, 0); } while (0)
; #define PG8_LDA(dst, b, h) do { _Pragma("unroll") for (int m = 0; m < 4; ++m) _Pragma("unroll") for (int k = 0; k < 2; ++k) dst[m][k] = *(const PG8_LAS bf16x8*)(lds + PG8_SA(b, h) + aoff + m * 2048 + k * 1024); } while (0)
; #define PG8_MMA(ai, bj, At, Bt) do { __builtin_amdgcn_s_setprio(1); _Pragma("unroll") for (int m = 0; m < 4; ++m) _Pragma("unroll") for (int n = 0; n < 2; ++n) _Pragma("unroll") for (int k = 0; k < 2; ++k) \
;         acc[ai][bj][m][n] = __builtin_amdgcn_mfma_f32_16x16x32_bf16(Bt[n][k], At[m][k], acc[ai][bj][m][n], 0, 0, 0); __builtin_amdgcn_s_setprio(0); } while (0)
; #define PG8_WAIT_V(n) asm volatile("s_waitcnt vmcnt(" #n ")" ::: "memory")
; #define PG8_WAIT_L(n) asm volatile("s_waitcnt lgkmcnt(" #n ")" ::: "memory")
; #define PG8_BAR __builtin_amdgcn_s_barrier()
; #define PG8_SCHED __builtin_amdgcn_sched_barrier(0)
; template <class Epi, class Sched, bool ALIGN_EPI = false, bool SP2 = false>
; __device__ __forceinline__ void gemm_phase(PG8_LAS unsigned char* lds, const Gemm g, const Sched& S, const Epi& E) {
;     ...
;             PG8_LDA(At, 1, 1); PG8_STAGE(PG8_SB(1, 0), b3, voffB); PG8_STAGE(PG8_SB(1, 1), b3 + hstepB, voffB); PG8_STAGE(PG8_SA(1, 0), a3, voffA);
;             PG8_WAIT_V(8); PG8_WAIT_L(0); PG8_BAR; PG8_MMA(1, 0, At, B0); PG8_MMA(1, 1, At, B1); PG8_BAR; PG8_SCHED;
;     ...
;         if constexpr (ALIGN_EPI) { if (wr == 0) PG8_BAR; }
	s_setprio 0
	s_add_i32 s36, s58, s39
	v_lshl_add_u64 v[180:181], v[180:181], 0, s[14:15]
	s_mov_b32 m0, s36
	ds_read_b128 v[176:179], v189 offset:49152
	ds_read_b128 v[192:195], v189 offset:50176
	ds_read_b128 v[196:199], v189 offset:51200
	ds_read_b128 v[200:203], v189 offset:52224
	ds_read_b128 v[204:207], v189 offset:53248
	ds_read_b128 v[208:211], v189 offset:54272
	ds_read_b128 v[212:215], v189 offset:55296
	ds_read_b128 v[216:219], v189 offset:56320
	global_load_lds_dwordx4 v[180:181], off
	s_add_i32 m0, s36, 0x2000
	s_add_u32 s34, s34, 0x40080
	v_lshl_add_u64 v[180:181], v[220:221], 0, s[14:15]
	s_addc_u32 s35, s35, 0
	s_add_i32 s36, s59, s39
	global_load_lds_dwordx4 v[180:181], off
	v_lshl_add_u64 v[180:181], s[34:35], 0, v[154:155]
	s_mov_b32 m0, s36
	s_nop 0
	global_load_lds_dwordx4 v[180:181], off
	v_lshl_add_u64 v[180:181], s[34:35], 0, v[158:159]
	s_add_i32 m0, s36, 0x2000
	s_nop 0
	global_load_lds_dwordx4 v[180:181], off
	v_lshl_add_u64 v[180:181], v[222:223], 0, s[14:15]
	s_mov_b32 m0, s44
	s_nop 0
	global_load_lds_dwordx4 v[180:181], off
	v_lshl_add_u64 v[180:181], v[224:225], 0, s[14:15]
	s_mov_b32 m0, s45
	s_nop 0
	global_load_lds_dwordx4 v[180:181], off
	s_waitcnt vmcnt(8) lgkmcnt(0)
	s_barrier
	v_mfma_f32_16x16x32_bf16 v[60:63], v[112:115], v[176:179], v[60:63]
	s_setprio 1
	v_mfma_f32_16x16x32_bf16 v[56:59], v[128:131], v[176:179], v[56:59]
	v_mfma_f32_16x16x32_bf16 v[44:47], v[112:115], v[196:199], v[44:47]
	v_mfma_f32_16x16x32_bf16 v[40:43], v[128:131], v[196:199], v[40:43]
	v_mfma_f32_16x16x32_bf16 v[28:31], v[112:115], v[204:207], v[28:31]
	v_mfma_f32_16x16x32_bf16 v[24:27], v[128:131], v[204:207], v[24:27]
	v_mfma_f32_16x16x32_bf16 v[12:15], v[112:115], v[212:215], v[12:15]
	v_mfma_f32_16x16x32_bf16 v[8:11], v[128:131], v[212:215], v[8:11]
	v_mfma_f32_16x16x32_bf16 v[60:63], v[116:119], v[192:195], v[60:63]
	v_mfma_f32_16x16x32_bf16 v[56:59], v[140:143], v[192:195], v[56:59]
	v_mfma_f32_16x16x32_bf16 v[44:47], v[116:119], v[200:203], v[44:47]
	v_mfma_f32_16x16x32_bf16 v[40:43], v[140:143], v[200:203], v[40:43]
	v_mfma_f32_16x16x32_bf16 v[28:31], v[116:119], v[208:211], v[28:31]
	v_mfma_f32_16x16x32_bf16 v[24:27], v[140:143], v[208:211], v[24:27]
	v_mfma_f32_16x16x32_bf16 v[12:15], v[116:119], v[216:219], v[12:15]
	v_mfma_f32_16x16x32_bf16 v[8:11], v[140:143], v[216:219], v[8:11]
	v_mfma_f32_16x16x32_bf16 v[52:55], v[144:147], v[176:179], v[52:55]
	v_mfma_f32_16x16x32_bf16 v[48:51], v[168:171], v[176:179], v[48:51]
	v_mfma_f32_16x16x32_bf16 v[36:39], v[144:147], v[196:199], v[36:39]
	v_mfma_f32_16x16x32_bf16 v[32:35], v[168:171], v[196:199], v[32:35]
	v_mfma_f32_16x16x32_bf16 v[20:23], v[144:147], v[204:207], v[20:23]
	v_mfma_f32_16x16x32_bf16 v[16:19], v[168:171], v[204:207], v[16:19]
	v_mfma_f32_16x16x32_bf16 v[4:7], v[144:147], v[212:215], v[4:7]
	v_mfma_f32_16x16x32_bf16 v[0:3], v[168:171], v[212:215], v[0:3]
	v_mfma_f32_16x16x32_bf16 v[52:55], v[148:151], v[192:195], v[52:55]
	v_mfma_f32_16x16x32_bf16 v[48:51], v[172:175], v[192:195], v[48:51]
	v_mfma_f32_16x16x32_bf16 v[36:39], v[148:151], v[200:203], v[36:39]
	v_mfma_f32_16x16x32_bf16 v[32:35], v[172:175], v[200:203], v[32:35]
	v_mfma_f32_16x16x32_bf16 v[20:23], v[148:151], v[208:211], v[20:23]
	v_mfma_f32_16x16x32_bf16 v[16:19], v[172:175], v[208:211], v[16:19]
	v_mfma_f32_16x16x32_bf16 v[4:7], v[148:151], v[216:219], v[4:7]
	v_mfma_f32_16x16x32_bf16 v[0:3], v[172:175], v[216:219], v[0:3]
	s_barrier
	s_setprio 0
	s_add_i32 s69, s69, 2
	s_add_u32 s30, s30, 0x100
	s_addc_u32 s31, s31, 0
	s_add_u32 s67, s67, 0x100
	s_addc_u32 s68, s68, 0
	s_cmp_gt_u32 s69, 13
	s_cbranch_scc0 .LBB0_1231
	s_and_b64 vcc, exec, s[16:17]
	s_cbranch_vccz .LBB0_1234
	s_barrier
